# AO epilogues rewritten (gates prefetched after each K-loop, IEEE division sequence kept) + conv_peer_table unrolled x8 (16 loads in flight)
# speedup vs baseline: 1.0164x; 1.0009x over previous
.Lk_aol0a_loop:
	s_barrier
	s_add_u32 m0, s50, 32768
	v_mfma_f32_16x16x32_bf16 v[94:97], v[114:117], v[142:145], v[94:97]
	ds_read_b128 v[30:33], v100 offset:32
	global_load_lds_dwordx4 v160, s[10:11] offset:0
	v_mfma_f32_16x16x32_bf16 v[90:93], v[114:117], v[146:149], v[90:93]
	ds_read_b128 v[46:49], v158 offset:32
	global_load_lds_dwordx4 v161, s[10:11] offset:1024
	v_mfma_f32_16x16x32_bf16 v[82:85], v[114:117], v[150:153], v[82:85]
	ds_read_b128 v[50:53], v158 offset:2080
	global_load_lds_dwordx4 v162, s[10:11] offset:2048
	v_mfma_f32_16x16x32_bf16 v[78:81], v[114:117], v[154:157], v[78:81]
	ds_read_b128 v[34:37], v100 offset:2080
	global_load_lds_dwordx4 v163, s[10:11] offset:3072
	s_add_u32 m0, s50, 49152
	v_mfma_f32_16x16x32_bf16 v[74:77], v[118:121], v[142:145], v[74:77]
	ds_read_b128 v[54:57], v158 offset:4128
	global_load_lds_dwordx4 v160, s[12:13] offset:0
	v_mfma_f32_16x16x32_bf16 v[70:73], v[118:121], v[146:149], v[70:73]
	ds_read_b128 v[62:65], v158 offset:6176
	global_load_lds_dwordx4 v161, s[12:13] offset:1024
	v_mfma_f32_16x16x32_bf16 v[66:69], v[118:121], v[150:153], v[66:69]
	ds_read_b128 v[38:41], v100 offset:4128
	global_load_lds_dwordx4 v162, s[12:13] offset:2048
	v_mfma_f32_16x16x32_bf16 v[58:61], v[118:121], v[154:157], v[58:61]
	ds_read_b128 v[42:45], v100 offset:6176
	global_load_lds_dwordx4 v163, s[12:13] offset:3072
	v_mfma_f32_16x16x32_bf16 v[26:29], v[122:125], v[142:145], v[26:29]
	v_mfma_f32_16x16x32_bf16 v[22:25], v[122:125], v[146:149], v[22:25]
	v_mfma_f32_16x16x32_bf16 v[18:21], v[122:125], v[150:153], v[18:21]
	v_mfma_f32_16x16x32_bf16 v[14:17], v[122:125], v[154:157], v[14:17]
	v_mfma_f32_16x16x32_bf16 v[10:13], v[138:141], v[142:145], v[10:13]
	v_mfma_f32_16x16x32_bf16 v[6:9], v[138:141], v[146:149], v[6:9]
	v_mfma_f32_16x16x32_bf16 v[2:5], v[138:141], v[150:153], v[2:5]
	v_mfma_f32_16x16x32_bf16 v[86:89], v[138:141], v[154:157], v[86:89]
	s_add_u32 s98, s98, 1
	s_and_b32 s98, s98, 15
	s_cmp_eq_u32 s98, 0
	s_cselect_b32 s99, 0x800, 0
	s_add_u32 s10, s10, 0x80
	s_addc_u32 s11, s11, 0
	s_sub_u32 s10, s10, s99
	s_subb_u32 s11, s11, 0
	s_add_u32 s12, s12, 0x80
	s_addc_u32 s13, s13, 0
	s_sub_u32 s12, s12, s99
	s_subb_u32 s13, s13, 0
	s_waitcnt lgkmcnt(0)
	v_mfma_f32_16x16x32_bf16 v[94:97], v[30:33], v[46:49], v[94:97]
	ds_read_b128 v[114:117], v111 offset:32
	v_mfma_f32_16x16x32_bf16 v[90:93], v[30:33], v[50:53], v[90:93]
	ds_read_b128 v[142:145], v159 offset:32
	v_mfma_f32_16x16x32_bf16 v[82:85], v[30:33], v[54:57], v[82:85]
	ds_read_b128 v[146:149], v159 offset:2080
	v_mfma_f32_16x16x32_bf16 v[78:81], v[30:33], v[62:65], v[78:81]
	ds_read_b128 v[118:121], v111 offset:2080
	v_mfma_f32_16x16x32_bf16 v[74:77], v[34:37], v[46:49], v[74:77]
	ds_read_b128 v[150:153], v159 offset:4128
	v_mfma_f32_16x16x32_bf16 v[70:73], v[34:37], v[50:53], v[70:73]
	ds_read_b128 v[154:157], v159 offset:6176
	v_mfma_f32_16x16x32_bf16 v[66:69], v[34:37], v[54:57], v[66:69]
	ds_read_b128 v[122:125], v111 offset:4128
	v_mfma_f32_16x16x32_bf16 v[58:61], v[34:37], v[62:65], v[58:61]
	ds_read_b128 v[138:141], v111 offset:6176
	v_mfma_f32_16x16x32_bf16 v[26:29], v[38:41], v[46:49], v[26:29]
	v_mfma_f32_16x16x32_bf16 v[22:25], v[38:41], v[50:53], v[22:25]
	v_mfma_f32_16x16x32_bf16 v[18:21], v[38:41], v[54:57], v[18:21]
	v_mfma_f32_16x16x32_bf16 v[14:17], v[38:41], v[62:65], v[14:17]
	v_mfma_f32_16x16x32_bf16 v[10:13], v[42:45], v[46:49], v[10:13]
	v_mfma_f32_16x16x32_bf16 v[6:9], v[42:45], v[50:53], v[6:9]
	v_mfma_f32_16x16x32_bf16 v[2:5], v[42:45], v[54:57], v[2:5]
	v_mfma_f32_16x16x32_bf16 v[86:89], v[42:45], v[62:65], v[86:89]
	s_waitcnt lgkmcnt(0)
	s_waitcnt vmcnt(0)
	s_barrier
	s_add_u32 m0, s50, 0
	v_mfma_f32_16x16x32_bf16 v[94:97], v[114:117], v[142:145], v[94:97]
	ds_read_b128 v[30:33], v100 offset:32800
	global_load_lds_dwordx4 v160, s[10:11] offset:0
	v_mfma_f32_16x16x32_bf16 v[90:93], v[114:117], v[146:149], v[90:93]
	ds_read_b128 v[46:49], v158 offset:32800
	global_load_lds_dwordx4 v161, s[10:11] offset:1024
	v_mfma_f32_16x16x32_bf16 v[82:85], v[114:117], v[150:153], v[82:85]
	ds_read_b128 v[50:53], v158 offset:34848
	global_load_lds_dwordx4 v162, s[10:11] offset:2048
	v_mfma_f32_16x16x32_bf16 v[78:81], v[114:117], v[154:157], v[78:81]
	ds_read_b128 v[34:37], v100 offset:34848
	global_load_lds_dwordx4 v163, s[10:11] offset:3072
	s_add_u32 m0, s50, 16384
	v_mfma_f32_16x16x32_bf16 v[74:77], v[118:121], v[142:145], v[74:77]
	ds_read_b128 v[54:57], v158 offset:36896
	global_load_lds_dwordx4 v160, s[12:13] offset:0
	v_mfma_f32_16x16x32_bf16 v[70:73], v[118:121], v[146:149], v[70:73]
	ds_read_b128 v[62:65], v158 offset:38944
	global_load_lds_dwordx4 v161, s[12:13] offset:1024
	v_mfma_f32_16x16x32_bf16 v[66:69], v[118:121], v[150:153], v[66:69]
	ds_read_b128 v[38:41], v100 offset:36896
	global_load_lds_dwordx4 v162, s[12:13] offset:2048
	v_mfma_f32_16x16x32_bf16 v[58:61], v[118:121], v[154:157], v[58:61]
	ds_read_b128 v[42:45], v100 offset:38944
	global_load_lds_dwordx4 v163, s[12:13] offset:3072
	v_mfma_f32_16x16x32_bf16 v[26:29], v[122:125], v[142:145], v[26:29]
	v_mfma_f32_16x16x32_bf16 v[22:25], v[122:125], v[146:149], v[22:25]
	v_mfma_f32_16x16x32_bf16 v[18:21], v[122:125], v[150:153], v[18:21]
	v_mfma_f32_16x16x32_bf16 v[14:17], v[122:125], v[154:157], v[14:17]
	v_mfma_f32_16x16x32_bf16 v[10:13], v[138:141], v[142:145], v[10:13]
	v_mfma_f32_16x16x32_bf16 v[6:9], v[138:141], v[146:149], v[6:9]
	v_mfma_f32_16x16x32_bf16 v[2:5], v[138:141], v[150:153], v[2:5]
	v_mfma_f32_16x16x32_bf16 v[86:89], v[138:141], v[154:157], v[86:89]
	s_add_u32 s98, s98, 1
	s_and_b32 s98, s98, 15
	s_cmp_eq_u32 s98, 0
	s_cselect_b32 s99, 0x800, 0
	s_add_u32 s10, s10, 0x80
	s_addc_u32 s11, s11, 0
	s_sub_u32 s10, s10, s99
	s_subb_u32 s11, s11, 0
	s_add_u32 s12, s12, 0x80
	s_addc_u32 s13, s13, 0
	s_sub_u32 s12, s12, s99
	s_subb_u32 s13, s13, 0
	s_waitcnt lgkmcnt(0)
	v_mfma_f32_16x16x32_bf16 v[94:97], v[30:33], v[46:49], v[94:97]
	ds_read_b128 v[114:117], v111 offset:32800
	v_mfma_f32_16x16x32_bf16 v[90:93], v[30:33], v[50:53], v[90:93]
	ds_read_b128 v[142:145], v159 offset:32800
	v_mfma_f32_16x16x32_bf16 v[82:85], v[30:33], v[54:57], v[82:85]
	ds_read_b128 v[146:149], v159 offset:34848
	v_mfma_f32_16x16x32_bf16 v[78:81], v[30:33], v[62:65], v[78:81]
	ds_read_b128 v[118:121], v111 offset:34848
	v_mfma_f32_16x16x32_bf16 v[74:77], v[34:37], v[46:49], v[74:77]
	ds_read_b128 v[150:153], v159 offset:36896
	v_mfma_f32_16x16x32_bf16 v[70:73], v[34:37], v[50:53], v[70:73]
	ds_read_b128 v[154:157], v159 offset:38944
	v_mfma_f32_16x16x32_bf16 v[66:69], v[34:37], v[54:57], v[66:69]
	ds_read_b128 v[122:125], v111 offset:36896
	v_mfma_f32_16x16x32_bf16 v[58:61], v[34:37], v[62:65], v[58:61]
	ds_read_b128 v[138:141], v111 offset:38944
	v_mfma_f32_16x16x32_bf16 v[26:29], v[38:41], v[46:49], v[26:29]
	v_mfma_f32_16x16x32_bf16 v[22:25], v[38:41], v[50:53], v[22:25]
	v_mfma_f32_16x16x32_bf16 v[18:21], v[38:41], v[54:57], v[18:21]
	v_mfma_f32_16x16x32_bf16 v[14:17], v[38:41], v[62:65], v[14:17]
	v_mfma_f32_16x16x32_bf16 v[10:13], v[42:45], v[46:49], v[10:13]
	v_mfma_f32_16x16x32_bf16 v[6:9], v[42:45], v[50:53], v[6:9]
	v_mfma_f32_16x16x32_bf16 v[2:5], v[42:45], v[54:57], v[2:5]
	v_mfma_f32_16x16x32_bf16 v[86:89], v[42:45], v[62:65], v[86:89]
	s_waitcnt lgkmcnt(0)
	s_waitcnt vmcnt(0)
	s_add_u32 s49, s49, 1
	s_cmp_lt_u32 s49, 7
	s_cbranch_scc1 .Lk_aol0a_loop
	s_barrier
	s_add_u32 m0, s50, 32768
	v_mfma_f32_16x16x32_bf16 v[94:97], v[114:117], v[142:145], v[94:97]
	ds_read_b128 v[30:33], v100 offset:32
	global_load_lds_dwordx4 v160, s[10:11] offset:0
	v_mfma_f32_16x16x32_bf16 v[90:93], v[114:117], v[146:149], v[90:93]
	ds_read_b128 v[46:49], v158 offset:32
	global_load_lds_dwordx4 v161, s[10:11] offset:1024
	v_mfma_f32_16x16x32_bf16 v[82:85], v[114:117], v[150:153], v[82:85]
	ds_read_b128 v[50:53], v158 offset:2080
	global_load_lds_dwordx4 v162, s[10:11] offset:2048
	v_mfma_f32_16x16x32_bf16 v[78:81], v[114:117], v[154:157], v[78:81]
	ds_read_b128 v[34:37], v100 offset:2080
	global_load_lds_dwordx4 v163, s[10:11] offset:3072
	s_add_u32 m0, s50, 49152
	v_mfma_f32_16x16x32_bf16 v[74:77], v[118:121], v[142:145], v[74:77]
	ds_read_b128 v[54:57], v158 offset:4128
	global_load_lds_dwordx4 v160, s[12:13] offset:0
	v_mfma_f32_16x16x32_bf16 v[70:73], v[118:121], v[146:149], v[70:73]
	ds_read_b128 v[62:65], v158 offset:6176
	global_load_lds_dwordx4 v161, s[12:13] offset:1024
	v_mfma_f32_16x16x32_bf16 v[66:69], v[118:121], v[150:153], v[66:69]
	ds_read_b128 v[38:41], v100 offset:4128
	global_load_lds_dwordx4 v162, s[12:13] offset:2048
	v_mfma_f32_16x16x32_bf16 v[58:61], v[118:121], v[154:157], v[58:61]
	ds_read_b128 v[42:45], v100 offset:6176
	global_load_lds_dwordx4 v163, s[12:13] offset:3072
	v_mfma_f32_16x16x32_bf16 v[26:29], v[122:125], v[142:145], v[26:29]
	v_mfma_f32_16x16x32_bf16 v[22:25], v[122:125], v[146:149], v[22:25]
	v_mfma_f32_16x16x32_bf16 v[18:21], v[122:125], v[150:153], v[18:21]
	v_mfma_f32_16x16x32_bf16 v[14:17], v[122:125], v[154:157], v[14:17]
	v_mfma_f32_16x16x32_bf16 v[10:13], v[138:141], v[142:145], v[10:13]
	v_mfma_f32_16x16x32_bf16 v[6:9], v[138:141], v[146:149], v[6:9]
	v_mfma_f32_16x16x32_bf16 v[2:5], v[138:141], v[150:153], v[2:5]
	v_mfma_f32_16x16x32_bf16 v[86:89], v[138:141], v[154:157], v[86:89]
	s_add_u32 s98, s98, 1
	s_and_b32 s98, s98, 15
	s_cmp_eq_u32 s98, 0
	s_cselect_b32 s99, 0x800, 0
	s_add_u32 s10, s10, 0x80
	s_addc_u32 s11, s11, 0
	s_sub_u32 s10, s10, s99
	s_subb_u32 s11, s11, 0
	s_add_u32 s12, s12, 0x80
	s_addc_u32 s13, s13, 0
	s_sub_u32 s12, s12, s99
	s_subb_u32 s13, s13, 0
	s_waitcnt lgkmcnt(0)
	v_mfma_f32_16x16x32_bf16 v[94:97], v[30:33], v[46:49], v[94:97]
	ds_read_b128 v[114:117], v111 offset:32
	v_mfma_f32_16x16x32_bf16 v[90:93], v[30:33], v[50:53], v[90:93]
	ds_read_b128 v[142:145], v159 offset:32
	v_mfma_f32_16x16x32_bf16 v[82:85], v[30:33], v[54:57], v[82:85]
	ds_read_b128 v[146:149], v159 offset:2080
	v_mfma_f32_16x16x32_bf16 v[78:81], v[30:33], v[62:65], v[78:81]
	ds_read_b128 v[118:121], v111 offset:2080
	v_mfma_f32_16x16x32_bf16 v[74:77], v[34:37], v[46:49], v[74:77]
	ds_read_b128 v[150:153], v159 offset:4128
	v_mfma_f32_16x16x32_bf16 v[70:73], v[34:37], v[50:53], v[70:73]
	ds_read_b128 v[154:157], v159 offset:6176
	v_mfma_f32_16x16x32_bf16 v[66:69], v[34:37], v[54:57], v[66:69]
	ds_read_b128 v[122:125], v111 offset:4128
	v_mfma_f32_16x16x32_bf16 v[58:61], v[34:37], v[62:65], v[58:61]
	ds_read_b128 v[138:141], v111 offset:6176
	v_mfma_f32_16x16x32_bf16 v[26:29], v[38:41], v[46:49], v[26:29]
	v_mfma_f32_16x16x32_bf16 v[22:25], v[38:41], v[50:53], v[22:25]
	v_mfma_f32_16x16x32_bf16 v[18:21], v[38:41], v[54:57], v[18:21]
	v_mfma_f32_16x16x32_bf16 v[14:17], v[38:41], v[62:65], v[14:17]
	v_mfma_f32_16x16x32_bf16 v[10:13], v[42:45], v[46:49], v[10:13]
	v_mfma_f32_16x16x32_bf16 v[6:9], v[42:45], v[50:53], v[6:9]
	v_mfma_f32_16x16x32_bf16 v[2:5], v[42:45], v[54:57], v[2:5]
	v_mfma_f32_16x16x32_bf16 v[86:89], v[42:45], v[62:65], v[86:89]
	s_waitcnt lgkmcnt(0)
	s_waitcnt vmcnt(0)
	s_barrier
	v_mfma_f32_16x16x32_bf16 v[94:97], v[114:117], v[142:145], v[94:97]
	ds_read_b128 v[30:33], v100 offset:32800
	v_mfma_f32_16x16x32_bf16 v[90:93], v[114:117], v[146:149], v[90:93]
	ds_read_b128 v[46:49], v158 offset:32800
	v_mfma_f32_16x16x32_bf16 v[82:85], v[114:117], v[150:153], v[82:85]
	ds_read_b128 v[50:53], v158 offset:34848
	v_mfma_f32_16x16x32_bf16 v[78:81], v[114:117], v[154:157], v[78:81]
	ds_read_b128 v[34:37], v100 offset:34848
	v_mfma_f32_16x16x32_bf16 v[74:77], v[118:121], v[142:145], v[74:77]
	ds_read_b128 v[54:57], v158 offset:36896
	v_mfma_f32_16x16x32_bf16 v[70:73], v[118:121], v[146:149], v[70:73]
	ds_read_b128 v[62:65], v158 offset:38944
	v_mfma_f32_16x16x32_bf16 v[66:69], v[118:121], v[150:153], v[66:69]
	ds_read_b128 v[38:41], v100 offset:36896
	v_mfma_f32_16x16x32_bf16 v[58:61], v[118:121], v[154:157], v[58:61]
	ds_read_b128 v[42:45], v100 offset:38944
	v_mfma_f32_16x16x32_bf16 v[26:29], v[122:125], v[142:145], v[26:29]
	v_mfma_f32_16x16x32_bf16 v[22:25], v[122:125], v[146:149], v[22:25]
	v_mfma_f32_16x16x32_bf16 v[18:21], v[122:125], v[150:153], v[18:21]
	v_mfma_f32_16x16x32_bf16 v[14:17], v[122:125], v[154:157], v[14:17]
	v_mfma_f32_16x16x32_bf16 v[10:13], v[138:141], v[142:145], v[10:13]
	v_mfma_f32_16x16x32_bf16 v[6:9], v[138:141], v[146:149], v[6:9]
	v_mfma_f32_16x16x32_bf16 v[2:5], v[138:141], v[150:153], v[2:5]
	v_mfma_f32_16x16x32_bf16 v[86:89], v[138:141], v[154:157], v[86:89]
	s_waitcnt lgkmcnt(0)
	v_mfma_f32_16x16x32_bf16 v[94:97], v[30:33], v[46:49], v[94:97]
	ds_read_b128 v[114:117], v111 offset:32800
	v_mfma_f32_16x16x32_bf16 v[90:93], v[30:33], v[50:53], v[90:93]
	ds_read_b128 v[142:145], v159 offset:32800
	v_mfma_f32_16x16x32_bf16 v[82:85], v[30:33], v[54:57], v[82:85]
	ds_read_b128 v[146:149], v159 offset:34848
	v_mfma_f32_16x16x32_bf16 v[78:81], v[30:33], v[62:65], v[78:81]
	ds_read_b128 v[118:121], v111 offset:34848
	v_mfma_f32_16x16x32_bf16 v[74:77], v[34:37], v[46:49], v[74:77]
	ds_read_b128 v[150:153], v159 offset:36896
	v_mfma_f32_16x16x32_bf16 v[70:73], v[34:37], v[50:53], v[70:73]
	ds_read_b128 v[154:157], v159 offset:38944
	v_mfma_f32_16x16x32_bf16 v[66:69], v[34:37], v[54:57], v[66:69]
	ds_read_b128 v[122:125], v111 offset:36896
	v_mfma_f32_16x16x32_bf16 v[58:61], v[34:37], v[62:65], v[58:61]
	ds_read_b128 v[138:141], v111 offset:38944
	v_mfma_f32_16x16x32_bf16 v[26:29], v[38:41], v[46:49], v[26:29]
	v_mfma_f32_16x16x32_bf16 v[22:25], v[38:41], v[50:53], v[22:25]
	v_mfma_f32_16x16x32_bf16 v[18:21], v[38:41], v[54:57], v[18:21]
	v_mfma_f32_16x16x32_bf16 v[14:17], v[38:41], v[62:65], v[14:17]
	v_mfma_f32_16x16x32_bf16 v[10:13], v[42:45], v[46:49], v[10:13]
	v_mfma_f32_16x16x32_bf16 v[6:9], v[42:45], v[50:53], v[6:9]
	v_mfma_f32_16x16x32_bf16 v[2:5], v[42:45], v[54:57], v[2:5]
	v_mfma_f32_16x16x32_bf16 v[86:89], v[42:45], v[62:65], v[86:89]
	s_waitcnt lgkmcnt(0)
	v_mfma_f32_16x16x32_bf16 v[94:97], v[114:117], v[142:145], v[94:97]
	v_mfma_f32_16x16x32_bf16 v[90:93], v[114:117], v[146:149], v[90:93]
	v_mfma_f32_16x16x32_bf16 v[82:85], v[114:117], v[150:153], v[82:85]
	v_mfma_f32_16x16x32_bf16 v[78:81], v[114:117], v[154:157], v[78:81]
	v_mfma_f32_16x16x32_bf16 v[74:77], v[118:121], v[142:145], v[74:77]
	v_mfma_f32_16x16x32_bf16 v[70:73], v[118:121], v[146:149], v[70:73]
	v_mfma_f32_16x16x32_bf16 v[66:69], v[118:121], v[150:153], v[66:69]
	v_mfma_f32_16x16x32_bf16 v[58:61], v[118:121], v[154:157], v[58:61]
	v_mfma_f32_16x16x32_bf16 v[26:29], v[122:125], v[142:145], v[26:29]
	v_mfma_f32_16x16x32_bf16 v[22:25], v[122:125], v[146:149], v[22:25]
	v_mfma_f32_16x16x32_bf16 v[18:21], v[122:125], v[150:153], v[18:21]
	v_mfma_f32_16x16x32_bf16 v[14:17], v[122:125], v[154:157], v[14:17]
	v_mfma_f32_16x16x32_bf16 v[10:13], v[138:141], v[142:145], v[10:13]
	v_mfma_f32_16x16x32_bf16 v[6:9], v[138:141], v[146:149], v[6:9]
	v_mfma_f32_16x16x32_bf16 v[2:5], v[138:141], v[150:153], v[2:5]
	v_mfma_f32_16x16x32_bf16 v[86:89], v[138:141], v[154:157], v[86:89]
	v_lshrrev_b32_e32 v117, 4, v0
	v_and_b32_e32 v117, 15, v117
	v_and_b32_e32 v118, 15, v0
	v_lshlrev_b32_e32 v118, 4, v118
	v_lshl_or_b32 v117, v117, 12, v118
	s_lshl_b32 s100, s48, 12
	s_lshl_b32 s98, s47, 8
	s_add_u32 s100, s100, s98
	s_add_u32 s98, s42, s100
	s_addc_u32 s99, s43, 0
	s_add_u32 s98, s98, 0x12d24000
	s_addc_u32 s99, s99, 0
	global_load_dwordx4 v[148:151], v117, s[98:99]
	global_load_dwordx4 v[152:155], v117, s[98:99] offset:2048
	s_add_u32 s98, s98, 0x10000
	s_addc_u32 s99, s99, 0
	global_load_dwordx4 v[156:159], v117, s[98:99]
	global_load_dwordx4 v[160:163], v117, s[98:99] offset:2048
	s_add_u32 s98, s98, 0x10000
	s_addc_u32 s99, s99, 0
	global_load_dwordx4 v[164:167], v117, s[98:99]
	global_load_dwordx4 v[168:171], v117, s[98:99] offset:2048
	s_add_u32 s98, s98, 0x10000
	s_addc_u32 s99, s99, 0
	global_load_dwordx4 v[172:175], v117, s[98:99]
	global_load_dwordx4 v[188:191], v117, s[98:99] offset:2048
	s_add_u32 s98, s98, 0x10000
	s_addc_u32 s99, s99, 0
	global_load_dwordx4 v[192:195], v117, s[98:99]
	global_load_dwordx4 v[196:199], v117, s[98:99] offset:2048
	s_add_u32 s98, s98, 0x10000
	s_addc_u32 s99, s99, 0
	global_load_dwordx4 v[200:203], v117, s[98:99]
	global_load_dwordx4 v[204:207], v117, s[98:99] offset:2048
	s_add_u32 s98, s98, 0x10000
	s_addc_u32 s99, s99, 0
	global_load_dwordx4 v[208:211], v117, s[98:99]
	global_load_dwordx4 v[34:37], v117, s[98:99] offset:2048
	s_add_u32 s98, s98, 0x10000
	s_addc_u32 s99, s99, 0
	global_load_dwordx4 v[38:41], v117, s[98:99]
	global_load_dwordx4 v[52:55], v117, s[98:99] offset:2048
	s_mul_i32 s4, s31, s25
	s_add_i32 s4, s4, s30
	s_and_b32 s4, s4, 0xff
	v_lshl_or_b32 v30, s4, 10, v132
	s_mul_hi_u32 s4, s4, 0x15555556
	s_mulk_i32 s4, 0xd000
	v_add_u32_e32 v30, s4, v30
	s_lshl_b32 s4, s47, 8
	v_add_u32_e32 v138, 0x400, v129
	v_add_u32_e32 v139, 0x2000, v129
	v_add_u32_e32 v140, 0x2400, v129
	v_add_u32_e32 v141, 0x4000, v129
	v_add_u32_e32 v142, 0x4400, v129
	v_add_u32_e32 v143, 0x4800, v129
	v_add_u32_e32 v144, 0x6000, v129
	v_add_u32_e32 v145, 0x6400, v129
	v_add_u32_e32 v146, 0x6800, v129
	v_lshl_add_u64 v[114:115], v[102:103], 0, s[4:5]
	v_cmp_gt_u32_e32 vcc, s29, v30
	s_barrier
	ds_write2_b32 v129, v94, v90 offset1:16
	ds_write2_b32 v129, v95, v91 offset0:132 offset1:148
	ds_write2_b32 v138, v96, v92 offset0:8 offset1:24
	ds_write2_b32 v138, v97, v93 offset0:140 offset1:156
	ds_write2_b32 v129, v82, v78 offset0:32 offset1:48
	ds_write2_b32 v129, v83, v79 offset0:164 offset1:180
	ds_write2_b32 v138, v84, v80 offset0:40 offset1:56
	ds_write2_b32 v138, v85, v81 offset0:172 offset1:188
	ds_write2_b32 v139, v74, v70 offset0:64 offset1:80
	ds_write2_b32 v139, v75, v71 offset0:196 offset1:212
	ds_write2_b32 v140, v76, v72 offset0:72 offset1:88
	ds_write2_b32 v140, v77, v73 offset0:204 offset1:220
	ds_write2_b32 v139, v66, v58 offset0:96 offset1:112
	ds_write2_b32 v139, v67, v59 offset0:228 offset1:244
	ds_write2_b32 v140, v68, v60 offset0:104 offset1:120
	ds_write2_b32 v140, v69, v61 offset0:236 offset1:252
	ds_write2_b32 v141, v26, v22 offset0:128 offset1:144
	ds_write2_b32 v142, v27, v23 offset0:4 offset1:20
	ds_write2_b32 v142, v28, v24 offset0:136 offset1:152
	ds_write2_b32 v143, v29, v25 offset0:12 offset1:28
	ds_write2_b32 v141, v18, v14 offset0:160 offset1:176
	ds_write2_b32 v142, v19, v15 offset0:36 offset1:52
	ds_write2_b32 v142, v20, v16 offset0:168 offset1:184
	ds_write2_b32 v143, v21, v17 offset0:44 offset1:60
	ds_write2_b32 v144, v10, v6 offset0:192 offset1:208
	ds_write2_b32 v145, v11, v7 offset0:68 offset1:84
	ds_write2_b32 v145, v12, v8 offset0:200 offset1:216
	ds_write2_b32 v146, v13, v9 offset0:76 offset1:92
	ds_write2_b32 v144, v2, v86 offset0:224 offset1:240
	ds_write2_b32 v145, v3, v87 offset0:100 offset1:116
	ds_write2_b32 v145, v4, v88 offset0:232 offset1:248
	ds_write2_b32 v146, v5, v89 offset0:108 offset1:124
	s_waitcnt lgkmcnt(0)
	s_barrier
	v_lshrrev_b32_e32 v50, 4, v0
	v_and_b32_e32 v50, 15, v50
	v_mul_u32_u24_e32 v50, 0x210, v50
	v_and_b32_e32 v2, 15, v0
	v_lshl_add_u32 v50, v2, 5, v50
	ds_read_b128 v[42:45], v50 offset:32
	ds_read_b128 v[46:49], v50 offset:48
	s_waitcnt vmcnt(14)
	v_lshlrev_b32_e32 v2, 16, v148
	v_lshlrev_b32_e32 v3, 16, v152
	v_div_scale_f32 v4, s[4:5], v3, v3, v2
	v_rcp_f32_e32 v5, v4
	s_nop 0
	v_fma_f32 v6, -v4, v5, 1.0
	v_fmac_f32_e32 v5, v6, v5
	v_div_scale_f32 v7, vcc, v2, v3, v2
	v_mul_f32_e32 v8, v7, v5
	v_fma_f32 v6, -v4, v8, v7
	v_fmac_f32_e32 v8, v6, v5
	v_fma_f32 v4, -v4, v8, v7
	v_div_fmas_f32 v4, v4, v5, v8
	v_div_fixup_f32 v10, v4, v3, v2
	v_and_b32_e32 v2, 0xffff0000, v148
	v_and_b32_e32 v3, 0xffff0000, v152
	v_div_scale_f32 v4, s[4:5], v3, v3, v2
	v_rcp_f32_e32 v5, v4
	s_nop 0
	v_fma_f32 v6, -v4, v5, 1.0
	v_fmac_f32_e32 v5, v6, v5
	v_div_scale_f32 v7, vcc, v2, v3, v2
	v_mul_f32_e32 v8, v7, v5
	v_fma_f32 v6, -v4, v8, v7
	v_fmac_f32_e32 v8, v6, v5
	v_fma_f32 v4, -v4, v8, v7
	v_div_fmas_f32 v4, v4, v5, v8
	v_div_fixup_f32 v11, v4, v3, v2
	v_lshlrev_b32_e32 v2, 16, v149
	v_lshlrev_b32_e32 v3, 16, v153
	v_div_scale_f32 v4, s[4:5], v3, v3, v2
	v_rcp_f32_e32 v5, v4
	s_nop 0
	v_fma_f32 v6, -v4, v5, 1.0
	v_fmac_f32_e32 v5, v6, v5
	v_div_scale_f32 v7, vcc, v2, v3, v2
	v_mul_f32_e32 v8, v7, v5
	v_fma_f32 v6, -v4, v8, v7
	v_fmac_f32_e32 v8, v6, v5
	v_fma_f32 v4, -v4, v8, v7
	v_div_fmas_f32 v4, v4, v5, v8
	v_div_fixup_f32 v12, v4, v3, v2
	v_and_b32_e32 v2, 0xffff0000, v149
	v_and_b32_e32 v3, 0xffff0000, v153
	v_div_scale_f32 v4, s[4:5], v3, v3, v2
	v_rcp_f32_e32 v5, v4
	s_nop 0
	v_fma_f32 v6, -v4, v5, 1.0
	v_fmac_f32_e32 v5, v6, v5
	v_div_scale_f32 v7, vcc, v2, v3, v2
	v_mul_f32_e32 v8, v7, v5
	v_fma_f32 v6, -v4, v8, v7
	v_fmac_f32_e32 v8, v6, v5
	v_fma_f32 v4, -v4, v8, v7
	v_div_fmas_f32 v4, v4, v5, v8
	v_div_fixup_f32 v13, v4, v3, v2
	v_lshlrev_b32_e32 v2, 16, v150
	v_lshlrev_b32_e32 v3, 16, v154
	v_div_scale_f32 v4, s[4:5], v3, v3, v2
	v_rcp_f32_e32 v5, v4
	s_nop 0
	v_fma_f32 v6, -v4, v5, 1.0
	v_fmac_f32_e32 v5, v6, v5
	v_div_scale_f32 v7, vcc, v2, v3, v2
	v_mul_f32_e32 v8, v7, v5
	v_fma_f32 v6, -v4, v8, v7
	v_fmac_f32_e32 v8, v6, v5
	v_fma_f32 v4, -v4, v8, v7
	v_div_fmas_f32 v4, v4, v5, v8
	v_div_fixup_f32 v14, v4, v3, v2
	v_and_b32_e32 v2, 0xffff0000, v150
	v_and_b32_e32 v3, 0xffff0000, v154
	v_div_scale_f32 v4, s[4:5], v3, v3, v2
	v_rcp_f32_e32 v5, v4
	s_nop 0
	v_fma_f32 v6, -v4, v5, 1.0
	v_fmac_f32_e32 v5, v6, v5
	v_div_scale_f32 v7, vcc, v2, v3, v2
	v_mul_f32_e32 v8, v7, v5
	v_fma_f32 v6, -v4, v8, v7
	v_fmac_f32_e32 v8, v6, v5
	v_fma_f32 v4, -v4, v8, v7
	v_div_fmas_f32 v4, v4, v5, v8
	v_div_fixup_f32 v15, v4, v3, v2
	v_lshlrev_b32_e32 v2, 16, v151
	v_lshlrev_b32_e32 v3, 16, v155
	v_div_scale_f32 v4, s[4:5], v3, v3, v2
	v_rcp_f32_e32 v5, v4
	s_nop 0
	v_fma_f32 v6, -v4, v5, 1.0
	v_fmac_f32_e32 v5, v6, v5
	v_div_scale_f32 v7, vcc, v2, v3, v2
	v_mul_f32_e32 v8, v7, v5
	v_fma_f32 v6, -v4, v8, v7
	v_fmac_f32_e32 v8, v6, v5
	v_fma_f32 v4, -v4, v8, v7
	v_div_fmas_f32 v4, v4, v5, v8
	v_div_fixup_f32 v16, v4, v3, v2
	v_and_b32_e32 v2, 0xffff0000, v151
	v_and_b32_e32 v3, 0xffff0000, v155
	v_div_scale_f32 v4, s[4:5], v3, v3, v2
	v_rcp_f32_e32 v5, v4
	s_nop 0
	v_fma_f32 v6, -v4, v5, 1.0
	v_fmac_f32_e32 v5, v6, v5
	v_div_scale_f32 v7, vcc, v2, v3, v2
	v_mul_f32_e32 v8, v7, v5
	v_fma_f32 v6, -v4, v8, v7
	v_fmac_f32_e32 v8, v6, v5
	v_fma_f32 v4, -v4, v8, v7
	v_div_fmas_f32 v4, v4, v5, v8
	v_div_fixup_f32 v17, v4, v3, v2
	s_waitcnt lgkmcnt(0)
	v_pk_mul_f32 v[42:43], v[42:43], v[10:11]
	v_pk_mul_f32 v[44:45], v[44:45], v[12:13]
	v_pk_mul_f32 v[46:47], v[46:47], v[14:15]
	v_pk_mul_f32 v[48:49], v[48:49], v[16:17]
	ds_write_b128 v50, v[42:45] offset:32
	ds_write_b128 v50, v[46:49] offset:48
	ds_read_b128 v[42:45], v50 offset:8480
	ds_read_b128 v[46:49], v50 offset:8496
	s_waitcnt vmcnt(12)
	v_lshlrev_b32_e32 v2, 16, v156
	v_lshlrev_b32_e32 v3, 16, v160
	v_div_scale_f32 v4, s[4:5], v3, v3, v2
	v_rcp_f32_e32 v5, v4
	s_nop 0
	v_fma_f32 v6, -v4, v5, 1.0
	v_fmac_f32_e32 v5, v6, v5
	v_div_scale_f32 v7, vcc, v2, v3, v2
	v_mul_f32_e32 v8, v7, v5
	v_fma_f32 v6, -v4, v8, v7
	v_fmac_f32_e32 v8, v6, v5
	v_fma_f32 v4, -v4, v8, v7
	v_div_fmas_f32 v4, v4, v5, v8
	v_div_fixup_f32 v10, v4, v3, v2
	v_and_b32_e32 v2, 0xffff0000, v156
	v_and_b32_e32 v3, 0xffff0000, v160
	v_div_scale_f32 v4, s[4:5], v3, v3, v2
	v_rcp_f32_e32 v5, v4
	s_nop 0
	v_fma_f32 v6, -v4, v5, 1.0
	v_fmac_f32_e32 v5, v6, v5
	v_div_scale_f32 v7, vcc, v2, v3, v2
	v_mul_f32_e32 v8, v7, v5
	v_fma_f32 v6, -v4, v8, v7
	v_fmac_f32_e32 v8, v6, v5
	v_fma_f32 v4, -v4, v8, v7
	v_div_fmas_f32 v4, v4, v5, v8
	v_div_fixup_f32 v11, v4, v3, v2
	v_lshlrev_b32_e32 v2, 16, v157
	v_lshlrev_b32_e32 v3, 16, v161
	v_div_scale_f32 v4, s[4:5], v3, v3, v2
	v_rcp_f32_e32 v5, v4
	s_nop 0
	v_fma_f32 v6, -v4, v5, 1.0
	v_fmac_f32_e32 v5, v6, v5
	v_div_scale_f32 v7, vcc, v2, v3, v2
	v_mul_f32_e32 v8, v7, v5
	v_fma_f32 v6, -v4, v8, v7
	v_fmac_f32_e32 v8, v6, v5
	v_fma_f32 v4, -v4, v8, v7
	v_div_fmas_f32 v4, v4, v5, v8
	v_div_fixup_f32 v12, v4, v3, v2
	v_and_b32_e32 v2, 0xffff0000, v157
	v_and_b32_e32 v3, 0xffff0000, v161
	v_div_scale_f32 v4, s[4:5], v3, v3, v2
	v_rcp_f32_e32 v5, v4
	s_nop 0
	v_fma_f32 v6, -v4, v5, 1.0
	v_fmac_f32_e32 v5, v6, v5
	v_div_scale_f32 v7, vcc, v2, v3, v2
	v_mul_f32_e32 v8, v7, v5
	v_fma_f32 v6, -v4, v8, v7
	v_fmac_f32_e32 v8, v6, v5
	v_fma_f32 v4, -v4, v8, v7
	v_div_fmas_f32 v4, v4, v5, v8
	v_div_fixup_f32 v13, v4, v3, v2
	v_lshlrev_b32_e32 v2, 16, v158
	v_lshlrev_b32_e32 v3, 16, v162
	v_div_scale_f32 v4, s[4:5], v3, v3, v2
	v_rcp_f32_e32 v5, v4
	s_nop 0
	v_fma_f32 v6, -v4, v5, 1.0
	v_fmac_f32_e32 v5, v6, v5
	v_div_scale_f32 v7, vcc, v2, v3, v2
	v_mul_f32_e32 v8, v7, v5
	v_fma_f32 v6, -v4, v8, v7
	v_fmac_f32_e32 v8, v6, v5
	v_fma_f32 v4, -v4, v8, v7
	v_div_fmas_f32 v4, v4, v5, v8
	v_div_fixup_f32 v14, v4, v3, v2
	v_and_b32_e32 v2, 0xffff0000, v158
	v_and_b32_e32 v3, 0xffff0000, v162
	v_div_scale_f32 v4, s[4:5], v3, v3, v2
	v_rcp_f32_e32 v5, v4
	s_nop 0
	v_fma_f32 v6, -v4, v5, 1.0
	v_fmac_f32_e32 v5, v6, v5
	v_div_scale_f32 v7, vcc, v2, v3, v2
	v_mul_f32_e32 v8, v7, v5
	v_fma_f32 v6, -v4, v8, v7
	v_fmac_f32_e32 v8, v6, v5
	v_fma_f32 v4, -v4, v8, v7
	v_div_fmas_f32 v4, v4, v5, v8
	v_div_fixup_f32 v15, v4, v3, v2
	v_lshlrev_b32_e32 v2, 16, v159
	v_lshlrev_b32_e32 v3, 16, v163
	v_div_scale_f32 v4, s[4:5], v3, v3, v2
	v_rcp_f32_e32 v5, v4
	s_nop 0
	v_fma_f32 v6, -v4, v5, 1.0
	v_fmac_f32_e32 v5, v6, v5
	v_div_scale_f32 v7, vcc, v2, v3, v2
	v_mul_f32_e32 v8, v7, v5
	v_fma_f32 v6, -v4, v8, v7
	v_fmac_f32_e32 v8, v6, v5
	v_fma_f32 v4, -v4, v8, v7
	v_div_fmas_f32 v4, v4, v5, v8
	v_div_fixup_f32 v16, v4, v3, v2
	v_and_b32_e32 v2, 0xffff0000, v159
	v_and_b32_e32 v3, 0xffff0000, v163
	v_div_scale_f32 v4, s[4:5], v3, v3, v2
	v_rcp_f32_e32 v5, v4
	s_nop 0
	v_fma_f32 v6, -v4, v5, 1.0
	v_fmac_f32_e32 v5, v6, v5
	v_div_scale_f32 v7, vcc, v2, v3, v2
	v_mul_f32_e32 v8, v7, v5
	v_fma_f32 v6, -v4, v8, v7
	v_fmac_f32_e32 v8, v6, v5
	v_fma_f32 v4, -v4, v8, v7
	v_div_fmas_f32 v4, v4, v5, v8
	v_div_fixup_f32 v17, v4, v3, v2
	s_waitcnt lgkmcnt(0)
	v_pk_mul_f32 v[42:43], v[42:43], v[10:11]
	v_pk_mul_f32 v[44:45], v[44:45], v[12:13]
	v_pk_mul_f32 v[46:47], v[46:47], v[14:15]
	v_pk_mul_f32 v[48:49], v[48:49], v[16:17]
	ds_write_b128 v50, v[42:45] offset:8480
	ds_write_b128 v50, v[46:49] offset:8496
	ds_read_b128 v[42:45], v50 offset:16928
	ds_read_b128 v[46:49], v50 offset:16944
	s_waitcnt vmcnt(10)
	v_lshlrev_b32_e32 v2, 16, v164
	v_lshlrev_b32_e32 v3, 16, v168
	v_div_scale_f32 v4, s[4:5], v3, v3, v2
	v_rcp_f32_e32 v5, v4
	s_nop 0
	v_fma_f32 v6, -v4, v5, 1.0
	v_fmac_f32_e32 v5, v6, v5
	v_div_scale_f32 v7, vcc, v2, v3, v2
	v_mul_f32_e32 v8, v7, v5
	v_fma_f32 v6, -v4, v8, v7
	v_fmac_f32_e32 v8, v6, v5
	v_fma_f32 v4, -v4, v8, v7
	v_div_fmas_f32 v4, v4, v5, v8
	v_div_fixup_f32 v10, v4, v3, v2
	v_and_b32_e32 v2, 0xffff0000, v164
	v_and_b32_e32 v3, 0xffff0000, v168
	v_div_scale_f32 v4, s[4:5], v3, v3, v2
	v_rcp_f32_e32 v5, v4
	s_nop 0
	v_fma_f32 v6, -v4, v5, 1.0
	v_fmac_f32_e32 v5, v6, v5
	v_div_scale_f32 v7, vcc, v2, v3, v2
	v_mul_f32_e32 v8, v7, v5
	v_fma_f32 v6, -v4, v8, v7
	v_fmac_f32_e32 v8, v6, v5
	v_fma_f32 v4, -v4, v8, v7
	v_div_fmas_f32 v4, v4, v5, v8
	v_div_fixup_f32 v11, v4, v3, v2
	v_lshlrev_b32_e32 v2, 16, v165
	v_lshlrev_b32_e32 v3, 16, v169
	v_div_scale_f32 v4, s[4:5], v3, v3, v2
	v_rcp_f32_e32 v5, v4
	s_nop 0
	v_fma_f32 v6, -v4, v5, 1.0
	v_fmac_f32_e32 v5, v6, v5
	v_div_scale_f32 v7, vcc, v2, v3, v2
	v_mul_f32_e32 v8, v7, v5
	v_fma_f32 v6, -v4, v8, v7
	v_fmac_f32_e32 v8, v6, v5
	v_fma_f32 v4, -v4, v8, v7
	v_div_fmas_f32 v4, v4, v5, v8
	v_div_fixup_f32 v12, v4, v3, v2
	v_and_b32_e32 v2, 0xffff0000, v165
	v_and_b32_e32 v3, 0xffff0000, v169
	v_div_scale_f32 v4, s[4:5], v3, v3, v2
	v_rcp_f32_e32 v5, v4
	s_nop 0
	v_fma_f32 v6, -v4, v5, 1.0
	v_fmac_f32_e32 v5, v6, v5
	v_div_scale_f32 v7, vcc, v2, v3, v2
	v_mul_f32_e32 v8, v7, v5
	v_fma_f32 v6, -v4, v8, v7
	v_fmac_f32_e32 v8, v6, v5
	v_fma_f32 v4, -v4, v8, v7
	v_div_fmas_f32 v4, v4, v5, v8
	v_div_fixup_f32 v13, v4, v3, v2
	v_lshlrev_b32_e32 v2, 16, v166
	v_lshlrev_b32_e32 v3, 16, v170
	v_div_scale_f32 v4, s[4:5], v3, v3, v2
	v_rcp_f32_e32 v5, v4
	s_nop 0
	v_fma_f32 v6, -v4, v5, 1.0
	v_fmac_f32_e32 v5, v6, v5
	v_div_scale_f32 v7, vcc, v2, v3, v2
	v_mul_f32_e32 v8, v7, v5
	v_fma_f32 v6, -v4, v8, v7
	v_fmac_f32_e32 v8, v6, v5
	v_fma_f32 v4, -v4, v8, v7
	v_div_fmas_f32 v4, v4, v5, v8
	v_div_fixup_f32 v14, v4, v3, v2
	v_and_b32_e32 v2, 0xffff0000, v166
	v_and_b32_e32 v3, 0xffff0000, v170
	v_div_scale_f32 v4, s[4:5], v3, v3, v2
	v_rcp_f32_e32 v5, v4
	s_nop 0
	v_fma_f32 v6, -v4, v5, 1.0
	v_fmac_f32_e32 v5, v6, v5
	v_div_scale_f32 v7, vcc, v2, v3, v2
	v_mul_f32_e32 v8, v7, v5
	v_fma_f32 v6, -v4, v8, v7
	v_fmac_f32_e32 v8, v6, v5
	v_fma_f32 v4, -v4, v8, v7
	v_div_fmas_f32 v4, v4, v5, v8
	v_div_fixup_f32 v15, v4, v3, v2
	v_lshlrev_b32_e32 v2, 16, v167
	v_lshlrev_b32_e32 v3, 16, v171
	v_div_scale_f32 v4, s[4:5], v3, v3, v2
	v_rcp_f32_e32 v5, v4
	s_nop 0
	v_fma_f32 v6, -v4, v5, 1.0
	v_fmac_f32_e32 v5, v6, v5
	v_div_scale_f32 v7, vcc, v2, v3, v2
	v_mul_f32_e32 v8, v7, v5
	v_fma_f32 v6, -v4, v8, v7
	v_fmac_f32_e32 v8, v6, v5
	v_fma_f32 v4, -v4, v8, v7
	v_div_fmas_f32 v4, v4, v5, v8
	v_div_fixup_f32 v16, v4, v3, v2
	v_and_b32_e32 v2, 0xffff0000, v167
	v_and_b32_e32 v3, 0xffff0000, v171
	v_div_scale_f32 v4, s[4:5], v3, v3, v2
	v_rcp_f32_e32 v5, v4
	s_nop 0
	v_fma_f32 v6, -v4, v5, 1.0
	v_fmac_f32_e32 v5, v6, v5
	v_div_scale_f32 v7, vcc, v2, v3, v2
	v_mul_f32_e32 v8, v7, v5
	v_fma_f32 v6, -v4, v8, v7
	v_fmac_f32_e32 v8, v6, v5
	v_fma_f32 v4, -v4, v8, v7
	v_div_fmas_f32 v4, v4, v5, v8
	v_div_fixup_f32 v17, v4, v3, v2
	s_waitcnt lgkmcnt(0)
	v_pk_mul_f32 v[42:43], v[42:43], v[10:11]
	v_pk_mul_f32 v[44:45], v[44:45], v[12:13]
	v_pk_mul_f32 v[46:47], v[46:47], v[14:15]
	v_pk_mul_f32 v[48:49], v[48:49], v[16:17]
	ds_write_b128 v50, v[42:45] offset:16928
	ds_write_b128 v50, v[46:49] offset:16944
	ds_read_b128 v[42:45], v50 offset:25376
	ds_read_b128 v[46:49], v50 offset:25392
	s_waitcnt vmcnt(8)
	v_lshlrev_b32_e32 v2, 16, v172
	v_lshlrev_b32_e32 v3, 16, v188
	v_div_scale_f32 v4, s[4:5], v3, v3, v2
	v_rcp_f32_e32 v5, v4
	s_nop 0
	v_fma_f32 v6, -v4, v5, 1.0
	v_fmac_f32_e32 v5, v6, v5
	v_div_scale_f32 v7, vcc, v2, v3, v2
	v_mul_f32_e32 v8, v7, v5
	v_fma_f32 v6, -v4, v8, v7
	v_fmac_f32_e32 v8, v6, v5
	v_fma_f32 v4, -v4, v8, v7
	v_div_fmas_f32 v4, v4, v5, v8
	v_div_fixup_f32 v10, v4, v3, v2
	v_and_b32_e32 v2, 0xffff0000, v172
	v_and_b32_e32 v3, 0xffff0000, v188
	v_div_scale_f32 v4, s[4:5], v3, v3, v2
	v_rcp_f32_e32 v5, v4
	s_nop 0
	v_fma_f32 v6, -v4, v5, 1.0
	v_fmac_f32_e32 v5, v6, v5
	v_div_scale_f32 v7, vcc, v2, v3, v2
	v_mul_f32_e32 v8, v7, v5
	v_fma_f32 v6, -v4, v8, v7
	v_fmac_f32_e32 v8, v6, v5
	v_fma_f32 v4, -v4, v8, v7
	v_div_fmas_f32 v4, v4, v5, v8
	v_div_fixup_f32 v11, v4, v3, v2
	v_lshlrev_b32_e32 v2, 16, v173
	v_lshlrev_b32_e32 v3, 16, v189
	v_div_scale_f32 v4, s[4:5], v3, v3, v2
	v_rcp_f32_e32 v5, v4
	s_nop 0
	v_fma_f32 v6, -v4, v5, 1.0
	v_fmac_f32_e32 v5, v6, v5
	v_div_scale_f32 v7, vcc, v2, v3, v2
	v_mul_f32_e32 v8, v7, v5
	v_fma_f32 v6, -v4, v8, v7
	v_fmac_f32_e32 v8, v6, v5
	v_fma_f32 v4, -v4, v8, v7
	v_div_fmas_f32 v4, v4, v5, v8
	v_div_fixup_f32 v12, v4, v3, v2
	v_and_b32_e32 v2, 0xffff0000, v173
	v_and_b32_e32 v3, 0xffff0000, v189
	v_div_scale_f32 v4, s[4:5], v3, v3, v2
	v_rcp_f32_e32 v5, v4
	s_nop 0
	v_fma_f32 v6, -v4, v5, 1.0
	v_fmac_f32_e32 v5, v6, v5
	v_div_scale_f32 v7, vcc, v2, v3, v2
	v_mul_f32_e32 v8, v7, v5
	v_fma_f32 v6, -v4, v8, v7
	v_fmac_f32_e32 v8, v6, v5
	v_fma_f32 v4, -v4, v8, v7
	v_div_fmas_f32 v4, v4, v5, v8
	v_div_fixup_f32 v13, v4, v3, v2
	v_lshlrev_b32_e32 v2, 16, v174
	v_lshlrev_b32_e32 v3, 16, v190
	v_div_scale_f32 v4, s[4:5], v3, v3, v2
	v_rcp_f32_e32 v5, v4
	s_nop 0
	v_fma_f32 v6, -v4, v5, 1.0
	v_fmac_f32_e32 v5, v6, v5
	v_div_scale_f32 v7, vcc, v2, v3, v2
	v_mul_f32_e32 v8, v7, v5
	v_fma_f32 v6, -v4, v8, v7
	v_fmac_f32_e32 v8, v6, v5
	v_fma_f32 v4, -v4, v8, v7
	v_div_fmas_f32 v4, v4, v5, v8
	v_div_fixup_f32 v14, v4, v3, v2
	v_and_b32_e32 v2, 0xffff0000, v174
	v_and_b32_e32 v3, 0xffff0000, v190
	v_div_scale_f32 v4, s[4:5], v3, v3, v2
	v_rcp_f32_e32 v5, v4
	s_nop 0
	v_fma_f32 v6, -v4, v5, 1.0
	v_fmac_f32_e32 v5, v6, v5
	v_div_scale_f32 v7, vcc, v2, v3, v2
	v_mul_f32_e32 v8, v7, v5
	v_fma_f32 v6, -v4, v8, v7
	v_fmac_f32_e32 v8, v6, v5
	v_fma_f32 v4, -v4, v8, v7
	v_div_fmas_f32 v4, v4, v5, v8
	v_div_fixup_f32 v15, v4, v3, v2
	v_lshlrev_b32_e32 v2, 16, v175
	v_lshlrev_b32_e32 v3, 16, v191
	v_div_scale_f32 v4, s[4:5], v3, v3, v2
	v_rcp_f32_e32 v5, v4
	s_nop 0
	v_fma_f32 v6, -v4, v5, 1.0
	v_fmac_f32_e32 v5, v6, v5
	v_div_scale_f32 v7, vcc, v2, v3, v2
	v_mul_f32_e32 v8, v7, v5
	v_fma_f32 v6, -v4, v8, v7
	v_fmac_f32_e32 v8, v6, v5
	v_fma_f32 v4, -v4, v8, v7
	v_div_fmas_f32 v4, v4, v5, v8
	v_div_fixup_f32 v16, v4, v3, v2
	v_and_b32_e32 v2, 0xffff0000, v175
	v_and_b32_e32 v3, 0xffff0000, v191
	v_div_scale_f32 v4, s[4:5], v3, v3, v2
	v_rcp_f32_e32 v5, v4
	s_nop 0
	v_fma_f32 v6, -v4, v5, 1.0
	v_fmac_f32_e32 v5, v6, v5
	v_div_scale_f32 v7, vcc, v2, v3, v2
	v_mul_f32_e32 v8, v7, v5
	v_fma_f32 v6, -v4, v8, v7
	v_fmac_f32_e32 v8, v6, v5
	v_fma_f32 v4, -v4, v8, v7
	v_div_fmas_f32 v4, v4, v5, v8
	v_div_fixup_f32 v17, v4, v3, v2
	s_waitcnt lgkmcnt(0)
	v_pk_mul_f32 v[42:43], v[42:43], v[10:11]
	v_pk_mul_f32 v[44:45], v[44:45], v[12:13]
	v_pk_mul_f32 v[46:47], v[46:47], v[14:15]
	v_pk_mul_f32 v[48:49], v[48:49], v[16:17]
	ds_write_b128 v50, v[42:45] offset:25376
	ds_write_b128 v50, v[46:49] offset:25392
	ds_read_b128 v[42:45], v50 offset:33824
	ds_read_b128 v[46:49], v50 offset:33840
	s_waitcnt vmcnt(6)
	v_lshlrev_b32_e32 v2, 16, v192
	v_lshlrev_b32_e32 v3, 16, v196
	v_div_scale_f32 v4, s[4:5], v3, v3, v2
	v_rcp_f32_e32 v5, v4
	s_nop 0
	v_fma_f32 v6, -v4, v5, 1.0
	v_fmac_f32_e32 v5, v6, v5
	v_div_scale_f32 v7, vcc, v2, v3, v2
	v_mul_f32_e32 v8, v7, v5
	v_fma_f32 v6, -v4, v8, v7
	v_fmac_f32_e32 v8, v6, v5
	v_fma_f32 v4, -v4, v8, v7
	v_div_fmas_f32 v4, v4, v5, v8
	v_div_fixup_f32 v10, v4, v3, v2
	v_and_b32_e32 v2, 0xffff0000, v192
	v_and_b32_e32 v3, 0xffff0000, v196
	v_div_scale_f32 v4, s[4:5], v3, v3, v2
	v_rcp_f32_e32 v5, v4
	s_nop 0
	v_fma_f32 v6, -v4, v5, 1.0
	v_fmac_f32_e32 v5, v6, v5
	v_div_scale_f32 v7, vcc, v2, v3, v2
	v_mul_f32_e32 v8, v7, v5
	v_fma_f32 v6, -v4, v8, v7
	v_fmac_f32_e32 v8, v6, v5
	v_fma_f32 v4, -v4, v8, v7
	v_div_fmas_f32 v4, v4, v5, v8
	v_div_fixup_f32 v11, v4, v3, v2
	v_lshlrev_b32_e32 v2, 16, v193
	v_lshlrev_b32_e32 v3, 16, v197
	v_div_scale_f32 v4, s[4:5], v3, v3, v2
	v_rcp_f32_e32 v5, v4
	s_nop 0
	v_fma_f32 v6, -v4, v5, 1.0
	v_fmac_f32_e32 v5, v6, v5
	v_div_scale_f32 v7, vcc, v2, v3, v2
	v_mul_f32_e32 v8, v7, v5
	v_fma_f32 v6, -v4, v8, v7
	v_fmac_f32_e32 v8, v6, v5
	v_fma_f32 v4, -v4, v8, v7
	v_div_fmas_f32 v4, v4, v5, v8
	v_div_fixup_f32 v12, v4, v3, v2
	v_and_b32_e32 v2, 0xffff0000, v193
	v_and_b32_e32 v3, 0xffff0000, v197
	v_div_scale_f32 v4, s[4:5], v3, v3, v2
	v_rcp_f32_e32 v5, v4
	s_nop 0
	v_fma_f32 v6, -v4, v5, 1.0
	v_fmac_f32_e32 v5, v6, v5
	v_div_scale_f32 v7, vcc, v2, v3, v2
	v_mul_f32_e32 v8, v7, v5
	v_fma_f32 v6, -v4, v8, v7
	v_fmac_f32_e32 v8, v6, v5
	v_fma_f32 v4, -v4, v8, v7
	v_div_fmas_f32 v4, v4, v5, v8
	v_div_fixup_f32 v13, v4, v3, v2
	v_lshlrev_b32_e32 v2, 16, v194
	v_lshlrev_b32_e32 v3, 16, v198
	v_div_scale_f32 v4, s[4:5], v3, v3, v2
	v_rcp_f32_e32 v5, v4
	s_nop 0
	v_fma_f32 v6, -v4, v5, 1.0
	v_fmac_f32_e32 v5, v6, v5
	v_div_scale_f32 v7, vcc, v2, v3, v2
	v_mul_f32_e32 v8, v7, v5
	v_fma_f32 v6, -v4, v8, v7
	v_fmac_f32_e32 v8, v6, v5
	v_fma_f32 v4, -v4, v8, v7
	v_div_fmas_f32 v4, v4, v5, v8
	v_div_fixup_f32 v14, v4, v3, v2
	v_and_b32_e32 v2, 0xffff0000, v194
	v_and_b32_e32 v3, 0xffff0000, v198
	v_div_scale_f32 v4, s[4:5], v3, v3, v2
	v_rcp_f32_e32 v5, v4
	s_nop 0
	v_fma_f32 v6, -v4, v5, 1.0
	v_fmac_f32_e32 v5, v6, v5
	v_div_scale_f32 v7, vcc, v2, v3, v2
	v_mul_f32_e32 v8, v7, v5
	v_fma_f32 v6, -v4, v8, v7
	v_fmac_f32_e32 v8, v6, v5
	v_fma_f32 v4, -v4, v8, v7
	v_div_fmas_f32 v4, v4, v5, v8
	v_div_fixup_f32 v15, v4, v3, v2
	v_lshlrev_b32_e32 v2, 16, v195
	v_lshlrev_b32_e32 v3, 16, v199
	v_div_scale_f32 v4, s[4:5], v3, v3, v2
	v_rcp_f32_e32 v5, v4
	s_nop 0
	v_fma_f32 v6, -v4, v5, 1.0
	v_fmac_f32_e32 v5, v6, v5
	v_div_scale_f32 v7, vcc, v2, v3, v2
	v_mul_f32_e32 v8, v7, v5
	v_fma_f32 v6, -v4, v8, v7
	v_fmac_f32_e32 v8, v6, v5
	v_fma_f32 v4, -v4, v8, v7
	v_div_fmas_f32 v4, v4, v5, v8
	v_div_fixup_f32 v16, v4, v3, v2
	v_and_b32_e32 v2, 0xffff0000, v195
	v_and_b32_e32 v3, 0xffff0000, v199
	v_div_scale_f32 v4, s[4:5], v3, v3, v2
	v_rcp_f32_e32 v5, v4
	s_nop 0
	v_fma_f32 v6, -v4, v5, 1.0
	v_fmac_f32_e32 v5, v6, v5
	v_div_scale_f32 v7, vcc, v2, v3, v2
	v_mul_f32_e32 v8, v7, v5
	v_fma_f32 v6, -v4, v8, v7
	v_fmac_f32_e32 v8, v6, v5
	v_fma_f32 v4, -v4, v8, v7
	v_div_fmas_f32 v4, v4, v5, v8
	v_div_fixup_f32 v17, v4, v3, v2
	s_waitcnt lgkmcnt(0)
	v_pk_mul_f32 v[42:43], v[42:43], v[10:11]
	v_pk_mul_f32 v[44:45], v[44:45], v[12:13]
	v_pk_mul_f32 v[46:47], v[46:47], v[14:15]
	v_pk_mul_f32 v[48:49], v[48:49], v[16:17]
	ds_write_b128 v50, v[42:45] offset:33824
	ds_write_b128 v50, v[46:49] offset:33840
	ds_read_b128 v[42:45], v50 offset:42272
	ds_read_b128 v[46:49], v50 offset:42288
	s_waitcnt vmcnt(4)
	v_lshlrev_b32_e32 v2, 16, v200
	v_lshlrev_b32_e32 v3, 16, v204
	v_div_scale_f32 v4, s[4:5], v3, v3, v2
	v_rcp_f32_e32 v5, v4
	s_nop 0
	v_fma_f32 v6, -v4, v5, 1.0
	v_fmac_f32_e32 v5, v6, v5
	v_div_scale_f32 v7, vcc, v2, v3, v2
	v_mul_f32_e32 v8, v7, v5
	v_fma_f32 v6, -v4, v8, v7
	v_fmac_f32_e32 v8, v6, v5
	v_fma_f32 v4, -v4, v8, v7
	v_div_fmas_f32 v4, v4, v5, v8
	v_div_fixup_f32 v10, v4, v3, v2
	v_and_b32_e32 v2, 0xffff0000, v200
	v_and_b32_e32 v3, 0xffff0000, v204
	v_div_scale_f32 v4, s[4:5], v3, v3, v2
	v_rcp_f32_e32 v5, v4
	s_nop 0
	v_fma_f32 v6, -v4, v5, 1.0
	v_fmac_f32_e32 v5, v6, v5
	v_div_scale_f32 v7, vcc, v2, v3, v2
	v_mul_f32_e32 v8, v7, v5
	v_fma_f32 v6, -v4, v8, v7
	v_fmac_f32_e32 v8, v6, v5
	v_fma_f32 v4, -v4, v8, v7
	v_div_fmas_f32 v4, v4, v5, v8
	v_div_fixup_f32 v11, v4, v3, v2
	v_lshlrev_b32_e32 v2, 16, v201
	v_lshlrev_b32_e32 v3, 16, v205
	v_div_scale_f32 v4, s[4:5], v3, v3, v2
	v_rcp_f32_e32 v5, v4
	s_nop 0
	v_fma_f32 v6, -v4, v5, 1.0
	v_fmac_f32_e32 v5, v6, v5
	v_div_scale_f32 v7, vcc, v2, v3, v2
	v_mul_f32_e32 v8, v7, v5
	v_fma_f32 v6, -v4, v8, v7
	v_fmac_f32_e32 v8, v6, v5
	v_fma_f32 v4, -v4, v8, v7
	v_div_fmas_f32 v4, v4, v5, v8
	v_div_fixup_f32 v12, v4, v3, v2
	v_and_b32_e32 v2, 0xffff0000, v201
	v_and_b32_e32 v3, 0xffff0000, v205
	v_div_scale_f32 v4, s[4:5], v3, v3, v2
	v_rcp_f32_e32 v5, v4
	s_nop 0
	v_fma_f32 v6, -v4, v5, 1.0
	v_fmac_f32_e32 v5, v6, v5
	v_div_scale_f32 v7, vcc, v2, v3, v2
	v_mul_f32_e32 v8, v7, v5
	v_fma_f32 v6, -v4, v8, v7
	v_fmac_f32_e32 v8, v6, v5
	v_fma_f32 v4, -v4, v8, v7
	v_div_fmas_f32 v4, v4, v5, v8
	v_div_fixup_f32 v13, v4, v3, v2
	v_lshlrev_b32_e32 v2, 16, v202
	v_lshlrev_b32_e32 v3, 16, v206
	v_div_scale_f32 v4, s[4:5], v3, v3, v2
	v_rcp_f32_e32 v5, v4
	s_nop 0
	v_fma_f32 v6, -v4, v5, 1.0
	v_fmac_f32_e32 v5, v6, v5
	v_div_scale_f32 v7, vcc, v2, v3, v2
	v_mul_f32_e32 v8, v7, v5
	v_fma_f32 v6, -v4, v8, v7
	v_fmac_f32_e32 v8, v6, v5
	v_fma_f32 v4, -v4, v8, v7
	v_div_fmas_f32 v4, v4, v5, v8
	v_div_fixup_f32 v14, v4, v3, v2
	v_and_b32_e32 v2, 0xffff0000, v202
	v_and_b32_e32 v3, 0xffff0000, v206
	v_div_scale_f32 v4, s[4:5], v3, v3, v2
	v_rcp_f32_e32 v5, v4
	s_nop 0
	v_fma_f32 v6, -v4, v5, 1.0
	v_fmac_f32_e32 v5, v6, v5
	v_div_scale_f32 v7, vcc, v2, v3, v2
	v_mul_f32_e32 v8, v7, v5
	v_fma_f32 v6, -v4, v8, v7
	v_fmac_f32_e32 v8, v6, v5
	v_fma_f32 v4, -v4, v8, v7
	v_div_fmas_f32 v4, v4, v5, v8
	v_div_fixup_f32 v15, v4, v3, v2
	v_lshlrev_b32_e32 v2, 16, v203
	v_lshlrev_b32_e32 v3, 16, v207
	v_div_scale_f32 v4, s[4:5], v3, v3, v2
	v_rcp_f32_e32 v5, v4
	s_nop 0
	v_fma_f32 v6, -v4, v5, 1.0
	v_fmac_f32_e32 v5, v6, v5
	v_div_scale_f32 v7, vcc, v2, v3, v2
	v_mul_f32_e32 v8, v7, v5
	v_fma_f32 v6, -v4, v8, v7
	v_fmac_f32_e32 v8, v6, v5
	v_fma_f32 v4, -v4, v8, v7
	v_div_fmas_f32 v4, v4, v5, v8
	v_div_fixup_f32 v16, v4, v3, v2
	v_and_b32_e32 v2, 0xffff0000, v203
	v_and_b32_e32 v3, 0xffff0000, v207
	v_div_scale_f32 v4, s[4:5], v3, v3, v2
	v_rcp_f32_e32 v5, v4
	s_nop 0
	v_fma_f32 v6, -v4, v5, 1.0
	v_fmac_f32_e32 v5, v6, v5
	v_div_scale_f32 v7, vcc, v2, v3, v2
	v_mul_f32_e32 v8, v7, v5
	v_fma_f32 v6, -v4, v8, v7
	v_fmac_f32_e32 v8, v6, v5
	v_fma_f32 v4, -v4, v8, v7
	v_div_fmas_f32 v4, v4, v5, v8
	v_div_fixup_f32 v17, v4, v3, v2
	s_waitcnt lgkmcnt(0)
	v_pk_mul_f32 v[42:43], v[42:43], v[10:11]
	v_pk_mul_f32 v[44:45], v[44:45], v[12:13]
	v_pk_mul_f32 v[46:47], v[46:47], v[14:15]
	v_pk_mul_f32 v[48:49], v[48:49], v[16:17]
	ds_write_b128 v50, v[42:45] offset:42272
	ds_write_b128 v50, v[46:49] offset:42288
	ds_read_b128 v[42:45], v50 offset:50720
	ds_read_b128 v[46:49], v50 offset:50736
	s_waitcnt vmcnt(2)
	v_lshlrev_b32_e32 v2, 16, v208
	v_lshlrev_b32_e32 v3, 16, v34
	v_div_scale_f32 v4, s[4:5], v3, v3, v2
	v_rcp_f32_e32 v5, v4
	s_nop 0
	v_fma_f32 v6, -v4, v5, 1.0
	v_fmac_f32_e32 v5, v6, v5
	v_div_scale_f32 v7, vcc, v2, v3, v2
	v_mul_f32_e32 v8, v7, v5
	v_fma_f32 v6, -v4, v8, v7
	v_fmac_f32_e32 v8, v6, v5
	v_fma_f32 v4, -v4, v8, v7
	v_div_fmas_f32 v4, v4, v5, v8
	v_div_fixup_f32 v10, v4, v3, v2
	v_and_b32_e32 v2, 0xffff0000, v208
	v_and_b32_e32 v3, 0xffff0000, v34
	v_div_scale_f32 v4, s[4:5], v3, v3, v2
	v_rcp_f32_e32 v5, v4
	s_nop 0
	v_fma_f32 v6, -v4, v5, 1.0
	v_fmac_f32_e32 v5, v6, v5
	v_div_scale_f32 v7, vcc, v2, v3, v2
	v_mul_f32_e32 v8, v7, v5
	v_fma_f32 v6, -v4, v8, v7
	v_fmac_f32_e32 v8, v6, v5
	v_fma_f32 v4, -v4, v8, v7
	v_div_fmas_f32 v4, v4, v5, v8
	v_div_fixup_f32 v11, v4, v3, v2
	v_lshlrev_b32_e32 v2, 16, v209
	v_lshlrev_b32_e32 v3, 16, v35
	v_div_scale_f32 v4, s[4:5], v3, v3, v2
	v_rcp_f32_e32 v5, v4
	s_nop 0
	v_fma_f32 v6, -v4, v5, 1.0
	v_fmac_f32_e32 v5, v6, v5
	v_div_scale_f32 v7, vcc, v2, v3, v2
	v_mul_f32_e32 v8, v7, v5
	v_fma_f32 v6, -v4, v8, v7
	v_fmac_f32_e32 v8, v6, v5
	v_fma_f32 v4, -v4, v8, v7
	v_div_fmas_f32 v4, v4, v5, v8
	v_div_fixup_f32 v12, v4, v3, v2
	v_and_b32_e32 v2, 0xffff0000, v209
	v_and_b32_e32 v3, 0xffff0000, v35
	v_div_scale_f32 v4, s[4:5], v3, v3, v2
	v_rcp_f32_e32 v5, v4
	s_nop 0
	v_fma_f32 v6, -v4, v5, 1.0
	v_fmac_f32_e32 v5, v6, v5
	v_div_scale_f32 v7, vcc, v2, v3, v2
	v_mul_f32_e32 v8, v7, v5
	v_fma_f32 v6, -v4, v8, v7
	v_fmac_f32_e32 v8, v6, v5
	v_fma_f32 v4, -v4, v8, v7
	v_div_fmas_f32 v4, v4, v5, v8
	v_div_fixup_f32 v13, v4, v3, v2
	v_lshlrev_b32_e32 v2, 16, v210
	v_lshlrev_b32_e32 v3, 16, v36
	v_div_scale_f32 v4, s[4:5], v3, v3, v2
	v_rcp_f32_e32 v5, v4
	s_nop 0
	v_fma_f32 v6, -v4, v5, 1.0
	v_fmac_f32_e32 v5, v6, v5
	v_div_scale_f32 v7, vcc, v2, v3, v2
	v_mul_f32_e32 v8, v7, v5
	v_fma_f32 v6, -v4, v8, v7
	v_fmac_f32_e32 v8, v6, v5
	v_fma_f32 v4, -v4, v8, v7
	v_div_fmas_f32 v4, v4, v5, v8
	v_div_fixup_f32 v14, v4, v3, v2
	v_and_b32_e32 v2, 0xffff0000, v210
	v_and_b32_e32 v3, 0xffff0000, v36
	v_div_scale_f32 v4, s[4:5], v3, v3, v2
	v_rcp_f32_e32 v5, v4
	s_nop 0
	v_fma_f32 v6, -v4, v5, 1.0
	v_fmac_f32_e32 v5, v6, v5
	v_div_scale_f32 v7, vcc, v2, v3, v2
	v_mul_f32_e32 v8, v7, v5
	v_fma_f32 v6, -v4, v8, v7
	v_fmac_f32_e32 v8, v6, v5
	v_fma_f32 v4, -v4, v8, v7
	v_div_fmas_f32 v4, v4, v5, v8
	v_div_fixup_f32 v15, v4, v3, v2
	v_lshlrev_b32_e32 v2, 16, v211
	v_lshlrev_b32_e32 v3, 16, v37
	v_div_scale_f32 v4, s[4:5], v3, v3, v2
	v_rcp_f32_e32 v5, v4
	s_nop 0
	v_fma_f32 v6, -v4, v5, 1.0
	v_fmac_f32_e32 v5, v6, v5
	v_div_scale_f32 v7, vcc, v2, v3, v2
	v_mul_f32_e32 v8, v7, v5
	v_fma_f32 v6, -v4, v8, v7
	v_fmac_f32_e32 v8, v6, v5
	v_fma_f32 v4, -v4, v8, v7
	v_div_fmas_f32 v4, v4, v5, v8
	v_div_fixup_f32 v16, v4, v3, v2
	v_and_b32_e32 v2, 0xffff0000, v211
	v_and_b32_e32 v3, 0xffff0000, v37
	v_div_scale_f32 v4, s[4:5], v3, v3, v2
	v_rcp_f32_e32 v5, v4
	s_nop 0
	v_fma_f32 v6, -v4, v5, 1.0
	v_fmac_f32_e32 v5, v6, v5
	v_div_scale_f32 v7, vcc, v2, v3, v2
	v_mul_f32_e32 v8, v7, v5
	v_fma_f32 v6, -v4, v8, v7
	v_fmac_f32_e32 v8, v6, v5
	v_fma_f32 v4, -v4, v8, v7
	v_div_fmas_f32 v4, v4, v5, v8
	v_div_fixup_f32 v17, v4, v3, v2
	s_waitcnt lgkmcnt(0)
	v_pk_mul_f32 v[42:43], v[42:43], v[10:11]
	v_pk_mul_f32 v[44:45], v[44:45], v[12:13]
	v_pk_mul_f32 v[46:47], v[46:47], v[14:15]
	v_pk_mul_f32 v[48:49], v[48:49], v[16:17]
	ds_write_b128 v50, v[42:45] offset:50720
	ds_write_b128 v50, v[46:49] offset:50736
	ds_read_b128 v[42:45], v50 offset:59168
	ds_read_b128 v[46:49], v50 offset:59184
	s_waitcnt vmcnt(0)
	v_lshlrev_b32_e32 v2, 16, v38
	v_lshlrev_b32_e32 v3, 16, v52
	v_div_scale_f32 v4, s[4:5], v3, v3, v2
	v_rcp_f32_e32 v5, v4
	s_nop 0
	v_fma_f32 v6, -v4, v5, 1.0
	v_fmac_f32_e32 v5, v6, v5
	v_div_scale_f32 v7, vcc, v2, v3, v2
	v_mul_f32_e32 v8, v7, v5
	v_fma_f32 v6, -v4, v8, v7
	v_fmac_f32_e32 v8, v6, v5
	v_fma_f32 v4, -v4, v8, v7
	v_div_fmas_f32 v4, v4, v5, v8
	v_div_fixup_f32 v10, v4, v3, v2
	v_and_b32_e32 v2, 0xffff0000, v38
	v_and_b32_e32 v3, 0xffff0000, v52
	v_div_scale_f32 v4, s[4:5], v3, v3, v2
	v_rcp_f32_e32 v5, v4
	s_nop 0
	v_fma_f32 v6, -v4, v5, 1.0
	v_fmac_f32_e32 v5, v6, v5
	v_div_scale_f32 v7, vcc, v2, v3, v2
	v_mul_f32_e32 v8, v7, v5
	v_fma_f32 v6, -v4, v8, v7
	v_fmac_f32_e32 v8, v6, v5
	v_fma_f32 v4, -v4, v8, v7
	v_div_fmas_f32 v4, v4, v5, v8
	v_div_fixup_f32 v11, v4, v3, v2
	v_lshlrev_b32_e32 v2, 16, v39
	v_lshlrev_b32_e32 v3, 16, v53
	v_div_scale_f32 v4, s[4:5], v3, v3, v2
	v_rcp_f32_e32 v5, v4
	s_nop 0
	v_fma_f32 v6, -v4, v5, 1.0
	v_fmac_f32_e32 v5, v6, v5
	v_div_scale_f32 v7, vcc, v2, v3, v2
	v_mul_f32_e32 v8, v7, v5
	v_fma_f32 v6, -v4, v8, v7
	v_fmac_f32_e32 v8, v6, v5
	v_fma_f32 v4, -v4, v8, v7
	v_div_fmas_f32 v4, v4, v5, v8
	v_div_fixup_f32 v12, v4, v3, v2
	v_and_b32_e32 v2, 0xffff0000, v39
	v_and_b32_e32 v3, 0xffff0000, v53
	v_div_scale_f32 v4, s[4:5], v3, v3, v2
	v_rcp_f32_e32 v5, v4
	s_nop 0
	v_fma_f32 v6, -v4, v5, 1.0
	v_fmac_f32_e32 v5, v6, v5
	v_div_scale_f32 v7, vcc, v2, v3, v2
	v_mul_f32_e32 v8, v7, v5
	v_fma_f32 v6, -v4, v8, v7
	v_fmac_f32_e32 v8, v6, v5
	v_fma_f32 v4, -v4, v8, v7
	v_div_fmas_f32 v4, v4, v5, v8
	v_div_fixup_f32 v13, v4, v3, v2
	v_lshlrev_b32_e32 v2, 16, v40
	v_lshlrev_b32_e32 v3, 16, v54
	v_div_scale_f32 v4, s[4:5], v3, v3, v2
	v_rcp_f32_e32 v5, v4
	s_nop 0
	v_fma_f32 v6, -v4, v5, 1.0
	v_fmac_f32_e32 v5, v6, v5
	v_div_scale_f32 v7, vcc, v2, v3, v2
	v_mul_f32_e32 v8, v7, v5
	v_fma_f32 v6, -v4, v8, v7
	v_fmac_f32_e32 v8, v6, v5
	v_fma_f32 v4, -v4, v8, v7
	v_div_fmas_f32 v4, v4, v5, v8
	v_div_fixup_f32 v14, v4, v3, v2
	v_and_b32_e32 v2, 0xffff0000, v40
	v_and_b32_e32 v3, 0xffff0000, v54
	v_div_scale_f32 v4, s[4:5], v3, v3, v2
	v_rcp_f32_e32 v5, v4
	s_nop 0
	v_fma_f32 v6, -v4, v5, 1.0
	v_fmac_f32_e32 v5, v6, v5
	v_div_scale_f32 v7, vcc, v2, v3, v2
	v_mul_f32_e32 v8, v7, v5
	v_fma_f32 v6, -v4, v8, v7
	v_fmac_f32_e32 v8, v6, v5
	v_fma_f32 v4, -v4, v8, v7
	v_div_fmas_f32 v4, v4, v5, v8
	v_div_fixup_f32 v15, v4, v3, v2
	v_lshlrev_b32_e32 v2, 16, v41
	v_lshlrev_b32_e32 v3, 16, v55
	v_div_scale_f32 v4, s[4:5], v3, v3, v2
	v_rcp_f32_e32 v5, v4
	s_nop 0
	v_fma_f32 v6, -v4, v5, 1.0
	v_fmac_f32_e32 v5, v6, v5
	v_div_scale_f32 v7, vcc, v2, v3, v2
	v_mul_f32_e32 v8, v7, v5
	v_fma_f32 v6, -v4, v8, v7
	v_fmac_f32_e32 v8, v6, v5
	v_fma_f32 v4, -v4, v8, v7
	v_div_fmas_f32 v4, v4, v5, v8
	v_div_fixup_f32 v16, v4, v3, v2
	v_and_b32_e32 v2, 0xffff0000, v41
	v_and_b32_e32 v3, 0xffff0000, v55
	v_div_scale_f32 v4, s[4:5], v3, v3, v2
	v_rcp_f32_e32 v5, v4
	s_nop 0
	v_fma_f32 v6, -v4, v5, 1.0
	v_fmac_f32_e32 v5, v6, v5
	v_div_scale_f32 v7, vcc, v2, v3, v2
	v_mul_f32_e32 v8, v7, v5
	v_fma_f32 v6, -v4, v8, v7
	v_fmac_f32_e32 v8, v6, v5
	v_fma_f32 v4, -v4, v8, v7
	v_div_fmas_f32 v4, v4, v5, v8
	v_div_fixup_f32 v17, v4, v3, v2
	s_waitcnt lgkmcnt(0)
	v_pk_mul_f32 v[42:43], v[42:43], v[10:11]
	v_pk_mul_f32 v[44:45], v[44:45], v[12:13]
	v_pk_mul_f32 v[46:47], v[46:47], v[14:15]
	v_pk_mul_f32 v[48:49], v[48:49], v[16:17]
	ds_write_b128 v50, v[42:45] offset:59168
	ds_write_b128 v50, v[46:49] offset:59184

.Lk_aol0b_loop:
	s_barrier
	s_add_u32 m0, s4, 32768
	v_mfma_f32_16x16x32_bf16 v[26:29], v[116:119], v[152:155], v[26:29]
	ds_read_b128 v[34:37], v100 offset:32
	global_load_lds_dwordx4 v170, s[12:13] offset:0
	v_mfma_f32_16x16x32_bf16 v[90:93], v[116:119], v[156:159], v[90:93]
	ds_read_b128 v[50:53], v168 offset:32
	global_load_lds_dwordx4 v171, s[12:13] offset:1024
	v_mfma_f32_16x16x32_bf16 v[22:25], v[116:119], v[160:163], v[22:25]
	ds_read_b128 v[54:57], v168 offset:2080
	global_load_lds_dwordx4 v172, s[12:13] offset:2048
	v_mfma_f32_16x16x32_bf16 v[86:89], v[116:119], v[164:167], v[86:89]
	ds_read_b128 v[38:41], v100 offset:2080
	global_load_lds_dwordx4 v173, s[12:13] offset:3072
	s_add_u32 m0, s4, 49152
	v_mfma_f32_16x16x32_bf16 v[18:21], v[120:123], v[152:155], v[18:21]
	ds_read_b128 v[58:61], v168 offset:4128
	global_load_lds_dwordx4 v170, s[46:47] offset:0
	v_mfma_f32_16x16x32_bf16 v[82:85], v[120:123], v[156:159], v[82:85]
	ds_read_b128 v[62:65], v168 offset:6176
	global_load_lds_dwordx4 v171, s[46:47] offset:1024
	v_mfma_f32_16x16x32_bf16 v[14:17], v[120:123], v[160:163], v[14:17]
	ds_read_b128 v[42:45], v100 offset:4128
	global_load_lds_dwordx4 v172, s[46:47] offset:2048
	v_mfma_f32_16x16x32_bf16 v[78:81], v[120:123], v[164:167], v[78:81]
	ds_read_b128 v[46:49], v100 offset:6176
	global_load_lds_dwordx4 v173, s[46:47] offset:3072
	v_mfma_f32_16x16x32_bf16 v[10:13], v[124:127], v[152:155], v[10:13]
	v_mfma_f32_16x16x32_bf16 v[74:77], v[124:127], v[156:159], v[74:77]
	v_mfma_f32_16x16x32_bf16 v[6:9], v[124:127], v[160:163], v[6:9]
	v_mfma_f32_16x16x32_bf16 v[70:73], v[124:127], v[164:167], v[70:73]
	v_mfma_f32_16x16x32_bf16 v[2:5], v[148:151], v[152:155], v[2:5]
	v_mfma_f32_16x16x32_bf16 v[66:69], v[148:151], v[156:159], v[66:69]
	v_mfma_f32_16x16x32_bf16 v[30:33], v[148:151], v[160:163], v[30:33]
	v_mfma_f32_16x16x32_bf16 v[94:97], v[148:151], v[164:167], v[94:97]
	s_add_u32 s98, s98, 1
	s_and_b32 s98, s98, 15
	s_cmp_eq_u32 s98, 0
	s_cselect_b32 s99, 0x800, 0
	s_add_u32 s12, s12, 0x80
	s_addc_u32 s13, s13, 0
	s_sub_u32 s12, s12, s99
	s_subb_u32 s13, s13, 0
	s_add_u32 s46, s46, 0x80
	s_addc_u32 s47, s47, 0
	s_sub_u32 s46, s46, s99
	s_subb_u32 s47, s47, 0
	s_waitcnt lgkmcnt(0)
	v_mfma_f32_16x16x32_bf16 v[26:29], v[34:37], v[50:53], v[26:29]
	ds_read_b128 v[116:119], v111 offset:32
	v_mfma_f32_16x16x32_bf16 v[90:93], v[34:37], v[54:57], v[90:93]
	ds_read_b128 v[152:155], v169 offset:32
	v_mfma_f32_16x16x32_bf16 v[22:25], v[34:37], v[58:61], v[22:25]
	ds_read_b128 v[156:159], v169 offset:2080
	v_mfma_f32_16x16x32_bf16 v[86:89], v[34:37], v[62:65], v[86:89]
	ds_read_b128 v[120:123], v111 offset:2080
	v_mfma_f32_16x16x32_bf16 v[18:21], v[38:41], v[50:53], v[18:21]
	ds_read_b128 v[160:163], v169 offset:4128
	v_mfma_f32_16x16x32_bf16 v[82:85], v[38:41], v[54:57], v[82:85]
	ds_read_b128 v[164:167], v169 offset:6176
	v_mfma_f32_16x16x32_bf16 v[14:17], v[38:41], v[58:61], v[14:17]
	ds_read_b128 v[124:127], v111 offset:4128
	v_mfma_f32_16x16x32_bf16 v[78:81], v[38:41], v[62:65], v[78:81]
	ds_read_b128 v[148:151], v111 offset:6176
	v_mfma_f32_16x16x32_bf16 v[10:13], v[42:45], v[50:53], v[10:13]
	v_mfma_f32_16x16x32_bf16 v[74:77], v[42:45], v[54:57], v[74:77]
	v_mfma_f32_16x16x32_bf16 v[6:9], v[42:45], v[58:61], v[6:9]
	v_mfma_f32_16x16x32_bf16 v[70:73], v[42:45], v[62:65], v[70:73]
	v_mfma_f32_16x16x32_bf16 v[2:5], v[46:49], v[50:53], v[2:5]
	v_mfma_f32_16x16x32_bf16 v[66:69], v[46:49], v[54:57], v[66:69]
	v_mfma_f32_16x16x32_bf16 v[30:33], v[46:49], v[58:61], v[30:33]
	v_mfma_f32_16x16x32_bf16 v[94:97], v[46:49], v[62:65], v[94:97]
	s_waitcnt lgkmcnt(0)
	s_waitcnt vmcnt(0)
	s_barrier
	s_add_u32 m0, s4, 0
	v_mfma_f32_16x16x32_bf16 v[26:29], v[116:119], v[152:155], v[26:29]
	ds_read_b128 v[34:37], v100 offset:32800
	global_load_lds_dwordx4 v170, s[12:13] offset:0
	v_mfma_f32_16x16x32_bf16 v[90:93], v[116:119], v[156:159], v[90:93]
	ds_read_b128 v[50:53], v168 offset:32800
	global_load_lds_dwordx4 v171, s[12:13] offset:1024
	v_mfma_f32_16x16x32_bf16 v[22:25], v[116:119], v[160:163], v[22:25]
	ds_read_b128 v[54:57], v168 offset:34848
	global_load_lds_dwordx4 v172, s[12:13] offset:2048
	v_mfma_f32_16x16x32_bf16 v[86:89], v[116:119], v[164:167], v[86:89]
	ds_read_b128 v[38:41], v100 offset:34848
	global_load_lds_dwordx4 v173, s[12:13] offset:3072
	s_add_u32 m0, s4, 16384
	v_mfma_f32_16x16x32_bf16 v[18:21], v[120:123], v[152:155], v[18:21]
	ds_read_b128 v[58:61], v168 offset:36896
	global_load_lds_dwordx4 v170, s[46:47] offset:0
	v_mfma_f32_16x16x32_bf16 v[82:85], v[120:123], v[156:159], v[82:85]
	ds_read_b128 v[62:65], v168 offset:38944
	global_load_lds_dwordx4 v171, s[46:47] offset:1024
	v_mfma_f32_16x16x32_bf16 v[14:17], v[120:123], v[160:163], v[14:17]
	ds_read_b128 v[42:45], v100 offset:36896
	global_load_lds_dwordx4 v172, s[46:47] offset:2048
	v_mfma_f32_16x16x32_bf16 v[78:81], v[120:123], v[164:167], v[78:81]
	ds_read_b128 v[46:49], v100 offset:38944
	global_load_lds_dwordx4 v173, s[46:47] offset:3072
	v_mfma_f32_16x16x32_bf16 v[10:13], v[124:127], v[152:155], v[10:13]
	v_mfma_f32_16x16x32_bf16 v[74:77], v[124:127], v[156:159], v[74:77]
	v_mfma_f32_16x16x32_bf16 v[6:9], v[124:127], v[160:163], v[6:9]
	v_mfma_f32_16x16x32_bf16 v[70:73], v[124:127], v[164:167], v[70:73]
	v_mfma_f32_16x16x32_bf16 v[2:5], v[148:151], v[152:155], v[2:5]
	v_mfma_f32_16x16x32_bf16 v[66:69], v[148:151], v[156:159], v[66:69]
	v_mfma_f32_16x16x32_bf16 v[30:33], v[148:151], v[160:163], v[30:33]
	v_mfma_f32_16x16x32_bf16 v[94:97], v[148:151], v[164:167], v[94:97]
	s_add_u32 s98, s98, 1
	s_and_b32 s98, s98, 15
	s_cmp_eq_u32 s98, 0
	s_cselect_b32 s99, 0x800, 0
	s_add_u32 s12, s12, 0x80
	s_addc_u32 s13, s13, 0
	s_sub_u32 s12, s12, s99
	s_subb_u32 s13, s13, 0
	s_add_u32 s46, s46, 0x80
	s_addc_u32 s47, s47, 0
	s_sub_u32 s46, s46, s99
	s_subb_u32 s47, s47, 0
	s_waitcnt lgkmcnt(0)
	v_mfma_f32_16x16x32_bf16 v[26:29], v[34:37], v[50:53], v[26:29]
	ds_read_b128 v[116:119], v111 offset:32800
	v_mfma_f32_16x16x32_bf16 v[90:93], v[34:37], v[54:57], v[90:93]
	ds_read_b128 v[152:155], v169 offset:32800
	v_mfma_f32_16x16x32_bf16 v[22:25], v[34:37], v[58:61], v[22:25]
	ds_read_b128 v[156:159], v169 offset:34848
	v_mfma_f32_16x16x32_bf16 v[86:89], v[34:37], v[62:65], v[86:89]
	ds_read_b128 v[120:123], v111 offset:34848
	v_mfma_f32_16x16x32_bf16 v[18:21], v[38:41], v[50:53], v[18:21]
	ds_read_b128 v[160:163], v169 offset:36896
	v_mfma_f32_16x16x32_bf16 v[82:85], v[38:41], v[54:57], v[82:85]
	ds_read_b128 v[164:167], v169 offset:38944
	v_mfma_f32_16x16x32_bf16 v[14:17], v[38:41], v[58:61], v[14:17]
	ds_read_b128 v[124:127], v111 offset:36896
	v_mfma_f32_16x16x32_bf16 v[78:81], v[38:41], v[62:65], v[78:81]
	ds_read_b128 v[148:151], v111 offset:38944
	v_mfma_f32_16x16x32_bf16 v[10:13], v[42:45], v[50:53], v[10:13]
	v_mfma_f32_16x16x32_bf16 v[74:77], v[42:45], v[54:57], v[74:77]
	v_mfma_f32_16x16x32_bf16 v[6:9], v[42:45], v[58:61], v[6:9]
	v_mfma_f32_16x16x32_bf16 v[70:73], v[42:45], v[62:65], v[70:73]
	v_mfma_f32_16x16x32_bf16 v[2:5], v[46:49], v[50:53], v[2:5]
	v_mfma_f32_16x16x32_bf16 v[66:69], v[46:49], v[54:57], v[66:69]
	v_mfma_f32_16x16x32_bf16 v[30:33], v[46:49], v[58:61], v[30:33]
	v_mfma_f32_16x16x32_bf16 v[94:97], v[46:49], v[62:65], v[94:97]
	s_waitcnt lgkmcnt(0)
	s_waitcnt vmcnt(0)
	s_add_u32 s11, s11, 1
	s_cmp_lt_u32 s11, 7
	s_cbranch_scc1 .Lk_aol0b_loop
	s_barrier
	s_add_u32 m0, s4, 32768
	v_mfma_f32_16x16x32_bf16 v[26:29], v[116:119], v[152:155], v[26:29]
	ds_read_b128 v[34:37], v100 offset:32
	global_load_lds_dwordx4 v170, s[12:13] offset:0
	v_mfma_f32_16x16x32_bf16 v[90:93], v[116:119], v[156:159], v[90:93]
	ds_read_b128 v[50:53], v168 offset:32
	global_load_lds_dwordx4 v171, s[12:13] offset:1024
	v_mfma_f32_16x16x32_bf16 v[22:25], v[116:119], v[160:163], v[22:25]
	ds_read_b128 v[54:57], v168 offset:2080
	global_load_lds_dwordx4 v172, s[12:13] offset:2048
	v_mfma_f32_16x16x32_bf16 v[86:89], v[116:119], v[164:167], v[86:89]
	ds_read_b128 v[38:41], v100 offset:2080
	global_load_lds_dwordx4 v173, s[12:13] offset:3072
	s_add_u32 m0, s4, 49152
	v_mfma_f32_16x16x32_bf16 v[18:21], v[120:123], v[152:155], v[18:21]
	ds_read_b128 v[58:61], v168 offset:4128
	global_load_lds_dwordx4 v170, s[46:47] offset:0
	v_mfma_f32_16x16x32_bf16 v[82:85], v[120:123], v[156:159], v[82:85]
	ds_read_b128 v[62:65], v168 offset:6176
	global_load_lds_dwordx4 v171, s[46:47] offset:1024
	v_mfma_f32_16x16x32_bf16 v[14:17], v[120:123], v[160:163], v[14:17]
	ds_read_b128 v[42:45], v100 offset:4128
	global_load_lds_dwordx4 v172, s[46:47] offset:2048
	v_mfma_f32_16x16x32_bf16 v[78:81], v[120:123], v[164:167], v[78:81]
	ds_read_b128 v[46:49], v100 offset:6176
	global_load_lds_dwordx4 v173, s[46:47] offset:3072
	v_mfma_f32_16x16x32_bf16 v[10:13], v[124:127], v[152:155], v[10:13]
	v_mfma_f32_16x16x32_bf16 v[74:77], v[124:127], v[156:159], v[74:77]
	v_mfma_f32_16x16x32_bf16 v[6:9], v[124:127], v[160:163], v[6:9]
	v_mfma_f32_16x16x32_bf16 v[70:73], v[124:127], v[164:167], v[70:73]
	v_mfma_f32_16x16x32_bf16 v[2:5], v[148:151], v[152:155], v[2:5]
	v_mfma_f32_16x16x32_bf16 v[66:69], v[148:151], v[156:159], v[66:69]
	v_mfma_f32_16x16x32_bf16 v[30:33], v[148:151], v[160:163], v[30:33]
	v_mfma_f32_16x16x32_bf16 v[94:97], v[148:151], v[164:167], v[94:97]
	s_add_u32 s98, s98, 1
	s_and_b32 s98, s98, 15
	s_cmp_eq_u32 s98, 0
	s_cselect_b32 s99, 0x800, 0
	s_add_u32 s12, s12, 0x80
	s_addc_u32 s13, s13, 0
	s_sub_u32 s12, s12, s99
	s_subb_u32 s13, s13, 0
	s_add_u32 s46, s46, 0x80
	s_addc_u32 s47, s47, 0
	s_sub_u32 s46, s46, s99
	s_subb_u32 s47, s47, 0
	s_waitcnt lgkmcnt(0)
	v_mfma_f32_16x16x32_bf16 v[26:29], v[34:37], v[50:53], v[26:29]
	ds_read_b128 v[116:119], v111 offset:32
	v_mfma_f32_16x16x32_bf16 v[90:93], v[34:37], v[54:57], v[90:93]
	ds_read_b128 v[152:155], v169 offset:32
	v_mfma_f32_16x16x32_bf16 v[22:25], v[34:37], v[58:61], v[22:25]
	ds_read_b128 v[156:159], v169 offset:2080
	v_mfma_f32_16x16x32_bf16 v[86:89], v[34:37], v[62:65], v[86:89]
	ds_read_b128 v[120:123], v111 offset:2080
	v_mfma_f32_16x16x32_bf16 v[18:21], v[38:41], v[50:53], v[18:21]
	ds_read_b128 v[160:163], v169 offset:4128
	v_mfma_f32_16x16x32_bf16 v[82:85], v[38:41], v[54:57], v[82:85]
	ds_read_b128 v[164:167], v169 offset:6176
	v_mfma_f32_16x16x32_bf16 v[14:17], v[38:41], v[58:61], v[14:17]
	ds_read_b128 v[124:127], v111 offset:4128
	v_mfma_f32_16x16x32_bf16 v[78:81], v[38:41], v[62:65], v[78:81]
	ds_read_b128 v[148:151], v111 offset:6176
	v_mfma_f32_16x16x32_bf16 v[10:13], v[42:45], v[50:53], v[10:13]
	v_mfma_f32_16x16x32_bf16 v[74:77], v[42:45], v[54:57], v[74:77]
	v_mfma_f32_16x16x32_bf16 v[6:9], v[42:45], v[58:61], v[6:9]
	v_mfma_f32_16x16x32_bf16 v[70:73], v[42:45], v[62:65], v[70:73]
	v_mfma_f32_16x16x32_bf16 v[2:5], v[46:49], v[50:53], v[2:5]
	v_mfma_f32_16x16x32_bf16 v[66:69], v[46:49], v[54:57], v[66:69]
	v_mfma_f32_16x16x32_bf16 v[30:33], v[46:49], v[58:61], v[30:33]
	v_mfma_f32_16x16x32_bf16 v[94:97], v[46:49], v[62:65], v[94:97]
	s_waitcnt lgkmcnt(0)
	s_waitcnt vmcnt(0)
	s_barrier
	v_mfma_f32_16x16x32_bf16 v[26:29], v[116:119], v[152:155], v[26:29]
	ds_read_b128 v[34:37], v100 offset:32800
	v_mfma_f32_16x16x32_bf16 v[90:93], v[116:119], v[156:159], v[90:93]
	ds_read_b128 v[50:53], v168 offset:32800
	v_mfma_f32_16x16x32_bf16 v[22:25], v[116:119], v[160:163], v[22:25]
	ds_read_b128 v[54:57], v168 offset:34848
	v_mfma_f32_16x16x32_bf16 v[86:89], v[116:119], v[164:167], v[86:89]
	ds_read_b128 v[38:41], v100 offset:34848
	v_mfma_f32_16x16x32_bf16 v[18:21], v[120:123], v[152:155], v[18:21]
	ds_read_b128 v[58:61], v168 offset:36896
	v_mfma_f32_16x16x32_bf16 v[82:85], v[120:123], v[156:159], v[82:85]
	ds_read_b128 v[62:65], v168 offset:38944
	v_mfma_f32_16x16x32_bf16 v[14:17], v[120:123], v[160:163], v[14:17]
	ds_read_b128 v[42:45], v100 offset:36896
	v_mfma_f32_16x16x32_bf16 v[78:81], v[120:123], v[164:167], v[78:81]
	ds_read_b128 v[46:49], v100 offset:38944
	v_mfma_f32_16x16x32_bf16 v[10:13], v[124:127], v[152:155], v[10:13]
	v_mfma_f32_16x16x32_bf16 v[74:77], v[124:127], v[156:159], v[74:77]
	v_mfma_f32_16x16x32_bf16 v[6:9], v[124:127], v[160:163], v[6:9]
	v_mfma_f32_16x16x32_bf16 v[70:73], v[124:127], v[164:167], v[70:73]
	v_mfma_f32_16x16x32_bf16 v[2:5], v[148:151], v[152:155], v[2:5]
	v_mfma_f32_16x16x32_bf16 v[66:69], v[148:151], v[156:159], v[66:69]
	v_mfma_f32_16x16x32_bf16 v[30:33], v[148:151], v[160:163], v[30:33]
	v_mfma_f32_16x16x32_bf16 v[94:97], v[148:151], v[164:167], v[94:97]
	s_waitcnt lgkmcnt(0)
	v_mfma_f32_16x16x32_bf16 v[26:29], v[34:37], v[50:53], v[26:29]
	ds_read_b128 v[116:119], v111 offset:32800
	v_mfma_f32_16x16x32_bf16 v[90:93], v[34:37], v[54:57], v[90:93]
	ds_read_b128 v[152:155], v169 offset:32800
	v_mfma_f32_16x16x32_bf16 v[22:25], v[34:37], v[58:61], v[22:25]
	ds_read_b128 v[156:159], v169 offset:34848
	v_mfma_f32_16x16x32_bf16 v[86:89], v[34:37], v[62:65], v[86:89]
	ds_read_b128 v[120:123], v111 offset:34848
	v_mfma_f32_16x16x32_bf16 v[18:21], v[38:41], v[50:53], v[18:21]
	ds_read_b128 v[160:163], v169 offset:36896
	v_mfma_f32_16x16x32_bf16 v[82:85], v[38:41], v[54:57], v[82:85]
	ds_read_b128 v[164:167], v169 offset:38944
	v_mfma_f32_16x16x32_bf16 v[14:17], v[38:41], v[58:61], v[14:17]
	ds_read_b128 v[124:127], v111 offset:36896
	v_mfma_f32_16x16x32_bf16 v[78:81], v[38:41], v[62:65], v[78:81]
	ds_read_b128 v[148:151], v111 offset:38944
	v_mfma_f32_16x16x32_bf16 v[10:13], v[42:45], v[50:53], v[10:13]
	v_mfma_f32_16x16x32_bf16 v[74:77], v[42:45], v[54:57], v[74:77]
	v_mfma_f32_16x16x32_bf16 v[6:9], v[42:45], v[58:61], v[6:9]
	v_mfma_f32_16x16x32_bf16 v[70:73], v[42:45], v[62:65], v[70:73]
	v_mfma_f32_16x16x32_bf16 v[2:5], v[46:49], v[50:53], v[2:5]
	v_mfma_f32_16x16x32_bf16 v[66:69], v[46:49], v[54:57], v[66:69]
	v_mfma_f32_16x16x32_bf16 v[30:33], v[46:49], v[58:61], v[30:33]
	v_mfma_f32_16x16x32_bf16 v[94:97], v[46:49], v[62:65], v[94:97]
	s_waitcnt lgkmcnt(0)
	v_mfma_f32_16x16x32_bf16 v[26:29], v[116:119], v[152:155], v[26:29]
	v_mfma_f32_16x16x32_bf16 v[90:93], v[116:119], v[156:159], v[90:93]
	v_mfma_f32_16x16x32_bf16 v[22:25], v[116:119], v[160:163], v[22:25]
	v_mfma_f32_16x16x32_bf16 v[86:89], v[116:119], v[164:167], v[86:89]
	v_mfma_f32_16x16x32_bf16 v[18:21], v[120:123], v[152:155], v[18:21]
	v_mfma_f32_16x16x32_bf16 v[82:85], v[120:123], v[156:159], v[82:85]
	v_mfma_f32_16x16x32_bf16 v[14:17], v[120:123], v[160:163], v[14:17]
	v_mfma_f32_16x16x32_bf16 v[78:81], v[120:123], v[164:167], v[78:81]
	v_mfma_f32_16x16x32_bf16 v[10:13], v[124:127], v[152:155], v[10:13]
	v_mfma_f32_16x16x32_bf16 v[74:77], v[124:127], v[156:159], v[74:77]
	v_mfma_f32_16x16x32_bf16 v[6:9], v[124:127], v[160:163], v[6:9]
	v_mfma_f32_16x16x32_bf16 v[70:73], v[124:127], v[164:167], v[70:73]
	v_mfma_f32_16x16x32_bf16 v[2:5], v[148:151], v[152:155], v[2:5]
	v_mfma_f32_16x16x32_bf16 v[66:69], v[148:151], v[156:159], v[66:69]
	v_mfma_f32_16x16x32_bf16 v[30:33], v[148:151], v[160:163], v[30:33]
	v_mfma_f32_16x16x32_bf16 v[94:97], v[148:151], v[164:167], v[94:97]
	s_lshr_b32 s101, s10, 7
	v_lshrrev_b32_e32 v117, 4, v0
	v_and_b32_e32 v117, 15, v117
	v_and_b32_e32 v118, 15, v0
	v_lshlrev_b32_e32 v118, 4, v118
	v_lshl_or_b32 v117, v117, 12, v118
	s_lshl_b32 s100, s48, 12
	s_lshl_b32 s98, s101, 8
	s_add_u32 s100, s100, s98
	s_add_u32 s98, s42, s100
	s_addc_u32 s99, s43, 0
	s_add_u32 s98, s98, 0x12d24800
	s_addc_u32 s99, s99, 0
	global_load_dwordx4 v[148:151], v117, s[98:99]
	s_add_u32 s98, s98, 0x10000
	s_addc_u32 s99, s99, 0
	global_load_dwordx4 v[152:155], v117, s[98:99]
	s_add_u32 s98, s98, 0x10000
	s_addc_u32 s99, s99, 0
	global_load_dwordx4 v[156:159], v117, s[98:99]
	s_add_u32 s98, s98, 0x10000
	s_addc_u32 s99, s99, 0
	global_load_dwordx4 v[160:163], v117, s[98:99]
	s_add_u32 s98, s98, 0x10000
	s_addc_u32 s99, s99, 0
	global_load_dwordx4 v[164:167], v117, s[98:99]
	s_add_u32 s98, s98, 0x10000
	s_addc_u32 s99, s99, 0
	global_load_dwordx4 v[168:171], v117, s[98:99]
	s_add_u32 s98, s98, 0x10000
	s_addc_u32 s99, s99, 0
	global_load_dwordx4 v[172:175], v117, s[98:99]
	s_add_u32 s98, s98, 0x10000
	s_addc_u32 s99, s99, 0
	global_load_dwordx4 v[188:191], v117, s[98:99]
	s_lshl_b32 s4, s10, 1
	s_barrier
	ds_write2_b32 v129, v26, v90 offset1:16
	ds_write2_b32 v129, v27, v91 offset0:132 offset1:148
	ds_write2_b32 v138, v28, v92 offset0:8 offset1:24
	ds_write2_b32 v138, v29, v93 offset0:140 offset1:156
	ds_write2_b32 v129, v22, v86 offset0:32 offset1:48
	ds_write2_b32 v129, v23, v87 offset0:164 offset1:180
	ds_write2_b32 v138, v24, v88 offset0:40 offset1:56
	ds_write2_b32 v138, v25, v89 offset0:172 offset1:188
	ds_write2_b32 v139, v18, v82 offset0:64 offset1:80
	ds_write2_b32 v139, v19, v83 offset0:196 offset1:212
	ds_write2_b32 v140, v20, v84 offset0:72 offset1:88
	ds_write2_b32 v140, v21, v85 offset0:204 offset1:220
	ds_write2_b32 v139, v14, v78 offset0:96 offset1:112
	ds_write2_b32 v139, v15, v79 offset0:228 offset1:244
	ds_write2_b32 v140, v16, v80 offset0:104 offset1:120
	ds_write2_b32 v140, v17, v81 offset0:236 offset1:252
	ds_write2_b32 v141, v10, v74 offset0:128 offset1:144
	ds_write2_b32 v142, v11, v75 offset0:4 offset1:20
	ds_write2_b32 v142, v12, v76 offset0:136 offset1:152
	ds_write2_b32 v143, v13, v77 offset0:12 offset1:28
	ds_write2_b32 v141, v6, v70 offset0:160 offset1:176
	ds_write2_b32 v142, v7, v71 offset0:36 offset1:52
	ds_write2_b32 v142, v8, v72 offset0:168 offset1:184
	ds_write2_b32 v143, v9, v73 offset0:44 offset1:60
	ds_write2_b32 v144, v2, v66 offset0:192 offset1:208
	ds_write2_b32 v145, v3, v67 offset0:68 offset1:84
	ds_write2_b32 v145, v4, v68 offset0:200 offset1:216
	ds_write2_b32 v146, v5, v69 offset0:76 offset1:92
	ds_write2_b32 v144, v30, v94 offset0:224 offset1:240
	ds_write2_b32 v145, v31, v95 offset0:100 offset1:116
	ds_write2_b32 v145, v32, v96 offset0:232 offset1:248
	ds_write2_b32 v146, v33, v97 offset0:108 offset1:124
	v_lshl_add_u64 v[2:3], v[106:107], 0, s[4:5]
	s_lshl_b32 s4, s34, 10
	s_mul_hi_u32 s10, s34, 0x15555556
	v_or_b32_e32 v4, s4, v134
	s_mulk_i32 s10, 0x3000
	v_or_b32_e32 v5, s4, v132
	v_subrev_u32_e32 v4, s10, v4
	v_subrev_u32_e32 v100, s10, v5
	s_mov_b32 s4, 0
	s_waitcnt lgkmcnt(0)
	s_barrier
	v_lshrrev_b32_e32 v52, 4, v0
	v_and_b32_e32 v52, 15, v52
	v_and_b32_e32 v50, 15, v0
	v_lshlrev_b32_e32 v53, 4, v50
	v_lshl_or_b32 v53, v52, 11, v53
	v_mul_u32_u24_e32 v52, 0x210, v52
	v_lshl_add_u32 v52, v50, 5, v52
	s_lshl_b32 s100, s48, 11
	s_lshl_b32 s98, s101, 8
	s_add_u32 s100, s100, s98
	s_add_u32 s98, s42, s100
	s_addc_u32 s99, s43, 0
	s_add_u32 s98, s98, 0xb724000
	s_addc_u32 s99, s99, 0
	ds_read_b128 v[34:37], v52 offset:32
	ds_read_b128 v[38:41], v52 offset:48
	ds_read_b128 v[42:45], v52 offset:8480
	ds_read_b128 v[46:49], v52 offset:8496
	s_waitcnt vmcnt(7) lgkmcnt(2)
	v_lshlrev_b32_e32 v51, 16, v148
	v_mul_f32_e32 v34, v34, v51
	v_and_b32_e32 v51, 0xffff0000, v148
	v_mul_f32_e32 v35, v35, v51
	v_lshlrev_b32_e32 v51, 16, v149
	v_mul_f32_e32 v36, v36, v51
	v_and_b32_e32 v51, 0xffff0000, v149
	v_mul_f32_e32 v37, v37, v51
	v_lshlrev_b32_e32 v51, 16, v150
	v_mul_f32_e32 v38, v38, v51
	v_and_b32_e32 v51, 0xffff0000, v150
	v_mul_f32_e32 v39, v39, v51
	v_lshlrev_b32_e32 v51, 16, v151
	v_mul_f32_e32 v40, v40, v51
	v_and_b32_e32 v51, 0xffff0000, v151
	v_mul_f32_e32 v41, v41, v51
	v_cvt_pk_bf16_f32 v34, v34, v35
	v_cvt_pk_bf16_f32 v35, v36, v37
	v_cvt_pk_bf16_f32 v36, v38, v39
	v_cvt_pk_bf16_f32 v37, v40, v41
	global_store_dwordx4 v53, v[34:37], s[98:99]
	s_add_u32 s98, s98, 0x8000
	s_addc_u32 s99, s99, 0
	s_nop 1
	ds_read_b128 v[34:37], v52 offset:16928
	ds_read_b128 v[38:41], v52 offset:16944
	s_waitcnt vmcnt(7) lgkmcnt(2)
	v_lshlrev_b32_e32 v51, 16, v152
	v_mul_f32_e32 v42, v42, v51
	v_and_b32_e32 v51, 0xffff0000, v152
	v_mul_f32_e32 v43, v43, v51
	v_lshlrev_b32_e32 v51, 16, v153
	v_mul_f32_e32 v44, v44, v51
	v_and_b32_e32 v51, 0xffff0000, v153
	v_mul_f32_e32 v45, v45, v51
	v_lshlrev_b32_e32 v51, 16, v154
	v_mul_f32_e32 v46, v46, v51
	v_and_b32_e32 v51, 0xffff0000, v154
	v_mul_f32_e32 v47, v47, v51
	v_lshlrev_b32_e32 v51, 16, v155
	v_mul_f32_e32 v48, v48, v51
	v_and_b32_e32 v51, 0xffff0000, v155
	v_mul_f32_e32 v49, v49, v51
	v_cvt_pk_bf16_f32 v42, v42, v43
	v_cvt_pk_bf16_f32 v43, v44, v45
	v_cvt_pk_bf16_f32 v44, v46, v47
	v_cvt_pk_bf16_f32 v45, v48, v49
	global_store_dwordx4 v53, v[42:45], s[98:99]
	s_add_u32 s98, s98, 0x8000
	s_addc_u32 s99, s99, 0
	s_nop 1
	ds_read_b128 v[42:45], v52 offset:25376
	ds_read_b128 v[46:49], v52 offset:25392
	s_waitcnt vmcnt(7) lgkmcnt(2)
	v_lshlrev_b32_e32 v51, 16, v156
	v_mul_f32_e32 v34, v34, v51
	v_and_b32_e32 v51, 0xffff0000, v156
	v_mul_f32_e32 v35, v35, v51
	v_lshlrev_b32_e32 v51, 16, v157
	v_mul_f32_e32 v36, v36, v51
	v_and_b32_e32 v51, 0xffff0000, v157
	v_mul_f32_e32 v37, v37, v51
	v_lshlrev_b32_e32 v51, 16, v158
	v_mul_f32_e32 v38, v38, v51
	v_and_b32_e32 v51, 0xffff0000, v158
	v_mul_f32_e32 v39, v39, v51
	v_lshlrev_b32_e32 v51, 16, v159
	v_mul_f32_e32 v40, v40, v51
	v_and_b32_e32 v51, 0xffff0000, v159
	v_mul_f32_e32 v41, v41, v51
	v_cvt_pk_bf16_f32 v34, v34, v35
	v_cvt_pk_bf16_f32 v35, v36, v37
	v_cvt_pk_bf16_f32 v36, v38, v39
	v_cvt_pk_bf16_f32 v37, v40, v41
	global_store_dwordx4 v53, v[34:37], s[98:99]
	s_add_u32 s98, s98, 0x8000
	s_addc_u32 s99, s99, 0
	s_nop 1
	ds_read_b128 v[34:37], v52 offset:33824
	ds_read_b128 v[38:41], v52 offset:33840
	s_waitcnt vmcnt(7) lgkmcnt(2)
	v_lshlrev_b32_e32 v51, 16, v160
	v_mul_f32_e32 v42, v42, v51
	v_and_b32_e32 v51, 0xffff0000, v160
	v_mul_f32_e32 v43, v43, v51
	v_lshlrev_b32_e32 v51, 16, v161
	v_mul_f32_e32 v44, v44, v51
	v_and_b32_e32 v51, 0xffff0000, v161
	v_mul_f32_e32 v45, v45, v51
	v_lshlrev_b32_e32 v51, 16, v162
	v_mul_f32_e32 v46, v46, v51
	v_and_b32_e32 v51, 0xffff0000, v162
	v_mul_f32_e32 v47, v47, v51
	v_lshlrev_b32_e32 v51, 16, v163
	v_mul_f32_e32 v48, v48, v51
	v_and_b32_e32 v51, 0xffff0000, v163
	v_mul_f32_e32 v49, v49, v51
	v_cvt_pk_bf16_f32 v42, v42, v43
	v_cvt_pk_bf16_f32 v43, v44, v45
	v_cvt_pk_bf16_f32 v44, v46, v47
	v_cvt_pk_bf16_f32 v45, v48, v49
	global_store_dwordx4 v53, v[42:45], s[98:99]
	s_add_u32 s98, s98, 0x8000
	s_addc_u32 s99, s99, 0
	s_nop 1
	ds_read_b128 v[42:45], v52 offset:42272
	ds_read_b128 v[46:49], v52 offset:42288
	s_waitcnt vmcnt(7) lgkmcnt(2)
	v_lshlrev_b32_e32 v51, 16, v164
	v_mul_f32_e32 v34, v34, v51
	v_and_b32_e32 v51, 0xffff0000, v164
	v_mul_f32_e32 v35, v35, v51
	v_lshlrev_b32_e32 v51, 16, v165
	v_mul_f32_e32 v36, v36, v51
	v_and_b32_e32 v51, 0xffff0000, v165
	v_mul_f32_e32 v37, v37, v51
	v_lshlrev_b32_e32 v51, 16, v166
	v_mul_f32_e32 v38, v38, v51
	v_and_b32_e32 v51, 0xffff0000, v166
	v_mul_f32_e32 v39, v39, v51
	v_lshlrev_b32_e32 v51, 16, v167
	v_mul_f32_e32 v40, v40, v51
	v_and_b32_e32 v51, 0xffff0000, v167
	v_mul_f32_e32 v41, v41, v51
	v_cvt_pk_bf16_f32 v34, v34, v35
	v_cvt_pk_bf16_f32 v35, v36, v37
	v_cvt_pk_bf16_f32 v36, v38, v39
	v_cvt_pk_bf16_f32 v37, v40, v41
	global_store_dwordx4 v53, v[34:37], s[98:99]
	s_add_u32 s98, s98, 0x8000
	s_addc_u32 s99, s99, 0
	s_nop 1
	ds_read_b128 v[34:37], v52 offset:50720
	ds_read_b128 v[38:41], v52 offset:50736
	s_waitcnt vmcnt(7) lgkmcnt(2)
	v_lshlrev_b32_e32 v51, 16, v168
	v_mul_f32_e32 v42, v42, v51
	v_and_b32_e32 v51, 0xffff0000, v168
	v_mul_f32_e32 v43, v43, v51
	v_lshlrev_b32_e32 v51, 16, v169
	v_mul_f32_e32 v44, v44, v51
	v_and_b32_e32 v51, 0xffff0000, v169
	v_mul_f32_e32 v45, v45, v51
	v_lshlrev_b32_e32 v51, 16, v170
	v_mul_f32_e32 v46, v46, v51
	v_and_b32_e32 v51, 0xffff0000, v170
	v_mul_f32_e32 v47, v47, v51
	v_lshlrev_b32_e32 v51, 16, v171
	v_mul_f32_e32 v48, v48, v51
	v_and_b32_e32 v51, 0xffff0000, v171
	v_mul_f32_e32 v49, v49, v51
	v_cvt_pk_bf16_f32 v42, v42, v43
	v_cvt_pk_bf16_f32 v43, v44, v45
	v_cvt_pk_bf16_f32 v44, v46, v47
	v_cvt_pk_bf16_f32 v45, v48, v49
	global_store_dwordx4 v53, v[42:45], s[98:99]
	s_add_u32 s98, s98, 0x8000
	s_addc_u32 s99, s99, 0
	s_nop 1
	ds_read_b128 v[42:45], v52 offset:59168
	ds_read_b128 v[46:49], v52 offset:59184
	s_waitcnt vmcnt(7) lgkmcnt(2)
	v_lshlrev_b32_e32 v51, 16, v172
	v_mul_f32_e32 v34, v34, v51
	v_and_b32_e32 v51, 0xffff0000, v172
	v_mul_f32_e32 v35, v35, v51
	v_lshlrev_b32_e32 v51, 16, v173
	v_mul_f32_e32 v36, v36, v51
	v_and_b32_e32 v51, 0xffff0000, v173
	v_mul_f32_e32 v37, v37, v51
	v_lshlrev_b32_e32 v51, 16, v174
	v_mul_f32_e32 v38, v38, v51
	v_and_b32_e32 v51, 0xffff0000, v174
	v_mul_f32_e32 v39, v39, v51
	v_lshlrev_b32_e32 v51, 16, v175
	v_mul_f32_e32 v40, v40, v51
	v_and_b32_e32 v51, 0xffff0000, v175
	v_mul_f32_e32 v41, v41, v51
	v_cvt_pk_bf16_f32 v34, v34, v35
	v_cvt_pk_bf16_f32 v35, v36, v37
	v_cvt_pk_bf16_f32 v36, v38, v39
	v_cvt_pk_bf16_f32 v37, v40, v41
	global_store_dwordx4 v53, v[34:37], s[98:99]
	s_add_u32 s98, s98, 0x8000
	s_addc_u32 s99, s99, 0
	s_waitcnt vmcnt(7) lgkmcnt(0)
	v_lshlrev_b32_e32 v51, 16, v188
	v_mul_f32_e32 v42, v42, v51
	v_and_b32_e32 v51, 0xffff0000, v188
	v_mul_f32_e32 v43, v43, v51
	v_lshlrev_b32_e32 v51, 16, v189
	v_mul_f32_e32 v44, v44, v51
	v_and_b32_e32 v51, 0xffff0000, v189
	v_mul_f32_e32 v45, v45, v51
	v_lshlrev_b32_e32 v51, 16, v190
	v_mul_f32_e32 v46, v46, v51
	v_and_b32_e32 v51, 0xffff0000, v190
	v_mul_f32_e32 v47, v47, v51
	v_lshlrev_b32_e32 v51, 16, v191
	v_mul_f32_e32 v48, v48, v51
	v_and_b32_e32 v51, 0xffff0000, v191
	v_mul_f32_e32 v49, v49, v51
	v_cvt_pk_bf16_f32 v42, v42, v43
	v_cvt_pk_bf16_f32 v43, v44, v45
	v_cvt_pk_bf16_f32 v44, v46, v47
	v_cvt_pk_bf16_f32 v45, v48, v49
	global_store_dwordx4 v53, v[42:45], s[98:99]
	s_add_i32 s33, s33, s25
	s_add_i32 s31, s31, 1
	s_cmpk_gt_u32 s33, 0x5f
	s_cbranch_scc0 .LBB0_552
	s_load_dwordx16 s[48:63], s[0:1], 0x0

.Lcv_cv0_top:
	v_add_co_u32_e32 v96, vcc, 0x700, v2
	s_nop 1
	v_addc_co_u32_e32 v97, vcc, 0, v3, vcc
	v_cmp_gt_u64_e32 vcc, s[4:5], v[96:97]
	s_cmp_eq_u64 vcc, exec
	s_cbranch_scc0 .Lcv_cv0_exit
	v_lshlrev_b32_e32 v80, 5, v2
	v_lshlrev_b32_e32 v88, 3, v2
	v_add_u32_e32 v81, 0x2000, v80
	v_add_u32_e32 v89, 0x800, v88
	v_add_u32_e32 v82, 0x4000, v80
	v_add_u32_e32 v90, 0x1000, v88
	v_add_u32_e32 v83, 0x6000, v80
	v_add_u32_e32 v91, 0x1800, v88
	v_add_u32_e32 v84, 0x8000, v80
	v_add_u32_e32 v92, 0x2000, v88
	v_add_u32_e32 v85, 0xa000, v80
	v_add_u32_e32 v93, 0x2800, v88
	v_add_u32_e32 v86, 0xc000, v80
	v_add_u32_e32 v94, 0x3000, v88
	v_add_u32_e32 v87, 0xe000, v80
	v_add_u32_e32 v95, 0x3800, v88
	global_load_dwordx4 v[16:19], v80, s[36:37] nt
	global_load_dwordx4 v[20:23], v80, s[36:37] offset:16 nt
	global_load_dwordx4 v[24:27], v81, s[36:37] nt
	global_load_dwordx4 v[28:31], v81, s[36:37] offset:16 nt
	global_load_dwordx4 v[32:35], v82, s[36:37] nt
	global_load_dwordx4 v[36:39], v82, s[36:37] offset:16 nt
	global_load_dwordx4 v[40:43], v83, s[36:37] nt
	global_load_dwordx4 v[44:47], v83, s[36:37] offset:16 nt
	global_load_dwordx4 v[48:51], v84, s[36:37] nt
	global_load_dwordx4 v[52:55], v84, s[36:37] offset:16 nt
	global_load_dwordx4 v[56:59], v85, s[36:37] nt
	global_load_dwordx4 v[60:63], v85, s[36:37] offset:16 nt
	global_load_dwordx4 v[64:67], v86, s[36:37] nt
	global_load_dwordx4 v[68:71], v86, s[36:37] offset:16 nt
	global_load_dwordx4 v[72:75], v87, s[36:37] nt
	global_load_dwordx4 v[76:79], v87, s[36:37] offset:16 nt
	v_add_co_u32_e32 v2, vcc, 0x800, v2
	s_nop 1
	v_addc_co_u32_e32 v3, vcc, 0, v3, vcc
	s_waitcnt vmcnt(14)
	v_mul_f32_e32 v116, 0x43000000, v16
	v_mul_f32_e32 v117, 0x43000000, v17
	v_mul_f32_e32 v118, 0x43000000, v18
	v_mul_f32_e32 v119, 0x43000000, v19
	v_mul_f32_e32 v120, 0x43000000, v20
	v_mul_f32_e32 v121, 0x43000000, v21
	v_mul_f32_e32 v122, 0x43000000, v22
	v_mul_f32_e32 v123, 0x43000000, v23
	v_cvt_pk_fp8_f32 v100, v116, v117
	v_cvt_pk_fp8_f32 v101, v120, v121
	v_cvt_pk_fp8_f32 v100, v118, v119 op_sel:[0,0,1]
	v_cvt_pk_fp8_f32 v101, v122, v123 op_sel:[0,0,1]
	global_store_dwordx2 v88, v[100:101], s[8:9]
	s_waitcnt vmcnt(13)
	v_mul_f32_e32 v116, 0x43000000, v24
	v_mul_f32_e32 v117, 0x43000000, v25
	v_mul_f32_e32 v118, 0x43000000, v26
	v_mul_f32_e32 v119, 0x43000000, v27
	v_mul_f32_e32 v120, 0x43000000, v28
	v_mul_f32_e32 v121, 0x43000000, v29
	v_mul_f32_e32 v122, 0x43000000, v30
	v_mul_f32_e32 v123, 0x43000000, v31
	v_cvt_pk_fp8_f32 v102, v116, v117
	v_cvt_pk_fp8_f32 v103, v120, v121
	v_cvt_pk_fp8_f32 v102, v118, v119 op_sel:[0,0,1]
	v_cvt_pk_fp8_f32 v103, v122, v123 op_sel:[0,0,1]
	global_store_dwordx2 v89, v[102:103], s[8:9]
	s_waitcnt vmcnt(12)
	v_mul_f32_e32 v116, 0x43000000, v32
	v_mul_f32_e32 v117, 0x43000000, v33
	v_mul_f32_e32 v118, 0x43000000, v34
	v_mul_f32_e32 v119, 0x43000000, v35
	v_mul_f32_e32 v120, 0x43000000, v36
	v_mul_f32_e32 v121, 0x43000000, v37
	v_mul_f32_e32 v122, 0x43000000, v38
	v_mul_f32_e32 v123, 0x43000000, v39
	v_cvt_pk_fp8_f32 v104, v116, v117
	v_cvt_pk_fp8_f32 v105, v120, v121
	v_cvt_pk_fp8_f32 v104, v118, v119 op_sel:[0,0,1]
	v_cvt_pk_fp8_f32 v105, v122, v123 op_sel:[0,0,1]
	global_store_dwordx2 v90, v[104:105], s[8:9]
	s_waitcnt vmcnt(11)
	v_mul_f32_e32 v116, 0x43000000, v40
	v_mul_f32_e32 v117, 0x43000000, v41
	v_mul_f32_e32 v118, 0x43000000, v42
	v_mul_f32_e32 v119, 0x43000000, v43
	v_mul_f32_e32 v120, 0x43000000, v44
	v_mul_f32_e32 v121, 0x43000000, v45
	v_mul_f32_e32 v122, 0x43000000, v46
	v_mul_f32_e32 v123, 0x43000000, v47
	v_cvt_pk_fp8_f32 v106, v116, v117
	v_cvt_pk_fp8_f32 v107, v120, v121
	v_cvt_pk_fp8_f32 v106, v118, v119 op_sel:[0,0,1]
	v_cvt_pk_fp8_f32 v107, v122, v123 op_sel:[0,0,1]
	global_store_dwordx2 v91, v[106:107], s[8:9]
	s_waitcnt vmcnt(10)
	v_mul_f32_e32 v116, 0x43000000, v48
	v_mul_f32_e32 v117, 0x43000000, v49
	v_mul_f32_e32 v118, 0x43000000, v50
	v_mul_f32_e32 v119, 0x43000000, v51
	v_mul_f32_e32 v120, 0x43000000, v52
	v_mul_f32_e32 v121, 0x43000000, v53
	v_mul_f32_e32 v122, 0x43000000, v54
	v_mul_f32_e32 v123, 0x43000000, v55
	v_cvt_pk_fp8_f32 v108, v116, v117
	v_cvt_pk_fp8_f32 v109, v120, v121
	v_cvt_pk_fp8_f32 v108, v118, v119 op_sel:[0,0,1]
	v_cvt_pk_fp8_f32 v109, v122, v123 op_sel:[0,0,1]
	global_store_dwordx2 v92, v[108:109], s[8:9]
	s_waitcnt vmcnt(9)
	v_mul_f32_e32 v116, 0x43000000, v56
	v_mul_f32_e32 v117, 0x43000000, v57
	v_mul_f32_e32 v118, 0x43000000, v58
	v_mul_f32_e32 v119, 0x43000000, v59
	v_mul_f32_e32 v120, 0x43000000, v60
	v_mul_f32_e32 v121, 0x43000000, v61
	v_mul_f32_e32 v122, 0x43000000, v62
	v_mul_f32_e32 v123, 0x43000000, v63
	v_cvt_pk_fp8_f32 v110, v116, v117
	v_cvt_pk_fp8_f32 v111, v120, v121
	v_cvt_pk_fp8_f32 v110, v118, v119 op_sel:[0,0,1]
	v_cvt_pk_fp8_f32 v111, v122, v123 op_sel:[0,0,1]
	global_store_dwordx2 v93, v[110:111], s[8:9]
	s_waitcnt vmcnt(8)
	v_mul_f32_e32 v116, 0x43000000, v64
	v_mul_f32_e32 v117, 0x43000000, v65
	v_mul_f32_e32 v118, 0x43000000, v66
	v_mul_f32_e32 v119, 0x43000000, v67
	v_mul_f32_e32 v120, 0x43000000, v68
	v_mul_f32_e32 v121, 0x43000000, v69
	v_mul_f32_e32 v122, 0x43000000, v70
	v_mul_f32_e32 v123, 0x43000000, v71
	v_cvt_pk_fp8_f32 v112, v116, v117
	v_cvt_pk_fp8_f32 v113, v120, v121
	v_cvt_pk_fp8_f32 v112, v118, v119 op_sel:[0,0,1]
	v_cvt_pk_fp8_f32 v113, v122, v123 op_sel:[0,0,1]
	global_store_dwordx2 v94, v[112:113], s[8:9]
	s_waitcnt vmcnt(7)
	v_mul_f32_e32 v116, 0x43000000, v72
	v_mul_f32_e32 v117, 0x43000000, v73
	v_mul_f32_e32 v118, 0x43000000, v74
	v_mul_f32_e32 v119, 0x43000000, v75
	v_mul_f32_e32 v120, 0x43000000, v76
	v_mul_f32_e32 v121, 0x43000000, v77
	v_mul_f32_e32 v122, 0x43000000, v78
	v_mul_f32_e32 v123, 0x43000000, v79
	v_cvt_pk_fp8_f32 v114, v116, v117
	v_cvt_pk_fp8_f32 v115, v120, v121
	v_cvt_pk_fp8_f32 v114, v118, v119 op_sel:[0,0,1]
	v_cvt_pk_fp8_f32 v115, v122, v123 op_sel:[0,0,1]
	global_store_dwordx2 v95, v[114:115], s[8:9]
	s_branch .Lcv_cv0_top
.Lcv_cv0_exit:
	v_cmp_gt_u64_e32 vcc, s[4:5], v[2:3]
	s_and_b64 exec, exec, vcc
	s_cbranch_execz .LBB0_573

.Lcv_cv1_top:
	v_add_co_u32_e32 v96, vcc, 0x700, v2
	s_nop 1
	v_addc_co_u32_e32 v97, vcc, 0, v3, vcc
	v_cmp_gt_u64_e32 vcc, s[6:7], v[96:97]
	s_cmp_eq_u64 vcc, exec
	s_cbranch_scc0 .Lcv_cv1_exit
	v_lshlrev_b32_e32 v80, 5, v2
	v_lshlrev_b32_e32 v88, 3, v2
	v_add_u32_e32 v81, 0x2000, v80
	v_add_u32_e32 v89, 0x800, v88
	v_add_u32_e32 v82, 0x4000, v80
	v_add_u32_e32 v90, 0x1000, v88
	v_add_u32_e32 v83, 0x6000, v80
	v_add_u32_e32 v91, 0x1800, v88
	v_add_u32_e32 v84, 0x8000, v80
	v_add_u32_e32 v92, 0x2000, v88
	v_add_u32_e32 v85, 0xa000, v80
	v_add_u32_e32 v93, 0x2800, v88
	v_add_u32_e32 v86, 0xc000, v80
	v_add_u32_e32 v94, 0x3000, v88
	v_add_u32_e32 v87, 0xe000, v80
	v_add_u32_e32 v95, 0x3800, v88
	global_load_dwordx4 v[16:19], v80, s[38:39] nt
	global_load_dwordx4 v[20:23], v80, s[38:39] offset:16 nt
	global_load_dwordx4 v[24:27], v81, s[38:39] nt
	global_load_dwordx4 v[28:31], v81, s[38:39] offset:16 nt
	global_load_dwordx4 v[32:35], v82, s[38:39] nt
	global_load_dwordx4 v[36:39], v82, s[38:39] offset:16 nt
	global_load_dwordx4 v[40:43], v83, s[38:39] nt
	global_load_dwordx4 v[44:47], v83, s[38:39] offset:16 nt
	global_load_dwordx4 v[48:51], v84, s[38:39] nt
	global_load_dwordx4 v[52:55], v84, s[38:39] offset:16 nt
	global_load_dwordx4 v[56:59], v85, s[38:39] nt
	global_load_dwordx4 v[60:63], v85, s[38:39] offset:16 nt
	global_load_dwordx4 v[64:67], v86, s[38:39] nt
	global_load_dwordx4 v[68:71], v86, s[38:39] offset:16 nt
	global_load_dwordx4 v[72:75], v87, s[38:39] nt
	global_load_dwordx4 v[76:79], v87, s[38:39] offset:16 nt
	v_add_co_u32_e32 v2, vcc, 0x800, v2
	s_nop 1
	v_addc_co_u32_e32 v3, vcc, 0, v3, vcc
	s_waitcnt vmcnt(14)
	v_mul_f32_e32 v116, 0x41800000, v16
	v_mul_f32_e32 v117, 0x41800000, v17
	v_mul_f32_e32 v118, 0x41800000, v18
	v_mul_f32_e32 v119, 0x41800000, v19
	v_mul_f32_e32 v120, 0x41800000, v20
	v_mul_f32_e32 v121, 0x41800000, v21
	v_mul_f32_e32 v122, 0x41800000, v22
	v_mul_f32_e32 v123, 0x41800000, v23
	v_cvt_pk_fp8_f32 v100, v116, v117
	v_cvt_pk_fp8_f32 v101, v120, v121
	v_cvt_pk_fp8_f32 v100, v118, v119 op_sel:[0,0,1]
	v_cvt_pk_fp8_f32 v101, v122, v123 op_sel:[0,0,1]
	global_store_dwordx2 v88, v[100:101], s[10:11]
	s_waitcnt vmcnt(13)
	v_mul_f32_e32 v116, 0x41800000, v24
	v_mul_f32_e32 v117, 0x41800000, v25
	v_mul_f32_e32 v118, 0x41800000, v26
	v_mul_f32_e32 v119, 0x41800000, v27
	v_mul_f32_e32 v120, 0x41800000, v28
	v_mul_f32_e32 v121, 0x41800000, v29
	v_mul_f32_e32 v122, 0x41800000, v30
	v_mul_f32_e32 v123, 0x41800000, v31
	v_cvt_pk_fp8_f32 v102, v116, v117
	v_cvt_pk_fp8_f32 v103, v120, v121
	v_cvt_pk_fp8_f32 v102, v118, v119 op_sel:[0,0,1]
	v_cvt_pk_fp8_f32 v103, v122, v123 op_sel:[0,0,1]
	global_store_dwordx2 v89, v[102:103], s[10:11]
	s_waitcnt vmcnt(12)
	v_mul_f32_e32 v116, 0x41800000, v32
	v_mul_f32_e32 v117, 0x41800000, v33
	v_mul_f32_e32 v118, 0x41800000, v34
	v_mul_f32_e32 v119, 0x41800000, v35
	v_mul_f32_e32 v120, 0x41800000, v36
	v_mul_f32_e32 v121, 0x41800000, v37
	v_mul_f32_e32 v122, 0x41800000, v38
	v_mul_f32_e32 v123, 0x41800000, v39
	v_cvt_pk_fp8_f32 v104, v116, v117
	v_cvt_pk_fp8_f32 v105, v120, v121
	v_cvt_pk_fp8_f32 v104, v118, v119 op_sel:[0,0,1]
	v_cvt_pk_fp8_f32 v105, v122, v123 op_sel:[0,0,1]
	global_store_dwordx2 v90, v[104:105], s[10:11]
	s_waitcnt vmcnt(11)
	v_mul_f32_e32 v116, 0x41800000, v40
	v_mul_f32_e32 v117, 0x41800000, v41
	v_mul_f32_e32 v118, 0x41800000, v42
	v_mul_f32_e32 v119, 0x41800000, v43
	v_mul_f32_e32 v120, 0x41800000, v44
	v_mul_f32_e32 v121, 0x41800000, v45
	v_mul_f32_e32 v122, 0x41800000, v46
	v_mul_f32_e32 v123, 0x41800000, v47
	v_cvt_pk_fp8_f32 v106, v116, v117
	v_cvt_pk_fp8_f32 v107, v120, v121
	v_cvt_pk_fp8_f32 v106, v118, v119 op_sel:[0,0,1]
	v_cvt_pk_fp8_f32 v107, v122, v123 op_sel:[0,0,1]
	global_store_dwordx2 v91, v[106:107], s[10:11]
	s_waitcnt vmcnt(10)
	v_mul_f32_e32 v116, 0x41800000, v48
	v_mul_f32_e32 v117, 0x41800000, v49
	v_mul_f32_e32 v118, 0x41800000, v50
	v_mul_f32_e32 v119, 0x41800000, v51
	v_mul_f32_e32 v120, 0x41800000, v52
	v_mul_f32_e32 v121, 0x41800000, v53
	v_mul_f32_e32 v122, 0x41800000, v54
	v_mul_f32_e32 v123, 0x41800000, v55
	v_cvt_pk_fp8_f32 v108, v116, v117
	v_cvt_pk_fp8_f32 v109, v120, v121
	v_cvt_pk_fp8_f32 v108, v118, v119 op_sel:[0,0,1]
	v_cvt_pk_fp8_f32 v109, v122, v123 op_sel:[0,0,1]
	global_store_dwordx2 v92, v[108:109], s[10:11]
	s_waitcnt vmcnt(9)
	v_mul_f32_e32 v116, 0x41800000, v56
	v_mul_f32_e32 v117, 0x41800000, v57
	v_mul_f32_e32 v118, 0x41800000, v58
	v_mul_f32_e32 v119, 0x41800000, v59
	v_mul_f32_e32 v120, 0x41800000, v60
	v_mul_f32_e32 v121, 0x41800000, v61
	v_mul_f32_e32 v122, 0x41800000, v62
	v_mul_f32_e32 v123, 0x41800000, v63
	v_cvt_pk_fp8_f32 v110, v116, v117
	v_cvt_pk_fp8_f32 v111, v120, v121
	v_cvt_pk_fp8_f32 v110, v118, v119 op_sel:[0,0,1]
	v_cvt_pk_fp8_f32 v111, v122, v123 op_sel:[0,0,1]
	global_store_dwordx2 v93, v[110:111], s[10:11]
	s_waitcnt vmcnt(8)
	v_mul_f32_e32 v116, 0x41800000, v64
	v_mul_f32_e32 v117, 0x41800000, v65
	v_mul_f32_e32 v118, 0x41800000, v66
	v_mul_f32_e32 v119, 0x41800000, v67
	v_mul_f32_e32 v120, 0x41800000, v68
	v_mul_f32_e32 v121, 0x41800000, v69
	v_mul_f32_e32 v122, 0x41800000, v70
	v_mul_f32_e32 v123, 0x41800000, v71
	v_cvt_pk_fp8_f32 v112, v116, v117
	v_cvt_pk_fp8_f32 v113, v120, v121
	v_cvt_pk_fp8_f32 v112, v118, v119 op_sel:[0,0,1]
	v_cvt_pk_fp8_f32 v113, v122, v123 op_sel:[0,0,1]
	global_store_dwordx2 v94, v[112:113], s[10:11]
	s_waitcnt vmcnt(7)
	v_mul_f32_e32 v116, 0x41800000, v72
	v_mul_f32_e32 v117, 0x41800000, v73
	v_mul_f32_e32 v118, 0x41800000, v74
	v_mul_f32_e32 v119, 0x41800000, v75
	v_mul_f32_e32 v120, 0x41800000, v76
	v_mul_f32_e32 v121, 0x41800000, v77
	v_mul_f32_e32 v122, 0x41800000, v78
	v_mul_f32_e32 v123, 0x41800000, v79
	v_cvt_pk_fp8_f32 v114, v116, v117
	v_cvt_pk_fp8_f32 v115, v120, v121
	v_cvt_pk_fp8_f32 v114, v118, v119 op_sel:[0,0,1]
	v_cvt_pk_fp8_f32 v115, v122, v123 op_sel:[0,0,1]
	global_store_dwordx2 v95, v[114:115], s[10:11]
	s_branch .Lcv_cv1_top
.Lcv_cv1_exit:
	v_cmp_gt_u64_e32 vcc, s[6:7], v[2:3]
	s_and_b64 exec, exec, vcc
	s_cbranch_execz .LBB0_646

.Lcv_cv2_top:
	v_add_co_u32_e32 v96, vcc, 0x700, v2
	s_nop 1
	v_addc_co_u32_e32 v97, vcc, 0, v3, vcc
	v_cmp_gt_u64_e32 vcc, s[6:7], v[96:97]
	s_cmp_eq_u64 vcc, exec
	s_cbranch_scc0 .Lcv_cv2_exit
	v_lshlrev_b32_e32 v80, 5, v2
	v_lshlrev_b32_e32 v88, 3, v2
	v_add_u32_e32 v81, 0x2000, v80
	v_add_u32_e32 v89, 0x800, v88
	v_add_u32_e32 v82, 0x4000, v80
	v_add_u32_e32 v90, 0x1000, v88
	v_add_u32_e32 v83, 0x6000, v80
	v_add_u32_e32 v91, 0x1800, v88
	v_add_u32_e32 v84, 0x8000, v80
	v_add_u32_e32 v92, 0x2000, v88
	v_add_u32_e32 v85, 0xa000, v80
	v_add_u32_e32 v93, 0x2800, v88
	v_add_u32_e32 v86, 0xc000, v80
	v_add_u32_e32 v94, 0x3000, v88
	v_add_u32_e32 v87, 0xe000, v80
	v_add_u32_e32 v95, 0x3800, v88
	global_load_dwordx4 v[16:19], v80, s[10:11] nt
	global_load_dwordx4 v[20:23], v80, s[10:11] offset:16 nt
	global_load_dwordx4 v[24:27], v81, s[10:11] nt
	global_load_dwordx4 v[28:31], v81, s[10:11] offset:16 nt
	global_load_dwordx4 v[32:35], v82, s[10:11] nt
	global_load_dwordx4 v[36:39], v82, s[10:11] offset:16 nt
	global_load_dwordx4 v[40:43], v83, s[10:11] nt
	global_load_dwordx4 v[44:47], v83, s[10:11] offset:16 nt
	global_load_dwordx4 v[48:51], v84, s[10:11] nt
	global_load_dwordx4 v[52:55], v84, s[10:11] offset:16 nt
	global_load_dwordx4 v[56:59], v85, s[10:11] nt
	global_load_dwordx4 v[60:63], v85, s[10:11] offset:16 nt
	global_load_dwordx4 v[64:67], v86, s[10:11] nt
	global_load_dwordx4 v[68:71], v86, s[10:11] offset:16 nt
	global_load_dwordx4 v[72:75], v87, s[10:11] nt
	global_load_dwordx4 v[76:79], v87, s[10:11] offset:16 nt
	v_add_co_u32_e32 v2, vcc, 0x800, v2
	s_nop 1
	v_addc_co_u32_e32 v3, vcc, 0, v3, vcc
	s_waitcnt vmcnt(14)
	v_mul_f32_e32 v116, 0x43000000, v16
	v_mul_f32_e32 v117, 0x43000000, v17
	v_mul_f32_e32 v118, 0x43000000, v18
	v_mul_f32_e32 v119, 0x43000000, v19
	v_mul_f32_e32 v120, 0x43000000, v20
	v_mul_f32_e32 v121, 0x43000000, v21
	v_mul_f32_e32 v122, 0x43000000, v22
	v_mul_f32_e32 v123, 0x43000000, v23
	v_cvt_pk_fp8_f32 v100, v116, v117
	v_cvt_pk_fp8_f32 v101, v120, v121
	v_cvt_pk_fp8_f32 v100, v118, v119 op_sel:[0,0,1]
	v_cvt_pk_fp8_f32 v101, v122, v123 op_sel:[0,0,1]
	global_store_dwordx2 v88, v[100:101], s[12:13]
	s_waitcnt vmcnt(13)
	v_mul_f32_e32 v116, 0x43000000, v24
	v_mul_f32_e32 v117, 0x43000000, v25
	v_mul_f32_e32 v118, 0x43000000, v26
	v_mul_f32_e32 v119, 0x43000000, v27
	v_mul_f32_e32 v120, 0x43000000, v28
	v_mul_f32_e32 v121, 0x43000000, v29
	v_mul_f32_e32 v122, 0x43000000, v30
	v_mul_f32_e32 v123, 0x43000000, v31
	v_cvt_pk_fp8_f32 v102, v116, v117
	v_cvt_pk_fp8_f32 v103, v120, v121
	v_cvt_pk_fp8_f32 v102, v118, v119 op_sel:[0,0,1]
	v_cvt_pk_fp8_f32 v103, v122, v123 op_sel:[0,0,1]
	global_store_dwordx2 v89, v[102:103], s[12:13]
	s_waitcnt vmcnt(12)
	v_mul_f32_e32 v116, 0x43000000, v32
	v_mul_f32_e32 v117, 0x43000000, v33
	v_mul_f32_e32 v118, 0x43000000, v34
	v_mul_f32_e32 v119, 0x43000000, v35
	v_mul_f32_e32 v120, 0x43000000, v36
	v_mul_f32_e32 v121, 0x43000000, v37
	v_mul_f32_e32 v122, 0x43000000, v38
	v_mul_f32_e32 v123, 0x43000000, v39
	v_cvt_pk_fp8_f32 v104, v116, v117
	v_cvt_pk_fp8_f32 v105, v120, v121
	v_cvt_pk_fp8_f32 v104, v118, v119 op_sel:[0,0,1]
	v_cvt_pk_fp8_f32 v105, v122, v123 op_sel:[0,0,1]
	global_store_dwordx2 v90, v[104:105], s[12:13]
	s_waitcnt vmcnt(11)
	v_mul_f32_e32 v116, 0x43000000, v40
	v_mul_f32_e32 v117, 0x43000000, v41
	v_mul_f32_e32 v118, 0x43000000, v42
	v_mul_f32_e32 v119, 0x43000000, v43
	v_mul_f32_e32 v120, 0x43000000, v44
	v_mul_f32_e32 v121, 0x43000000, v45
	v_mul_f32_e32 v122, 0x43000000, v46
	v_mul_f32_e32 v123, 0x43000000, v47
	v_cvt_pk_fp8_f32 v106, v116, v117
	v_cvt_pk_fp8_f32 v107, v120, v121
	v_cvt_pk_fp8_f32 v106, v118, v119 op_sel:[0,0,1]
	v_cvt_pk_fp8_f32 v107, v122, v123 op_sel:[0,0,1]
	global_store_dwordx2 v91, v[106:107], s[12:13]
	s_waitcnt vmcnt(10)
	v_mul_f32_e32 v116, 0x43000000, v48
	v_mul_f32_e32 v117, 0x43000000, v49
	v_mul_f32_e32 v118, 0x43000000, v50
	v_mul_f32_e32 v119, 0x43000000, v51
	v_mul_f32_e32 v120, 0x43000000, v52
	v_mul_f32_e32 v121, 0x43000000, v53
	v_mul_f32_e32 v122, 0x43000000, v54
	v_mul_f32_e32 v123, 0x43000000, v55
	v_cvt_pk_fp8_f32 v108, v116, v117
	v_cvt_pk_fp8_f32 v109, v120, v121
	v_cvt_pk_fp8_f32 v108, v118, v119 op_sel:[0,0,1]
	v_cvt_pk_fp8_f32 v109, v122, v123 op_sel:[0,0,1]
	global_store_dwordx2 v92, v[108:109], s[12:13]
	s_waitcnt vmcnt(9)
	v_mul_f32_e32 v116, 0x43000000, v56
	v_mul_f32_e32 v117, 0x43000000, v57
	v_mul_f32_e32 v118, 0x43000000, v58
	v_mul_f32_e32 v119, 0x43000000, v59
	v_mul_f32_e32 v120, 0x43000000, v60
	v_mul_f32_e32 v121, 0x43000000, v61
	v_mul_f32_e32 v122, 0x43000000, v62
	v_mul_f32_e32 v123, 0x43000000, v63
	v_cvt_pk_fp8_f32 v110, v116, v117
	v_cvt_pk_fp8_f32 v111, v120, v121
	v_cvt_pk_fp8_f32 v110, v118, v119 op_sel:[0,0,1]
	v_cvt_pk_fp8_f32 v111, v122, v123 op_sel:[0,0,1]
	global_store_dwordx2 v93, v[110:111], s[12:13]
	s_waitcnt vmcnt(8)
	v_mul_f32_e32 v116, 0x43000000, v64
	v_mul_f32_e32 v117, 0x43000000, v65
	v_mul_f32_e32 v118, 0x43000000, v66
	v_mul_f32_e32 v119, 0x43000000, v67
	v_mul_f32_e32 v120, 0x43000000, v68
	v_mul_f32_e32 v121, 0x43000000, v69
	v_mul_f32_e32 v122, 0x43000000, v70
	v_mul_f32_e32 v123, 0x43000000, v71
	v_cvt_pk_fp8_f32 v112, v116, v117
	v_cvt_pk_fp8_f32 v113, v120, v121
	v_cvt_pk_fp8_f32 v112, v118, v119 op_sel:[0,0,1]
	v_cvt_pk_fp8_f32 v113, v122, v123 op_sel:[0,0,1]
	global_store_dwordx2 v94, v[112:113], s[12:13]
	s_waitcnt vmcnt(7)
	v_mul_f32_e32 v116, 0x43000000, v72
	v_mul_f32_e32 v117, 0x43000000, v73
	v_mul_f32_e32 v118, 0x43000000, v74
	v_mul_f32_e32 v119, 0x43000000, v75
	v_mul_f32_e32 v120, 0x43000000, v76
	v_mul_f32_e32 v121, 0x43000000, v77
	v_mul_f32_e32 v122, 0x43000000, v78
	v_mul_f32_e32 v123, 0x43000000, v79
	v_cvt_pk_fp8_f32 v114, v116, v117
	v_cvt_pk_fp8_f32 v115, v120, v121
	v_cvt_pk_fp8_f32 v114, v118, v119 op_sel:[0,0,1]
	v_cvt_pk_fp8_f32 v115, v122, v123 op_sel:[0,0,1]
	global_store_dwordx2 v95, v[114:115], s[12:13]
	s_branch .Lcv_cv2_top

.Lk_aol1a_loop:
	s_barrier
	s_add_u32 m0, s10, 32768
	v_mfma_f32_16x16x32_bf16 v[94:97], v[114:117], v[142:145], v[94:97]
	ds_read_b128 v[30:33], v100 offset:32
	global_load_lds_dwordx4 v160, s[4:5] offset:0
	v_mfma_f32_16x16x32_bf16 v[90:93], v[114:117], v[146:149], v[90:93]
	ds_read_b128 v[46:49], v158 offset:32
	global_load_lds_dwordx4 v161, s[4:5] offset:1024
	v_mfma_f32_16x16x32_bf16 v[82:85], v[114:117], v[150:153], v[82:85]
	ds_read_b128 v[50:53], v158 offset:2080
	global_load_lds_dwordx4 v162, s[4:5] offset:2048
	v_mfma_f32_16x16x32_bf16 v[78:81], v[114:117], v[154:157], v[78:81]
	ds_read_b128 v[34:37], v100 offset:2080
	global_load_lds_dwordx4 v163, s[4:5] offset:3072
	s_add_u32 m0, s10, 49152
	v_mfma_f32_16x16x32_bf16 v[74:77], v[118:121], v[142:145], v[74:77]
	ds_read_b128 v[54:57], v158 offset:4128
	global_load_lds_dwordx4 v160, s[6:7] offset:0
	v_mfma_f32_16x16x32_bf16 v[70:73], v[118:121], v[146:149], v[70:73]
	ds_read_b128 v[62:65], v158 offset:6176
	global_load_lds_dwordx4 v161, s[6:7] offset:1024
	v_mfma_f32_16x16x32_bf16 v[66:69], v[118:121], v[150:153], v[66:69]
	ds_read_b128 v[38:41], v100 offset:4128
	global_load_lds_dwordx4 v162, s[6:7] offset:2048
	v_mfma_f32_16x16x32_bf16 v[58:61], v[118:121], v[154:157], v[58:61]
	ds_read_b128 v[42:45], v100 offset:6176
	global_load_lds_dwordx4 v163, s[6:7] offset:3072
	v_mfma_f32_16x16x32_bf16 v[26:29], v[122:125], v[142:145], v[26:29]
	v_mfma_f32_16x16x32_bf16 v[22:25], v[122:125], v[146:149], v[22:25]
	v_mfma_f32_16x16x32_bf16 v[18:21], v[122:125], v[150:153], v[18:21]
	v_mfma_f32_16x16x32_bf16 v[14:17], v[122:125], v[154:157], v[14:17]
	v_mfma_f32_16x16x32_bf16 v[10:13], v[138:141], v[142:145], v[10:13]
	v_mfma_f32_16x16x32_bf16 v[6:9], v[138:141], v[146:149], v[6:9]
	v_mfma_f32_16x16x32_bf16 v[2:5], v[138:141], v[150:153], v[2:5]
	v_mfma_f32_16x16x32_bf16 v[86:89], v[138:141], v[154:157], v[86:89]
	s_add_u32 s98, s98, 1
	s_and_b32 s98, s98, 15
	s_cmp_eq_u32 s98, 0
	s_cselect_b32 s99, 0x800, 0
	s_add_u32 s4, s4, 0x80
	s_addc_u32 s5, s5, 0
	s_sub_u32 s4, s4, s99
	s_subb_u32 s5, s5, 0
	s_add_u32 s6, s6, 0x80
	s_addc_u32 s7, s7, 0
	s_sub_u32 s6, s6, s99
	s_subb_u32 s7, s7, 0
	s_waitcnt lgkmcnt(0)
	v_mfma_f32_16x16x32_bf16 v[94:97], v[30:33], v[46:49], v[94:97]
	ds_read_b128 v[114:117], v111 offset:32
	v_mfma_f32_16x16x32_bf16 v[90:93], v[30:33], v[50:53], v[90:93]
	ds_read_b128 v[142:145], v159 offset:32
	v_mfma_f32_16x16x32_bf16 v[82:85], v[30:33], v[54:57], v[82:85]
	ds_read_b128 v[146:149], v159 offset:2080
	v_mfma_f32_16x16x32_bf16 v[78:81], v[30:33], v[62:65], v[78:81]
	ds_read_b128 v[118:121], v111 offset:2080
	v_mfma_f32_16x16x32_bf16 v[74:77], v[34:37], v[46:49], v[74:77]
	ds_read_b128 v[150:153], v159 offset:4128
	v_mfma_f32_16x16x32_bf16 v[70:73], v[34:37], v[50:53], v[70:73]
	ds_read_b128 v[154:157], v159 offset:6176
	v_mfma_f32_16x16x32_bf16 v[66:69], v[34:37], v[54:57], v[66:69]
	ds_read_b128 v[122:125], v111 offset:4128
	v_mfma_f32_16x16x32_bf16 v[58:61], v[34:37], v[62:65], v[58:61]
	ds_read_b128 v[138:141], v111 offset:6176
	v_mfma_f32_16x16x32_bf16 v[26:29], v[38:41], v[46:49], v[26:29]
	v_mfma_f32_16x16x32_bf16 v[22:25], v[38:41], v[50:53], v[22:25]
	v_mfma_f32_16x16x32_bf16 v[18:21], v[38:41], v[54:57], v[18:21]
	v_mfma_f32_16x16x32_bf16 v[14:17], v[38:41], v[62:65], v[14:17]
	v_mfma_f32_16x16x32_bf16 v[10:13], v[42:45], v[46:49], v[10:13]
	v_mfma_f32_16x16x32_bf16 v[6:9], v[42:45], v[50:53], v[6:9]
	v_mfma_f32_16x16x32_bf16 v[2:5], v[42:45], v[54:57], v[2:5]
	v_mfma_f32_16x16x32_bf16 v[86:89], v[42:45], v[62:65], v[86:89]
	s_waitcnt lgkmcnt(0)
	s_waitcnt vmcnt(0)
	s_barrier
	s_add_u32 m0, s10, 0
	v_mfma_f32_16x16x32_bf16 v[94:97], v[114:117], v[142:145], v[94:97]
	ds_read_b128 v[30:33], v100 offset:32800
	global_load_lds_dwordx4 v160, s[4:5] offset:0
	v_mfma_f32_16x16x32_bf16 v[90:93], v[114:117], v[146:149], v[90:93]
	ds_read_b128 v[46:49], v158 offset:32800
	global_load_lds_dwordx4 v161, s[4:5] offset:1024
	v_mfma_f32_16x16x32_bf16 v[82:85], v[114:117], v[150:153], v[82:85]
	ds_read_b128 v[50:53], v158 offset:34848
	global_load_lds_dwordx4 v162, s[4:5] offset:2048
	v_mfma_f32_16x16x32_bf16 v[78:81], v[114:117], v[154:157], v[78:81]
	ds_read_b128 v[34:37], v100 offset:34848
	global_load_lds_dwordx4 v163, s[4:5] offset:3072
	s_add_u32 m0, s10, 16384
	v_mfma_f32_16x16x32_bf16 v[74:77], v[118:121], v[142:145], v[74:77]
	ds_read_b128 v[54:57], v158 offset:36896
	global_load_lds_dwordx4 v160, s[6:7] offset:0
	v_mfma_f32_16x16x32_bf16 v[70:73], v[118:121], v[146:149], v[70:73]
	ds_read_b128 v[62:65], v158 offset:38944
	global_load_lds_dwordx4 v161, s[6:7] offset:1024
	v_mfma_f32_16x16x32_bf16 v[66:69], v[118:121], v[150:153], v[66:69]
	ds_read_b128 v[38:41], v100 offset:36896
	global_load_lds_dwordx4 v162, s[6:7] offset:2048
	v_mfma_f32_16x16x32_bf16 v[58:61], v[118:121], v[154:157], v[58:61]
	ds_read_b128 v[42:45], v100 offset:38944
	global_load_lds_dwordx4 v163, s[6:7] offset:3072
	v_mfma_f32_16x16x32_bf16 v[26:29], v[122:125], v[142:145], v[26:29]
	v_mfma_f32_16x16x32_bf16 v[22:25], v[122:125], v[146:149], v[22:25]
	v_mfma_f32_16x16x32_bf16 v[18:21], v[122:125], v[150:153], v[18:21]
	v_mfma_f32_16x16x32_bf16 v[14:17], v[122:125], v[154:157], v[14:17]
	v_mfma_f32_16x16x32_bf16 v[10:13], v[138:141], v[142:145], v[10:13]
	v_mfma_f32_16x16x32_bf16 v[6:9], v[138:141], v[146:149], v[6:9]
	v_mfma_f32_16x16x32_bf16 v[2:5], v[138:141], v[150:153], v[2:5]
	v_mfma_f32_16x16x32_bf16 v[86:89], v[138:141], v[154:157], v[86:89]
	s_add_u32 s98, s98, 1
	s_and_b32 s98, s98, 15
	s_cmp_eq_u32 s98, 0
	s_cselect_b32 s99, 0x800, 0
	s_add_u32 s4, s4, 0x80
	s_addc_u32 s5, s5, 0
	s_sub_u32 s4, s4, s99
	s_subb_u32 s5, s5, 0
	s_add_u32 s6, s6, 0x80
	s_addc_u32 s7, s7, 0
	s_sub_u32 s6, s6, s99
	s_subb_u32 s7, s7, 0
	s_waitcnt lgkmcnt(0)
	v_mfma_f32_16x16x32_bf16 v[94:97], v[30:33], v[46:49], v[94:97]
	ds_read_b128 v[114:117], v111 offset:32800
	v_mfma_f32_16x16x32_bf16 v[90:93], v[30:33], v[50:53], v[90:93]
	ds_read_b128 v[142:145], v159 offset:32800
	v_mfma_f32_16x16x32_bf16 v[82:85], v[30:33], v[54:57], v[82:85]
	ds_read_b128 v[146:149], v159 offset:34848
	v_mfma_f32_16x16x32_bf16 v[78:81], v[30:33], v[62:65], v[78:81]
	ds_read_b128 v[118:121], v111 offset:34848
	v_mfma_f32_16x16x32_bf16 v[74:77], v[34:37], v[46:49], v[74:77]
	ds_read_b128 v[150:153], v159 offset:36896
	v_mfma_f32_16x16x32_bf16 v[70:73], v[34:37], v[50:53], v[70:73]
	ds_read_b128 v[154:157], v159 offset:38944
	v_mfma_f32_16x16x32_bf16 v[66:69], v[34:37], v[54:57], v[66:69]
	ds_read_b128 v[122:125], v111 offset:36896
	v_mfma_f32_16x16x32_bf16 v[58:61], v[34:37], v[62:65], v[58:61]
	ds_read_b128 v[138:141], v111 offset:38944
	v_mfma_f32_16x16x32_bf16 v[26:29], v[38:41], v[46:49], v[26:29]
	v_mfma_f32_16x16x32_bf16 v[22:25], v[38:41], v[50:53], v[22:25]
	v_mfma_f32_16x16x32_bf16 v[18:21], v[38:41], v[54:57], v[18:21]
	v_mfma_f32_16x16x32_bf16 v[14:17], v[38:41], v[62:65], v[14:17]
	v_mfma_f32_16x16x32_bf16 v[10:13], v[42:45], v[46:49], v[10:13]
	v_mfma_f32_16x16x32_bf16 v[6:9], v[42:45], v[50:53], v[6:9]
	v_mfma_f32_16x16x32_bf16 v[2:5], v[42:45], v[54:57], v[2:5]
	v_mfma_f32_16x16x32_bf16 v[86:89], v[42:45], v[62:65], v[86:89]
	s_waitcnt lgkmcnt(0)
	s_waitcnt vmcnt(0)
	s_add_u32 s9, s9, 1
	s_cmp_lt_u32 s9, 7
	s_cbranch_scc1 .Lk_aol1a_loop
	s_barrier
	s_add_u32 m0, s10, 32768
	v_mfma_f32_16x16x32_bf16 v[94:97], v[114:117], v[142:145], v[94:97]
	ds_read_b128 v[30:33], v100 offset:32
	global_load_lds_dwordx4 v160, s[4:5] offset:0
	v_mfma_f32_16x16x32_bf16 v[90:93], v[114:117], v[146:149], v[90:93]
	ds_read_b128 v[46:49], v158 offset:32
	global_load_lds_dwordx4 v161, s[4:5] offset:1024
	v_mfma_f32_16x16x32_bf16 v[82:85], v[114:117], v[150:153], v[82:85]
	ds_read_b128 v[50:53], v158 offset:2080
	global_load_lds_dwordx4 v162, s[4:5] offset:2048
	v_mfma_f32_16x16x32_bf16 v[78:81], v[114:117], v[154:157], v[78:81]
	ds_read_b128 v[34:37], v100 offset:2080
	global_load_lds_dwordx4 v163, s[4:5] offset:3072
	s_add_u32 m0, s10, 49152
	v_mfma_f32_16x16x32_bf16 v[74:77], v[118:121], v[142:145], v[74:77]
	ds_read_b128 v[54:57], v158 offset:4128
	global_load_lds_dwordx4 v160, s[6:7] offset:0
	v_mfma_f32_16x16x32_bf16 v[70:73], v[118:121], v[146:149], v[70:73]
	ds_read_b128 v[62:65], v158 offset:6176
	global_load_lds_dwordx4 v161, s[6:7] offset:1024
	v_mfma_f32_16x16x32_bf16 v[66:69], v[118:121], v[150:153], v[66:69]
	ds_read_b128 v[38:41], v100 offset:4128
	global_load_lds_dwordx4 v162, s[6:7] offset:2048
	v_mfma_f32_16x16x32_bf16 v[58:61], v[118:121], v[154:157], v[58:61]
	ds_read_b128 v[42:45], v100 offset:6176
	global_load_lds_dwordx4 v163, s[6:7] offset:3072
	v_mfma_f32_16x16x32_bf16 v[26:29], v[122:125], v[142:145], v[26:29]
	v_mfma_f32_16x16x32_bf16 v[22:25], v[122:125], v[146:149], v[22:25]
	v_mfma_f32_16x16x32_bf16 v[18:21], v[122:125], v[150:153], v[18:21]
	v_mfma_f32_16x16x32_bf16 v[14:17], v[122:125], v[154:157], v[14:17]
	v_mfma_f32_16x16x32_bf16 v[10:13], v[138:141], v[142:145], v[10:13]
	v_mfma_f32_16x16x32_bf16 v[6:9], v[138:141], v[146:149], v[6:9]
	v_mfma_f32_16x16x32_bf16 v[2:5], v[138:141], v[150:153], v[2:5]
	v_mfma_f32_16x16x32_bf16 v[86:89], v[138:141], v[154:157], v[86:89]
	s_add_u32 s98, s98, 1
	s_and_b32 s98, s98, 15
	s_cmp_eq_u32 s98, 0
	s_cselect_b32 s99, 0x800, 0
	s_add_u32 s4, s4, 0x80
	s_addc_u32 s5, s5, 0
	s_sub_u32 s4, s4, s99
	s_subb_u32 s5, s5, 0
	s_add_u32 s6, s6, 0x80
	s_addc_u32 s7, s7, 0
	s_sub_u32 s6, s6, s99
	s_subb_u32 s7, s7, 0
	s_waitcnt lgkmcnt(0)
	v_mfma_f32_16x16x32_bf16 v[94:97], v[30:33], v[46:49], v[94:97]
	ds_read_b128 v[114:117], v111 offset:32
	v_mfma_f32_16x16x32_bf16 v[90:93], v[30:33], v[50:53], v[90:93]
	ds_read_b128 v[142:145], v159 offset:32
	v_mfma_f32_16x16x32_bf16 v[82:85], v[30:33], v[54:57], v[82:85]
	ds_read_b128 v[146:149], v159 offset:2080
	v_mfma_f32_16x16x32_bf16 v[78:81], v[30:33], v[62:65], v[78:81]
	ds_read_b128 v[118:121], v111 offset:2080
	v_mfma_f32_16x16x32_bf16 v[74:77], v[34:37], v[46:49], v[74:77]
	ds_read_b128 v[150:153], v159 offset:4128
	v_mfma_f32_16x16x32_bf16 v[70:73], v[34:37], v[50:53], v[70:73]
	ds_read_b128 v[154:157], v159 offset:6176
	v_mfma_f32_16x16x32_bf16 v[66:69], v[34:37], v[54:57], v[66:69]
	ds_read_b128 v[122:125], v111 offset:4128
	v_mfma_f32_16x16x32_bf16 v[58:61], v[34:37], v[62:65], v[58:61]
	ds_read_b128 v[138:141], v111 offset:6176
	v_mfma_f32_16x16x32_bf16 v[26:29], v[38:41], v[46:49], v[26:29]
	v_mfma_f32_16x16x32_bf16 v[22:25], v[38:41], v[50:53], v[22:25]
	v_mfma_f32_16x16x32_bf16 v[18:21], v[38:41], v[54:57], v[18:21]
	v_mfma_f32_16x16x32_bf16 v[14:17], v[38:41], v[62:65], v[14:17]
	v_mfma_f32_16x16x32_bf16 v[10:13], v[42:45], v[46:49], v[10:13]
	v_mfma_f32_16x16x32_bf16 v[6:9], v[42:45], v[50:53], v[6:9]
	v_mfma_f32_16x16x32_bf16 v[2:5], v[42:45], v[54:57], v[2:5]
	v_mfma_f32_16x16x32_bf16 v[86:89], v[42:45], v[62:65], v[86:89]
	s_waitcnt lgkmcnt(0)
	s_waitcnt vmcnt(0)
	s_barrier
	v_mfma_f32_16x16x32_bf16 v[94:97], v[114:117], v[142:145], v[94:97]
	ds_read_b128 v[30:33], v100 offset:32800
	v_mfma_f32_16x16x32_bf16 v[90:93], v[114:117], v[146:149], v[90:93]
	ds_read_b128 v[46:49], v158 offset:32800
	v_mfma_f32_16x16x32_bf16 v[82:85], v[114:117], v[150:153], v[82:85]
	ds_read_b128 v[50:53], v158 offset:34848
	v_mfma_f32_16x16x32_bf16 v[78:81], v[114:117], v[154:157], v[78:81]
	ds_read_b128 v[34:37], v100 offset:34848
	v_mfma_f32_16x16x32_bf16 v[74:77], v[118:121], v[142:145], v[74:77]
	ds_read_b128 v[54:57], v158 offset:36896
	v_mfma_f32_16x16x32_bf16 v[70:73], v[118:121], v[146:149], v[70:73]
	ds_read_b128 v[62:65], v158 offset:38944
	v_mfma_f32_16x16x32_bf16 v[66:69], v[118:121], v[150:153], v[66:69]
	ds_read_b128 v[38:41], v100 offset:36896
	v_mfma_f32_16x16x32_bf16 v[58:61], v[118:121], v[154:157], v[58:61]
	ds_read_b128 v[42:45], v100 offset:38944
	v_mfma_f32_16x16x32_bf16 v[26:29], v[122:125], v[142:145], v[26:29]
	v_mfma_f32_16x16x32_bf16 v[22:25], v[122:125], v[146:149], v[22:25]
	v_mfma_f32_16x16x32_bf16 v[18:21], v[122:125], v[150:153], v[18:21]
	v_mfma_f32_16x16x32_bf16 v[14:17], v[122:125], v[154:157], v[14:17]
	v_mfma_f32_16x16x32_bf16 v[10:13], v[138:141], v[142:145], v[10:13]
	v_mfma_f32_16x16x32_bf16 v[6:9], v[138:141], v[146:149], v[6:9]
	v_mfma_f32_16x16x32_bf16 v[2:5], v[138:141], v[150:153], v[2:5]
	v_mfma_f32_16x16x32_bf16 v[86:89], v[138:141], v[154:157], v[86:89]
	s_waitcnt lgkmcnt(0)
	v_mfma_f32_16x16x32_bf16 v[94:97], v[30:33], v[46:49], v[94:97]
	ds_read_b128 v[114:117], v111 offset:32800
	v_mfma_f32_16x16x32_bf16 v[90:93], v[30:33], v[50:53], v[90:93]
	ds_read_b128 v[142:145], v159 offset:32800
	v_mfma_f32_16x16x32_bf16 v[82:85], v[30:33], v[54:57], v[82:85]
	ds_read_b128 v[146:149], v159 offset:34848
	v_mfma_f32_16x16x32_bf16 v[78:81], v[30:33], v[62:65], v[78:81]
	ds_read_b128 v[118:121], v111 offset:34848
	v_mfma_f32_16x16x32_bf16 v[74:77], v[34:37], v[46:49], v[74:77]
	ds_read_b128 v[150:153], v159 offset:36896
	v_mfma_f32_16x16x32_bf16 v[70:73], v[34:37], v[50:53], v[70:73]
	ds_read_b128 v[154:157], v159 offset:38944
	v_mfma_f32_16x16x32_bf16 v[66:69], v[34:37], v[54:57], v[66:69]
	ds_read_b128 v[122:125], v111 offset:36896
	v_mfma_f32_16x16x32_bf16 v[58:61], v[34:37], v[62:65], v[58:61]
	ds_read_b128 v[138:141], v111 offset:38944
	v_mfma_f32_16x16x32_bf16 v[26:29], v[38:41], v[46:49], v[26:29]
	v_mfma_f32_16x16x32_bf16 v[22:25], v[38:41], v[50:53], v[22:25]
	v_mfma_f32_16x16x32_bf16 v[18:21], v[38:41], v[54:57], v[18:21]
	v_mfma_f32_16x16x32_bf16 v[14:17], v[38:41], v[62:65], v[14:17]
	v_mfma_f32_16x16x32_bf16 v[10:13], v[42:45], v[46:49], v[10:13]
	v_mfma_f32_16x16x32_bf16 v[6:9], v[42:45], v[50:53], v[6:9]
	v_mfma_f32_16x16x32_bf16 v[2:5], v[42:45], v[54:57], v[2:5]
	v_mfma_f32_16x16x32_bf16 v[86:89], v[42:45], v[62:65], v[86:89]
	s_waitcnt lgkmcnt(0)
	v_mfma_f32_16x16x32_bf16 v[94:97], v[114:117], v[142:145], v[94:97]
	v_mfma_f32_16x16x32_bf16 v[90:93], v[114:117], v[146:149], v[90:93]
	v_mfma_f32_16x16x32_bf16 v[82:85], v[114:117], v[150:153], v[82:85]
	v_mfma_f32_16x16x32_bf16 v[78:81], v[114:117], v[154:157], v[78:81]
	v_mfma_f32_16x16x32_bf16 v[74:77], v[118:121], v[142:145], v[74:77]
	v_mfma_f32_16x16x32_bf16 v[70:73], v[118:121], v[146:149], v[70:73]
	v_mfma_f32_16x16x32_bf16 v[66:69], v[118:121], v[150:153], v[66:69]
	v_mfma_f32_16x16x32_bf16 v[58:61], v[118:121], v[154:157], v[58:61]
	v_mfma_f32_16x16x32_bf16 v[26:29], v[122:125], v[142:145], v[26:29]
	v_mfma_f32_16x16x32_bf16 v[22:25], v[122:125], v[146:149], v[22:25]
	v_mfma_f32_16x16x32_bf16 v[18:21], v[122:125], v[150:153], v[18:21]
	v_mfma_f32_16x16x32_bf16 v[14:17], v[122:125], v[154:157], v[14:17]
	v_mfma_f32_16x16x32_bf16 v[10:13], v[138:141], v[142:145], v[10:13]
	v_mfma_f32_16x16x32_bf16 v[6:9], v[138:141], v[146:149], v[6:9]
	v_mfma_f32_16x16x32_bf16 v[2:5], v[138:141], v[150:153], v[2:5]
	v_mfma_f32_16x16x32_bf16 v[86:89], v[138:141], v[154:157], v[86:89]
	v_lshrrev_b32_e32 v117, 4, v0
	v_and_b32_e32 v117, 15, v117
	v_and_b32_e32 v118, 15, v0
	v_lshlrev_b32_e32 v118, 4, v118
	v_lshl_or_b32 v117, v117, 12, v118
	s_lshl_b32 s100, s8, 12
	s_lshl_b32 s98, s73, 8
	s_add_u32 s100, s100, s98
	s_add_u32 s98, s42, s100
	s_addc_u32 s99, s43, 0
	s_add_u32 s98, s98, 0x12d24000
	s_addc_u32 s99, s99, 0
	global_load_dwordx4 v[148:151], v117, s[98:99]
	global_load_dwordx4 v[152:155], v117, s[98:99] offset:2048
	s_add_u32 s98, s98, 0x10000
	s_addc_u32 s99, s99, 0
	global_load_dwordx4 v[156:159], v117, s[98:99]
	global_load_dwordx4 v[160:163], v117, s[98:99] offset:2048
	s_add_u32 s98, s98, 0x10000
	s_addc_u32 s99, s99, 0
	global_load_dwordx4 v[164:167], v117, s[98:99]
	global_load_dwordx4 v[168:171], v117, s[98:99] offset:2048
	s_add_u32 s98, s98, 0x10000
	s_addc_u32 s99, s99, 0
	global_load_dwordx4 v[172:175], v117, s[98:99]
	global_load_dwordx4 v[176:179], v117, s[98:99] offset:2048
	s_add_u32 s98, s98, 0x10000
	s_addc_u32 s99, s99, 0
	global_load_dwordx4 v[180:183], v117, s[98:99]
	global_load_dwordx4 v[184:187], v117, s[98:99] offset:2048
	s_add_u32 s98, s98, 0x10000
	s_addc_u32 s99, s99, 0
	global_load_dwordx4 v[188:191], v117, s[98:99]
	global_load_dwordx4 v[192:195], v117, s[98:99] offset:2048
	s_add_u32 s98, s98, 0x10000
	s_addc_u32 s99, s99, 0
	global_load_dwordx4 v[196:199], v117, s[98:99]
	global_load_dwordx4 v[34:37], v117, s[98:99] offset:2048
	s_add_u32 s98, s98, 0x10000
	s_addc_u32 s99, s99, 0
	global_load_dwordx4 v[38:41], v117, s[98:99]
	global_load_dwordx4 v[52:55], v117, s[98:99] offset:2048
	s_mul_i32 s4, s68, s62
	s_add_i32 s4, s4, s67
	s_and_b32 s4, s4, 0xff
	v_lshl_or_b32 v30, s4, 10, v132
	s_mul_hi_u32 s4, s4, 0x15555556
	s_mulk_i32 s4, 0xd000
	v_add_u32_e32 v30, s4, v30
	s_lshl_b32 s36, s73, 8
	v_add_u32_e32 v138, 0x400, v129
	v_add_u32_e32 v139, 0x2000, v129
	v_add_u32_e32 v140, 0x2400, v129
	v_add_u32_e32 v141, 0x4000, v129
	v_add_u32_e32 v142, 0x4400, v129
	v_add_u32_e32 v143, 0x4800, v129
	v_add_u32_e32 v144, 0x6000, v129
	v_add_u32_e32 v145, 0x6400, v129
	v_add_u32_e32 v146, 0x6800, v129
	v_lshl_add_u64 v[114:115], v[102:103], 0, s[36:37]
	v_cmp_gt_u32_e32 vcc, s66, v30
	s_barrier
	ds_write2_b32 v129, v94, v90 offset1:16
	ds_write2_b32 v129, v95, v91 offset0:132 offset1:148
	ds_write2_b32 v138, v96, v92 offset0:8 offset1:24
	ds_write2_b32 v138, v97, v93 offset0:140 offset1:156
	ds_write2_b32 v129, v82, v78 offset0:32 offset1:48
	ds_write2_b32 v129, v83, v79 offset0:164 offset1:180
	ds_write2_b32 v138, v84, v80 offset0:40 offset1:56
	ds_write2_b32 v138, v85, v81 offset0:172 offset1:188
	ds_write2_b32 v139, v74, v70 offset0:64 offset1:80
	ds_write2_b32 v139, v75, v71 offset0:196 offset1:212
	ds_write2_b32 v140, v76, v72 offset0:72 offset1:88
	ds_write2_b32 v140, v77, v73 offset0:204 offset1:220
	ds_write2_b32 v139, v66, v58 offset0:96 offset1:112
	ds_write2_b32 v139, v67, v59 offset0:228 offset1:244
	ds_write2_b32 v140, v68, v60 offset0:104 offset1:120
	ds_write2_b32 v140, v69, v61 offset0:236 offset1:252
	ds_write2_b32 v141, v26, v22 offset0:128 offset1:144
	ds_write2_b32 v142, v27, v23 offset0:4 offset1:20
	ds_write2_b32 v142, v28, v24 offset0:136 offset1:152
	ds_write2_b32 v143, v29, v25 offset0:12 offset1:28
	ds_write2_b32 v141, v18, v14 offset0:160 offset1:176
	ds_write2_b32 v142, v19, v15 offset0:36 offset1:52
	ds_write2_b32 v142, v20, v16 offset0:168 offset1:184
	ds_write2_b32 v143, v21, v17 offset0:44 offset1:60
	ds_write2_b32 v144, v10, v6 offset0:192 offset1:208
	ds_write2_b32 v145, v11, v7 offset0:68 offset1:84
	ds_write2_b32 v145, v12, v8 offset0:200 offset1:216
	ds_write2_b32 v146, v13, v9 offset0:76 offset1:92
	ds_write2_b32 v144, v2, v86 offset0:224 offset1:240
	ds_write2_b32 v145, v3, v87 offset0:100 offset1:116
	ds_write2_b32 v145, v4, v88 offset0:232 offset1:248
	ds_write2_b32 v146, v5, v89 offset0:108 offset1:124
	s_waitcnt lgkmcnt(0)
	s_barrier
	v_lshrrev_b32_e32 v50, 4, v0
	v_and_b32_e32 v50, 15, v50
	v_mul_u32_u24_e32 v50, 0x210, v50
	v_and_b32_e32 v2, 15, v0
	v_lshl_add_u32 v50, v2, 5, v50
	ds_read_b128 v[42:45], v50 offset:32
	ds_read_b128 v[46:49], v50 offset:48
	s_waitcnt vmcnt(14)
	v_lshlrev_b32_e32 v2, 16, v148
	v_lshlrev_b32_e32 v3, 16, v152
	v_div_scale_f32 v4, s[4:5], v3, v3, v2
	v_rcp_f32_e32 v5, v4
	s_nop 0
	v_fma_f32 v6, -v4, v5, 1.0
	v_fmac_f32_e32 v5, v6, v5
	v_div_scale_f32 v7, vcc, v2, v3, v2
	v_mul_f32_e32 v8, v7, v5
	v_fma_f32 v6, -v4, v8, v7
	v_fmac_f32_e32 v8, v6, v5
	v_fma_f32 v4, -v4, v8, v7
	v_div_fmas_f32 v4, v4, v5, v8
	v_div_fixup_f32 v10, v4, v3, v2
	v_and_b32_e32 v2, 0xffff0000, v148
	v_and_b32_e32 v3, 0xffff0000, v152
	v_div_scale_f32 v4, s[4:5], v3, v3, v2
	v_rcp_f32_e32 v5, v4
	s_nop 0
	v_fma_f32 v6, -v4, v5, 1.0
	v_fmac_f32_e32 v5, v6, v5
	v_div_scale_f32 v7, vcc, v2, v3, v2
	v_mul_f32_e32 v8, v7, v5
	v_fma_f32 v6, -v4, v8, v7
	v_fmac_f32_e32 v8, v6, v5
	v_fma_f32 v4, -v4, v8, v7
	v_div_fmas_f32 v4, v4, v5, v8
	v_div_fixup_f32 v11, v4, v3, v2
	v_lshlrev_b32_e32 v2, 16, v149
	v_lshlrev_b32_e32 v3, 16, v153
	v_div_scale_f32 v4, s[4:5], v3, v3, v2
	v_rcp_f32_e32 v5, v4
	s_nop 0
	v_fma_f32 v6, -v4, v5, 1.0
	v_fmac_f32_e32 v5, v6, v5
	v_div_scale_f32 v7, vcc, v2, v3, v2
	v_mul_f32_e32 v8, v7, v5
	v_fma_f32 v6, -v4, v8, v7
	v_fmac_f32_e32 v8, v6, v5
	v_fma_f32 v4, -v4, v8, v7
	v_div_fmas_f32 v4, v4, v5, v8
	v_div_fixup_f32 v12, v4, v3, v2
	v_and_b32_e32 v2, 0xffff0000, v149
	v_and_b32_e32 v3, 0xffff0000, v153
	v_div_scale_f32 v4, s[4:5], v3, v3, v2
	v_rcp_f32_e32 v5, v4
	s_nop 0
	v_fma_f32 v6, -v4, v5, 1.0
	v_fmac_f32_e32 v5, v6, v5
	v_div_scale_f32 v7, vcc, v2, v3, v2
	v_mul_f32_e32 v8, v7, v5
	v_fma_f32 v6, -v4, v8, v7
	v_fmac_f32_e32 v8, v6, v5
	v_fma_f32 v4, -v4, v8, v7
	v_div_fmas_f32 v4, v4, v5, v8
	v_div_fixup_f32 v13, v4, v3, v2
	v_lshlrev_b32_e32 v2, 16, v150
	v_lshlrev_b32_e32 v3, 16, v154
	v_div_scale_f32 v4, s[4:5], v3, v3, v2
	v_rcp_f32_e32 v5, v4
	s_nop 0
	v_fma_f32 v6, -v4, v5, 1.0
	v_fmac_f32_e32 v5, v6, v5
	v_div_scale_f32 v7, vcc, v2, v3, v2
	v_mul_f32_e32 v8, v7, v5
	v_fma_f32 v6, -v4, v8, v7
	v_fmac_f32_e32 v8, v6, v5
	v_fma_f32 v4, -v4, v8, v7
	v_div_fmas_f32 v4, v4, v5, v8
	v_div_fixup_f32 v14, v4, v3, v2
	v_and_b32_e32 v2, 0xffff0000, v150
	v_and_b32_e32 v3, 0xffff0000, v154
	v_div_scale_f32 v4, s[4:5], v3, v3, v2
	v_rcp_f32_e32 v5, v4
	s_nop 0
	v_fma_f32 v6, -v4, v5, 1.0
	v_fmac_f32_e32 v5, v6, v5
	v_div_scale_f32 v7, vcc, v2, v3, v2
	v_mul_f32_e32 v8, v7, v5
	v_fma_f32 v6, -v4, v8, v7
	v_fmac_f32_e32 v8, v6, v5
	v_fma_f32 v4, -v4, v8, v7
	v_div_fmas_f32 v4, v4, v5, v8
	v_div_fixup_f32 v15, v4, v3, v2
	v_lshlrev_b32_e32 v2, 16, v151
	v_lshlrev_b32_e32 v3, 16, v155
	v_div_scale_f32 v4, s[4:5], v3, v3, v2
	v_rcp_f32_e32 v5, v4
	s_nop 0
	v_fma_f32 v6, -v4, v5, 1.0
	v_fmac_f32_e32 v5, v6, v5
	v_div_scale_f32 v7, vcc, v2, v3, v2
	v_mul_f32_e32 v8, v7, v5
	v_fma_f32 v6, -v4, v8, v7
	v_fmac_f32_e32 v8, v6, v5
	v_fma_f32 v4, -v4, v8, v7
	v_div_fmas_f32 v4, v4, v5, v8
	v_div_fixup_f32 v16, v4, v3, v2
	v_and_b32_e32 v2, 0xffff0000, v151
	v_and_b32_e32 v3, 0xffff0000, v155
	v_div_scale_f32 v4, s[4:5], v3, v3, v2
	v_rcp_f32_e32 v5, v4
	s_nop 0
	v_fma_f32 v6, -v4, v5, 1.0
	v_fmac_f32_e32 v5, v6, v5
	v_div_scale_f32 v7, vcc, v2, v3, v2
	v_mul_f32_e32 v8, v7, v5
	v_fma_f32 v6, -v4, v8, v7
	v_fmac_f32_e32 v8, v6, v5
	v_fma_f32 v4, -v4, v8, v7
	v_div_fmas_f32 v4, v4, v5, v8
	v_div_fixup_f32 v17, v4, v3, v2
	s_waitcnt lgkmcnt(0)
	v_pk_mul_f32 v[42:43], v[42:43], v[10:11]
	v_pk_mul_f32 v[44:45], v[44:45], v[12:13]
	v_pk_mul_f32 v[46:47], v[46:47], v[14:15]
	v_pk_mul_f32 v[48:49], v[48:49], v[16:17]
	ds_write_b128 v50, v[42:45] offset:32
	ds_write_b128 v50, v[46:49] offset:48
	ds_read_b128 v[42:45], v50 offset:8480
	ds_read_b128 v[46:49], v50 offset:8496
	s_waitcnt vmcnt(12)
	v_lshlrev_b32_e32 v2, 16, v156
	v_lshlrev_b32_e32 v3, 16, v160
	v_div_scale_f32 v4, s[4:5], v3, v3, v2
	v_rcp_f32_e32 v5, v4
	s_nop 0
	v_fma_f32 v6, -v4, v5, 1.0
	v_fmac_f32_e32 v5, v6, v5
	v_div_scale_f32 v7, vcc, v2, v3, v2
	v_mul_f32_e32 v8, v7, v5
	v_fma_f32 v6, -v4, v8, v7
	v_fmac_f32_e32 v8, v6, v5
	v_fma_f32 v4, -v4, v8, v7
	v_div_fmas_f32 v4, v4, v5, v8
	v_div_fixup_f32 v10, v4, v3, v2
	v_and_b32_e32 v2, 0xffff0000, v156
	v_and_b32_e32 v3, 0xffff0000, v160
	v_div_scale_f32 v4, s[4:5], v3, v3, v2
	v_rcp_f32_e32 v5, v4
	s_nop 0
	v_fma_f32 v6, -v4, v5, 1.0
	v_fmac_f32_e32 v5, v6, v5
	v_div_scale_f32 v7, vcc, v2, v3, v2
	v_mul_f32_e32 v8, v7, v5
	v_fma_f32 v6, -v4, v8, v7
	v_fmac_f32_e32 v8, v6, v5
	v_fma_f32 v4, -v4, v8, v7
	v_div_fmas_f32 v4, v4, v5, v8
	v_div_fixup_f32 v11, v4, v3, v2
	v_lshlrev_b32_e32 v2, 16, v157
	v_lshlrev_b32_e32 v3, 16, v161
	v_div_scale_f32 v4, s[4:5], v3, v3, v2
	v_rcp_f32_e32 v5, v4
	s_nop 0
	v_fma_f32 v6, -v4, v5, 1.0
	v_fmac_f32_e32 v5, v6, v5
	v_div_scale_f32 v7, vcc, v2, v3, v2
	v_mul_f32_e32 v8, v7, v5
	v_fma_f32 v6, -v4, v8, v7
	v_fmac_f32_e32 v8, v6, v5
	v_fma_f32 v4, -v4, v8, v7
	v_div_fmas_f32 v4, v4, v5, v8
	v_div_fixup_f32 v12, v4, v3, v2
	v_and_b32_e32 v2, 0xffff0000, v157
	v_and_b32_e32 v3, 0xffff0000, v161
	v_div_scale_f32 v4, s[4:5], v3, v3, v2
	v_rcp_f32_e32 v5, v4
	s_nop 0
	v_fma_f32 v6, -v4, v5, 1.0
	v_fmac_f32_e32 v5, v6, v5
	v_div_scale_f32 v7, vcc, v2, v3, v2
	v_mul_f32_e32 v8, v7, v5
	v_fma_f32 v6, -v4, v8, v7
	v_fmac_f32_e32 v8, v6, v5
	v_fma_f32 v4, -v4, v8, v7
	v_div_fmas_f32 v4, v4, v5, v8
	v_div_fixup_f32 v13, v4, v3, v2
	v_lshlrev_b32_e32 v2, 16, v158
	v_lshlrev_b32_e32 v3, 16, v162
	v_div_scale_f32 v4, s[4:5], v3, v3, v2
	v_rcp_f32_e32 v5, v4
	s_nop 0
	v_fma_f32 v6, -v4, v5, 1.0
	v_fmac_f32_e32 v5, v6, v5
	v_div_scale_f32 v7, vcc, v2, v3, v2
	v_mul_f32_e32 v8, v7, v5
	v_fma_f32 v6, -v4, v8, v7
	v_fmac_f32_e32 v8, v6, v5
	v_fma_f32 v4, -v4, v8, v7
	v_div_fmas_f32 v4, v4, v5, v8
	v_div_fixup_f32 v14, v4, v3, v2
	v_and_b32_e32 v2, 0xffff0000, v158
	v_and_b32_e32 v3, 0xffff0000, v162
	v_div_scale_f32 v4, s[4:5], v3, v3, v2
	v_rcp_f32_e32 v5, v4
	s_nop 0
	v_fma_f32 v6, -v4, v5, 1.0
	v_fmac_f32_e32 v5, v6, v5
	v_div_scale_f32 v7, vcc, v2, v3, v2
	v_mul_f32_e32 v8, v7, v5
	v_fma_f32 v6, -v4, v8, v7
	v_fmac_f32_e32 v8, v6, v5
	v_fma_f32 v4, -v4, v8, v7
	v_div_fmas_f32 v4, v4, v5, v8
	v_div_fixup_f32 v15, v4, v3, v2
	v_lshlrev_b32_e32 v2, 16, v159
	v_lshlrev_b32_e32 v3, 16, v163
	v_div_scale_f32 v4, s[4:5], v3, v3, v2
	v_rcp_f32_e32 v5, v4
	s_nop 0
	v_fma_f32 v6, -v4, v5, 1.0
	v_fmac_f32_e32 v5, v6, v5
	v_div_scale_f32 v7, vcc, v2, v3, v2
	v_mul_f32_e32 v8, v7, v5
	v_fma_f32 v6, -v4, v8, v7
	v_fmac_f32_e32 v8, v6, v5
	v_fma_f32 v4, -v4, v8, v7
	v_div_fmas_f32 v4, v4, v5, v8
	v_div_fixup_f32 v16, v4, v3, v2
	v_and_b32_e32 v2, 0xffff0000, v159
	v_and_b32_e32 v3, 0xffff0000, v163
	v_div_scale_f32 v4, s[4:5], v3, v3, v2
	v_rcp_f32_e32 v5, v4
	s_nop 0
	v_fma_f32 v6, -v4, v5, 1.0
	v_fmac_f32_e32 v5, v6, v5
	v_div_scale_f32 v7, vcc, v2, v3, v2
	v_mul_f32_e32 v8, v7, v5
	v_fma_f32 v6, -v4, v8, v7
	v_fmac_f32_e32 v8, v6, v5
	v_fma_f32 v4, -v4, v8, v7
	v_div_fmas_f32 v4, v4, v5, v8
	v_div_fixup_f32 v17, v4, v3, v2
	s_waitcnt lgkmcnt(0)
	v_pk_mul_f32 v[42:43], v[42:43], v[10:11]
	v_pk_mul_f32 v[44:45], v[44:45], v[12:13]
	v_pk_mul_f32 v[46:47], v[46:47], v[14:15]
	v_pk_mul_f32 v[48:49], v[48:49], v[16:17]
	ds_write_b128 v50, v[42:45] offset:8480
	ds_write_b128 v50, v[46:49] offset:8496
	ds_read_b128 v[42:45], v50 offset:16928
	ds_read_b128 v[46:49], v50 offset:16944
	s_waitcnt vmcnt(10)
	v_lshlrev_b32_e32 v2, 16, v164
	v_lshlrev_b32_e32 v3, 16, v168
	v_div_scale_f32 v4, s[4:5], v3, v3, v2
	v_rcp_f32_e32 v5, v4
	s_nop 0
	v_fma_f32 v6, -v4, v5, 1.0
	v_fmac_f32_e32 v5, v6, v5
	v_div_scale_f32 v7, vcc, v2, v3, v2
	v_mul_f32_e32 v8, v7, v5
	v_fma_f32 v6, -v4, v8, v7
	v_fmac_f32_e32 v8, v6, v5
	v_fma_f32 v4, -v4, v8, v7
	v_div_fmas_f32 v4, v4, v5, v8
	v_div_fixup_f32 v10, v4, v3, v2
	v_and_b32_e32 v2, 0xffff0000, v164
	v_and_b32_e32 v3, 0xffff0000, v168
	v_div_scale_f32 v4, s[4:5], v3, v3, v2
	v_rcp_f32_e32 v5, v4
	s_nop 0
	v_fma_f32 v6, -v4, v5, 1.0
	v_fmac_f32_e32 v5, v6, v5
	v_div_scale_f32 v7, vcc, v2, v3, v2
	v_mul_f32_e32 v8, v7, v5
	v_fma_f32 v6, -v4, v8, v7
	v_fmac_f32_e32 v8, v6, v5
	v_fma_f32 v4, -v4, v8, v7
	v_div_fmas_f32 v4, v4, v5, v8
	v_div_fixup_f32 v11, v4, v3, v2
	v_lshlrev_b32_e32 v2, 16, v165
	v_lshlrev_b32_e32 v3, 16, v169
	v_div_scale_f32 v4, s[4:5], v3, v3, v2
	v_rcp_f32_e32 v5, v4
	s_nop 0
	v_fma_f32 v6, -v4, v5, 1.0
	v_fmac_f32_e32 v5, v6, v5
	v_div_scale_f32 v7, vcc, v2, v3, v2
	v_mul_f32_e32 v8, v7, v5
	v_fma_f32 v6, -v4, v8, v7
	v_fmac_f32_e32 v8, v6, v5
	v_fma_f32 v4, -v4, v8, v7
	v_div_fmas_f32 v4, v4, v5, v8
	v_div_fixup_f32 v12, v4, v3, v2
	v_and_b32_e32 v2, 0xffff0000, v165
	v_and_b32_e32 v3, 0xffff0000, v169
	v_div_scale_f32 v4, s[4:5], v3, v3, v2
	v_rcp_f32_e32 v5, v4
	s_nop 0
	v_fma_f32 v6, -v4, v5, 1.0
	v_fmac_f32_e32 v5, v6, v5
	v_div_scale_f32 v7, vcc, v2, v3, v2
	v_mul_f32_e32 v8, v7, v5
	v_fma_f32 v6, -v4, v8, v7
	v_fmac_f32_e32 v8, v6, v5
	v_fma_f32 v4, -v4, v8, v7
	v_div_fmas_f32 v4, v4, v5, v8
	v_div_fixup_f32 v13, v4, v3, v2
	v_lshlrev_b32_e32 v2, 16, v166
	v_lshlrev_b32_e32 v3, 16, v170
	v_div_scale_f32 v4, s[4:5], v3, v3, v2
	v_rcp_f32_e32 v5, v4
	s_nop 0
	v_fma_f32 v6, -v4, v5, 1.0
	v_fmac_f32_e32 v5, v6, v5
	v_div_scale_f32 v7, vcc, v2, v3, v2
	v_mul_f32_e32 v8, v7, v5
	v_fma_f32 v6, -v4, v8, v7
	v_fmac_f32_e32 v8, v6, v5
	v_fma_f32 v4, -v4, v8, v7
	v_div_fmas_f32 v4, v4, v5, v8
	v_div_fixup_f32 v14, v4, v3, v2
	v_and_b32_e32 v2, 0xffff0000, v166
	v_and_b32_e32 v3, 0xffff0000, v170
	v_div_scale_f32 v4, s[4:5], v3, v3, v2
	v_rcp_f32_e32 v5, v4
	s_nop 0
	v_fma_f32 v6, -v4, v5, 1.0
	v_fmac_f32_e32 v5, v6, v5
	v_div_scale_f32 v7, vcc, v2, v3, v2
	v_mul_f32_e32 v8, v7, v5
	v_fma_f32 v6, -v4, v8, v7
	v_fmac_f32_e32 v8, v6, v5
	v_fma_f32 v4, -v4, v8, v7
	v_div_fmas_f32 v4, v4, v5, v8
	v_div_fixup_f32 v15, v4, v3, v2
	v_lshlrev_b32_e32 v2, 16, v167
	v_lshlrev_b32_e32 v3, 16, v171
	v_div_scale_f32 v4, s[4:5], v3, v3, v2
	v_rcp_f32_e32 v5, v4
	s_nop 0
	v_fma_f32 v6, -v4, v5, 1.0
	v_fmac_f32_e32 v5, v6, v5
	v_div_scale_f32 v7, vcc, v2, v3, v2
	v_mul_f32_e32 v8, v7, v5
	v_fma_f32 v6, -v4, v8, v7
	v_fmac_f32_e32 v8, v6, v5
	v_fma_f32 v4, -v4, v8, v7
	v_div_fmas_f32 v4, v4, v5, v8
	v_div_fixup_f32 v16, v4, v3, v2
	v_and_b32_e32 v2, 0xffff0000, v167
	v_and_b32_e32 v3, 0xffff0000, v171
	v_div_scale_f32 v4, s[4:5], v3, v3, v2
	v_rcp_f32_e32 v5, v4
	s_nop 0
	v_fma_f32 v6, -v4, v5, 1.0
	v_fmac_f32_e32 v5, v6, v5
	v_div_scale_f32 v7, vcc, v2, v3, v2
	v_mul_f32_e32 v8, v7, v5
	v_fma_f32 v6, -v4, v8, v7
	v_fmac_f32_e32 v8, v6, v5
	v_fma_f32 v4, -v4, v8, v7
	v_div_fmas_f32 v4, v4, v5, v8
	v_div_fixup_f32 v17, v4, v3, v2
	s_waitcnt lgkmcnt(0)
	v_pk_mul_f32 v[42:43], v[42:43], v[10:11]
	v_pk_mul_f32 v[44:45], v[44:45], v[12:13]
	v_pk_mul_f32 v[46:47], v[46:47], v[14:15]
	v_pk_mul_f32 v[48:49], v[48:49], v[16:17]
	ds_write_b128 v50, v[42:45] offset:16928
	ds_write_b128 v50, v[46:49] offset:16944
	ds_read_b128 v[42:45], v50 offset:25376
	ds_read_b128 v[46:49], v50 offset:25392
	s_waitcnt vmcnt(8)
	v_lshlrev_b32_e32 v2, 16, v172
	v_lshlrev_b32_e32 v3, 16, v176
	v_div_scale_f32 v4, s[4:5], v3, v3, v2
	v_rcp_f32_e32 v5, v4
	s_nop 0
	v_fma_f32 v6, -v4, v5, 1.0
	v_fmac_f32_e32 v5, v6, v5
	v_div_scale_f32 v7, vcc, v2, v3, v2
	v_mul_f32_e32 v8, v7, v5
	v_fma_f32 v6, -v4, v8, v7
	v_fmac_f32_e32 v8, v6, v5
	v_fma_f32 v4, -v4, v8, v7
	v_div_fmas_f32 v4, v4, v5, v8
	v_div_fixup_f32 v10, v4, v3, v2
	v_and_b32_e32 v2, 0xffff0000, v172
	v_and_b32_e32 v3, 0xffff0000, v176
	v_div_scale_f32 v4, s[4:5], v3, v3, v2
	v_rcp_f32_e32 v5, v4
	s_nop 0
	v_fma_f32 v6, -v4, v5, 1.0
	v_fmac_f32_e32 v5, v6, v5
	v_div_scale_f32 v7, vcc, v2, v3, v2
	v_mul_f32_e32 v8, v7, v5
	v_fma_f32 v6, -v4, v8, v7
	v_fmac_f32_e32 v8, v6, v5
	v_fma_f32 v4, -v4, v8, v7
	v_div_fmas_f32 v4, v4, v5, v8
	v_div_fixup_f32 v11, v4, v3, v2
	v_lshlrev_b32_e32 v2, 16, v173
	v_lshlrev_b32_e32 v3, 16, v177
	v_div_scale_f32 v4, s[4:5], v3, v3, v2
	v_rcp_f32_e32 v5, v4
	s_nop 0
	v_fma_f32 v6, -v4, v5, 1.0
	v_fmac_f32_e32 v5, v6, v5
	v_div_scale_f32 v7, vcc, v2, v3, v2
	v_mul_f32_e32 v8, v7, v5
	v_fma_f32 v6, -v4, v8, v7
	v_fmac_f32_e32 v8, v6, v5
	v_fma_f32 v4, -v4, v8, v7
	v_div_fmas_f32 v4, v4, v5, v8
	v_div_fixup_f32 v12, v4, v3, v2
	v_and_b32_e32 v2, 0xffff0000, v173
	v_and_b32_e32 v3, 0xffff0000, v177
	v_div_scale_f32 v4, s[4:5], v3, v3, v2
	v_rcp_f32_e32 v5, v4
	s_nop 0
	v_fma_f32 v6, -v4, v5, 1.0
	v_fmac_f32_e32 v5, v6, v5
	v_div_scale_f32 v7, vcc, v2, v3, v2
	v_mul_f32_e32 v8, v7, v5
	v_fma_f32 v6, -v4, v8, v7
	v_fmac_f32_e32 v8, v6, v5
	v_fma_f32 v4, -v4, v8, v7
	v_div_fmas_f32 v4, v4, v5, v8
	v_div_fixup_f32 v13, v4, v3, v2
	v_lshlrev_b32_e32 v2, 16, v174
	v_lshlrev_b32_e32 v3, 16, v178
	v_div_scale_f32 v4, s[4:5], v3, v3, v2
	v_rcp_f32_e32 v5, v4
	s_nop 0
	v_fma_f32 v6, -v4, v5, 1.0
	v_fmac_f32_e32 v5, v6, v5
	v_div_scale_f32 v7, vcc, v2, v3, v2
	v_mul_f32_e32 v8, v7, v5
	v_fma_f32 v6, -v4, v8, v7
	v_fmac_f32_e32 v8, v6, v5
	v_fma_f32 v4, -v4, v8, v7
	v_div_fmas_f32 v4, v4, v5, v8
	v_div_fixup_f32 v14, v4, v3, v2
	v_and_b32_e32 v2, 0xffff0000, v174
	v_and_b32_e32 v3, 0xffff0000, v178
	v_div_scale_f32 v4, s[4:5], v3, v3, v2
	v_rcp_f32_e32 v5, v4
	s_nop 0
	v_fma_f32 v6, -v4, v5, 1.0
	v_fmac_f32_e32 v5, v6, v5
	v_div_scale_f32 v7, vcc, v2, v3, v2
	v_mul_f32_e32 v8, v7, v5
	v_fma_f32 v6, -v4, v8, v7
	v_fmac_f32_e32 v8, v6, v5
	v_fma_f32 v4, -v4, v8, v7
	v_div_fmas_f32 v4, v4, v5, v8
	v_div_fixup_f32 v15, v4, v3, v2
	v_lshlrev_b32_e32 v2, 16, v175
	v_lshlrev_b32_e32 v3, 16, v179
	v_div_scale_f32 v4, s[4:5], v3, v3, v2
	v_rcp_f32_e32 v5, v4
	s_nop 0
	v_fma_f32 v6, -v4, v5, 1.0
	v_fmac_f32_e32 v5, v6, v5
	v_div_scale_f32 v7, vcc, v2, v3, v2
	v_mul_f32_e32 v8, v7, v5
	v_fma_f32 v6, -v4, v8, v7
	v_fmac_f32_e32 v8, v6, v5
	v_fma_f32 v4, -v4, v8, v7
	v_div_fmas_f32 v4, v4, v5, v8
	v_div_fixup_f32 v16, v4, v3, v2
	v_and_b32_e32 v2, 0xffff0000, v175
	v_and_b32_e32 v3, 0xffff0000, v179
	v_div_scale_f32 v4, s[4:5], v3, v3, v2
	v_rcp_f32_e32 v5, v4
	s_nop 0
	v_fma_f32 v6, -v4, v5, 1.0
	v_fmac_f32_e32 v5, v6, v5
	v_div_scale_f32 v7, vcc, v2, v3, v2
	v_mul_f32_e32 v8, v7, v5
	v_fma_f32 v6, -v4, v8, v7
	v_fmac_f32_e32 v8, v6, v5
	v_fma_f32 v4, -v4, v8, v7
	v_div_fmas_f32 v4, v4, v5, v8
	v_div_fixup_f32 v17, v4, v3, v2
	s_waitcnt lgkmcnt(0)
	v_pk_mul_f32 v[42:43], v[42:43], v[10:11]
	v_pk_mul_f32 v[44:45], v[44:45], v[12:13]
	v_pk_mul_f32 v[46:47], v[46:47], v[14:15]
	v_pk_mul_f32 v[48:49], v[48:49], v[16:17]
	ds_write_b128 v50, v[42:45] offset:25376
	ds_write_b128 v50, v[46:49] offset:25392
	ds_read_b128 v[42:45], v50 offset:33824
	ds_read_b128 v[46:49], v50 offset:33840
	s_waitcnt vmcnt(6)
	v_lshlrev_b32_e32 v2, 16, v180
	v_lshlrev_b32_e32 v3, 16, v184
	v_div_scale_f32 v4, s[4:5], v3, v3, v2
	v_rcp_f32_e32 v5, v4
	s_nop 0
	v_fma_f32 v6, -v4, v5, 1.0
	v_fmac_f32_e32 v5, v6, v5
	v_div_scale_f32 v7, vcc, v2, v3, v2
	v_mul_f32_e32 v8, v7, v5
	v_fma_f32 v6, -v4, v8, v7
	v_fmac_f32_e32 v8, v6, v5
	v_fma_f32 v4, -v4, v8, v7
	v_div_fmas_f32 v4, v4, v5, v8
	v_div_fixup_f32 v10, v4, v3, v2
	v_and_b32_e32 v2, 0xffff0000, v180
	v_and_b32_e32 v3, 0xffff0000, v184
	v_div_scale_f32 v4, s[4:5], v3, v3, v2
	v_rcp_f32_e32 v5, v4
	s_nop 0
	v_fma_f32 v6, -v4, v5, 1.0
	v_fmac_f32_e32 v5, v6, v5
	v_div_scale_f32 v7, vcc, v2, v3, v2
	v_mul_f32_e32 v8, v7, v5
	v_fma_f32 v6, -v4, v8, v7
	v_fmac_f32_e32 v8, v6, v5
	v_fma_f32 v4, -v4, v8, v7
	v_div_fmas_f32 v4, v4, v5, v8
	v_div_fixup_f32 v11, v4, v3, v2
	v_lshlrev_b32_e32 v2, 16, v181
	v_lshlrev_b32_e32 v3, 16, v185
	v_div_scale_f32 v4, s[4:5], v3, v3, v2
	v_rcp_f32_e32 v5, v4
	s_nop 0
	v_fma_f32 v6, -v4, v5, 1.0
	v_fmac_f32_e32 v5, v6, v5
	v_div_scale_f32 v7, vcc, v2, v3, v2
	v_mul_f32_e32 v8, v7, v5
	v_fma_f32 v6, -v4, v8, v7
	v_fmac_f32_e32 v8, v6, v5
	v_fma_f32 v4, -v4, v8, v7
	v_div_fmas_f32 v4, v4, v5, v8
	v_div_fixup_f32 v12, v4, v3, v2
	v_and_b32_e32 v2, 0xffff0000, v181
	v_and_b32_e32 v3, 0xffff0000, v185
	v_div_scale_f32 v4, s[4:5], v3, v3, v2
	v_rcp_f32_e32 v5, v4
	s_nop 0
	v_fma_f32 v6, -v4, v5, 1.0
	v_fmac_f32_e32 v5, v6, v5
	v_div_scale_f32 v7, vcc, v2, v3, v2
	v_mul_f32_e32 v8, v7, v5
	v_fma_f32 v6, -v4, v8, v7
	v_fmac_f32_e32 v8, v6, v5
	v_fma_f32 v4, -v4, v8, v7
	v_div_fmas_f32 v4, v4, v5, v8
	v_div_fixup_f32 v13, v4, v3, v2
	v_lshlrev_b32_e32 v2, 16, v182
	v_lshlrev_b32_e32 v3, 16, v186
	v_div_scale_f32 v4, s[4:5], v3, v3, v2
	v_rcp_f32_e32 v5, v4
	s_nop 0
	v_fma_f32 v6, -v4, v5, 1.0
	v_fmac_f32_e32 v5, v6, v5
	v_div_scale_f32 v7, vcc, v2, v3, v2
	v_mul_f32_e32 v8, v7, v5
	v_fma_f32 v6, -v4, v8, v7
	v_fmac_f32_e32 v8, v6, v5
	v_fma_f32 v4, -v4, v8, v7
	v_div_fmas_f32 v4, v4, v5, v8
	v_div_fixup_f32 v14, v4, v3, v2
	v_and_b32_e32 v2, 0xffff0000, v182
	v_and_b32_e32 v3, 0xffff0000, v186
	v_div_scale_f32 v4, s[4:5], v3, v3, v2
	v_rcp_f32_e32 v5, v4
	s_nop 0
	v_fma_f32 v6, -v4, v5, 1.0
	v_fmac_f32_e32 v5, v6, v5
	v_div_scale_f32 v7, vcc, v2, v3, v2
	v_mul_f32_e32 v8, v7, v5
	v_fma_f32 v6, -v4, v8, v7
	v_fmac_f32_e32 v8, v6, v5
	v_fma_f32 v4, -v4, v8, v7
	v_div_fmas_f32 v4, v4, v5, v8
	v_div_fixup_f32 v15, v4, v3, v2
	v_lshlrev_b32_e32 v2, 16, v183
	v_lshlrev_b32_e32 v3, 16, v187
	v_div_scale_f32 v4, s[4:5], v3, v3, v2
	v_rcp_f32_e32 v5, v4
	s_nop 0
	v_fma_f32 v6, -v4, v5, 1.0
	v_fmac_f32_e32 v5, v6, v5
	v_div_scale_f32 v7, vcc, v2, v3, v2
	v_mul_f32_e32 v8, v7, v5
	v_fma_f32 v6, -v4, v8, v7
	v_fmac_f32_e32 v8, v6, v5
	v_fma_f32 v4, -v4, v8, v7
	v_div_fmas_f32 v4, v4, v5, v8
	v_div_fixup_f32 v16, v4, v3, v2
	v_and_b32_e32 v2, 0xffff0000, v183
	v_and_b32_e32 v3, 0xffff0000, v187
	v_div_scale_f32 v4, s[4:5], v3, v3, v2
	v_rcp_f32_e32 v5, v4
	s_nop 0
	v_fma_f32 v6, -v4, v5, 1.0
	v_fmac_f32_e32 v5, v6, v5
	v_div_scale_f32 v7, vcc, v2, v3, v2
	v_mul_f32_e32 v8, v7, v5
	v_fma_f32 v6, -v4, v8, v7
	v_fmac_f32_e32 v8, v6, v5
	v_fma_f32 v4, -v4, v8, v7
	v_div_fmas_f32 v4, v4, v5, v8
	v_div_fixup_f32 v17, v4, v3, v2
	s_waitcnt lgkmcnt(0)
	v_pk_mul_f32 v[42:43], v[42:43], v[10:11]
	v_pk_mul_f32 v[44:45], v[44:45], v[12:13]
	v_pk_mul_f32 v[46:47], v[46:47], v[14:15]
	v_pk_mul_f32 v[48:49], v[48:49], v[16:17]
	ds_write_b128 v50, v[42:45] offset:33824
	ds_write_b128 v50, v[46:49] offset:33840
	ds_read_b128 v[42:45], v50 offset:42272
	ds_read_b128 v[46:49], v50 offset:42288
	s_waitcnt vmcnt(4)
	v_lshlrev_b32_e32 v2, 16, v188
	v_lshlrev_b32_e32 v3, 16, v192
	v_div_scale_f32 v4, s[4:5], v3, v3, v2
	v_rcp_f32_e32 v5, v4
	s_nop 0
	v_fma_f32 v6, -v4, v5, 1.0
	v_fmac_f32_e32 v5, v6, v5
	v_div_scale_f32 v7, vcc, v2, v3, v2
	v_mul_f32_e32 v8, v7, v5
	v_fma_f32 v6, -v4, v8, v7
	v_fmac_f32_e32 v8, v6, v5
	v_fma_f32 v4, -v4, v8, v7
	v_div_fmas_f32 v4, v4, v5, v8
	v_div_fixup_f32 v10, v4, v3, v2
	v_and_b32_e32 v2, 0xffff0000, v188
	v_and_b32_e32 v3, 0xffff0000, v192
	v_div_scale_f32 v4, s[4:5], v3, v3, v2
	v_rcp_f32_e32 v5, v4
	s_nop 0
	v_fma_f32 v6, -v4, v5, 1.0
	v_fmac_f32_e32 v5, v6, v5
	v_div_scale_f32 v7, vcc, v2, v3, v2
	v_mul_f32_e32 v8, v7, v5
	v_fma_f32 v6, -v4, v8, v7
	v_fmac_f32_e32 v8, v6, v5
	v_fma_f32 v4, -v4, v8, v7
	v_div_fmas_f32 v4, v4, v5, v8
	v_div_fixup_f32 v11, v4, v3, v2
	v_lshlrev_b32_e32 v2, 16, v189
	v_lshlrev_b32_e32 v3, 16, v193
	v_div_scale_f32 v4, s[4:5], v3, v3, v2
	v_rcp_f32_e32 v5, v4
	s_nop 0
	v_fma_f32 v6, -v4, v5, 1.0
	v_fmac_f32_e32 v5, v6, v5
	v_div_scale_f32 v7, vcc, v2, v3, v2
	v_mul_f32_e32 v8, v7, v5
	v_fma_f32 v6, -v4, v8, v7
	v_fmac_f32_e32 v8, v6, v5
	v_fma_f32 v4, -v4, v8, v7
	v_div_fmas_f32 v4, v4, v5, v8
	v_div_fixup_f32 v12, v4, v3, v2
	v_and_b32_e32 v2, 0xffff0000, v189
	v_and_b32_e32 v3, 0xffff0000, v193
	v_div_scale_f32 v4, s[4:5], v3, v3, v2
	v_rcp_f32_e32 v5, v4
	s_nop 0
	v_fma_f32 v6, -v4, v5, 1.0
	v_fmac_f32_e32 v5, v6, v5
	v_div_scale_f32 v7, vcc, v2, v3, v2
	v_mul_f32_e32 v8, v7, v5
	v_fma_f32 v6, -v4, v8, v7
	v_fmac_f32_e32 v8, v6, v5
	v_fma_f32 v4, -v4, v8, v7
	v_div_fmas_f32 v4, v4, v5, v8
	v_div_fixup_f32 v13, v4, v3, v2
	v_lshlrev_b32_e32 v2, 16, v190
	v_lshlrev_b32_e32 v3, 16, v194
	v_div_scale_f32 v4, s[4:5], v3, v3, v2
	v_rcp_f32_e32 v5, v4
	s_nop 0
	v_fma_f32 v6, -v4, v5, 1.0
	v_fmac_f32_e32 v5, v6, v5
	v_div_scale_f32 v7, vcc, v2, v3, v2
	v_mul_f32_e32 v8, v7, v5
	v_fma_f32 v6, -v4, v8, v7
	v_fmac_f32_e32 v8, v6, v5
	v_fma_f32 v4, -v4, v8, v7
	v_div_fmas_f32 v4, v4, v5, v8
	v_div_fixup_f32 v14, v4, v3, v2
	v_and_b32_e32 v2, 0xffff0000, v190
	v_and_b32_e32 v3, 0xffff0000, v194
	v_div_scale_f32 v4, s[4:5], v3, v3, v2
	v_rcp_f32_e32 v5, v4
	s_nop 0
	v_fma_f32 v6, -v4, v5, 1.0
	v_fmac_f32_e32 v5, v6, v5
	v_div_scale_f32 v7, vcc, v2, v3, v2
	v_mul_f32_e32 v8, v7, v5
	v_fma_f32 v6, -v4, v8, v7
	v_fmac_f32_e32 v8, v6, v5
	v_fma_f32 v4, -v4, v8, v7
	v_div_fmas_f32 v4, v4, v5, v8
	v_div_fixup_f32 v15, v4, v3, v2
	v_lshlrev_b32_e32 v2, 16, v191
	v_lshlrev_b32_e32 v3, 16, v195
	v_div_scale_f32 v4, s[4:5], v3, v3, v2
	v_rcp_f32_e32 v5, v4
	s_nop 0
	v_fma_f32 v6, -v4, v5, 1.0
	v_fmac_f32_e32 v5, v6, v5
	v_div_scale_f32 v7, vcc, v2, v3, v2
	v_mul_f32_e32 v8, v7, v5
	v_fma_f32 v6, -v4, v8, v7
	v_fmac_f32_e32 v8, v6, v5
	v_fma_f32 v4, -v4, v8, v7
	v_div_fmas_f32 v4, v4, v5, v8
	v_div_fixup_f32 v16, v4, v3, v2
	v_and_b32_e32 v2, 0xffff0000, v191
	v_and_b32_e32 v3, 0xffff0000, v195
	v_div_scale_f32 v4, s[4:5], v3, v3, v2
	v_rcp_f32_e32 v5, v4
	s_nop 0
	v_fma_f32 v6, -v4, v5, 1.0
	v_fmac_f32_e32 v5, v6, v5
	v_div_scale_f32 v7, vcc, v2, v3, v2
	v_mul_f32_e32 v8, v7, v5
	v_fma_f32 v6, -v4, v8, v7
	v_fmac_f32_e32 v8, v6, v5
	v_fma_f32 v4, -v4, v8, v7
	v_div_fmas_f32 v4, v4, v5, v8
	v_div_fixup_f32 v17, v4, v3, v2
	s_waitcnt lgkmcnt(0)
	v_pk_mul_f32 v[42:43], v[42:43], v[10:11]
	v_pk_mul_f32 v[44:45], v[44:45], v[12:13]
	v_pk_mul_f32 v[46:47], v[46:47], v[14:15]
	v_pk_mul_f32 v[48:49], v[48:49], v[16:17]
	ds_write_b128 v50, v[42:45] offset:42272
	ds_write_b128 v50, v[46:49] offset:42288
	ds_read_b128 v[42:45], v50 offset:50720
	ds_read_b128 v[46:49], v50 offset:50736
	s_waitcnt vmcnt(2)
	v_lshlrev_b32_e32 v2, 16, v196
	v_lshlrev_b32_e32 v3, 16, v34
	v_div_scale_f32 v4, s[4:5], v3, v3, v2
	v_rcp_f32_e32 v5, v4
	s_nop 0
	v_fma_f32 v6, -v4, v5, 1.0
	v_fmac_f32_e32 v5, v6, v5
	v_div_scale_f32 v7, vcc, v2, v3, v2
	v_mul_f32_e32 v8, v7, v5
	v_fma_f32 v6, -v4, v8, v7
	v_fmac_f32_e32 v8, v6, v5
	v_fma_f32 v4, -v4, v8, v7
	v_div_fmas_f32 v4, v4, v5, v8
	v_div_fixup_f32 v10, v4, v3, v2
	v_and_b32_e32 v2, 0xffff0000, v196
	v_and_b32_e32 v3, 0xffff0000, v34
	v_div_scale_f32 v4, s[4:5], v3, v3, v2
	v_rcp_f32_e32 v5, v4
	s_nop 0
	v_fma_f32 v6, -v4, v5, 1.0
	v_fmac_f32_e32 v5, v6, v5
	v_div_scale_f32 v7, vcc, v2, v3, v2
	v_mul_f32_e32 v8, v7, v5
	v_fma_f32 v6, -v4, v8, v7
	v_fmac_f32_e32 v8, v6, v5
	v_fma_f32 v4, -v4, v8, v7
	v_div_fmas_f32 v4, v4, v5, v8
	v_div_fixup_f32 v11, v4, v3, v2
	v_lshlrev_b32_e32 v2, 16, v197
	v_lshlrev_b32_e32 v3, 16, v35
	v_div_scale_f32 v4, s[4:5], v3, v3, v2
	v_rcp_f32_e32 v5, v4
	s_nop 0
	v_fma_f32 v6, -v4, v5, 1.0
	v_fmac_f32_e32 v5, v6, v5
	v_div_scale_f32 v7, vcc, v2, v3, v2
	v_mul_f32_e32 v8, v7, v5
	v_fma_f32 v6, -v4, v8, v7
	v_fmac_f32_e32 v8, v6, v5
	v_fma_f32 v4, -v4, v8, v7
	v_div_fmas_f32 v4, v4, v5, v8
	v_div_fixup_f32 v12, v4, v3, v2
	v_and_b32_e32 v2, 0xffff0000, v197
	v_and_b32_e32 v3, 0xffff0000, v35
	v_div_scale_f32 v4, s[4:5], v3, v3, v2
	v_rcp_f32_e32 v5, v4
	s_nop 0
	v_fma_f32 v6, -v4, v5, 1.0
	v_fmac_f32_e32 v5, v6, v5
	v_div_scale_f32 v7, vcc, v2, v3, v2
	v_mul_f32_e32 v8, v7, v5
	v_fma_f32 v6, -v4, v8, v7
	v_fmac_f32_e32 v8, v6, v5
	v_fma_f32 v4, -v4, v8, v7
	v_div_fmas_f32 v4, v4, v5, v8
	v_div_fixup_f32 v13, v4, v3, v2
	v_lshlrev_b32_e32 v2, 16, v198
	v_lshlrev_b32_e32 v3, 16, v36
	v_div_scale_f32 v4, s[4:5], v3, v3, v2
	v_rcp_f32_e32 v5, v4
	s_nop 0
	v_fma_f32 v6, -v4, v5, 1.0
	v_fmac_f32_e32 v5, v6, v5
	v_div_scale_f32 v7, vcc, v2, v3, v2
	v_mul_f32_e32 v8, v7, v5
	v_fma_f32 v6, -v4, v8, v7
	v_fmac_f32_e32 v8, v6, v5
	v_fma_f32 v4, -v4, v8, v7
	v_div_fmas_f32 v4, v4, v5, v8
	v_div_fixup_f32 v14, v4, v3, v2
	v_and_b32_e32 v2, 0xffff0000, v198
	v_and_b32_e32 v3, 0xffff0000, v36
	v_div_scale_f32 v4, s[4:5], v3, v3, v2
	v_rcp_f32_e32 v5, v4
	s_nop 0
	v_fma_f32 v6, -v4, v5, 1.0
	v_fmac_f32_e32 v5, v6, v5
	v_div_scale_f32 v7, vcc, v2, v3, v2
	v_mul_f32_e32 v8, v7, v5
	v_fma_f32 v6, -v4, v8, v7
	v_fmac_f32_e32 v8, v6, v5
	v_fma_f32 v4, -v4, v8, v7
	v_div_fmas_f32 v4, v4, v5, v8
	v_div_fixup_f32 v15, v4, v3, v2
	v_lshlrev_b32_e32 v2, 16, v199
	v_lshlrev_b32_e32 v3, 16, v37
	v_div_scale_f32 v4, s[4:5], v3, v3, v2
	v_rcp_f32_e32 v5, v4
	s_nop 0
	v_fma_f32 v6, -v4, v5, 1.0
	v_fmac_f32_e32 v5, v6, v5
	v_div_scale_f32 v7, vcc, v2, v3, v2
	v_mul_f32_e32 v8, v7, v5
	v_fma_f32 v6, -v4, v8, v7
	v_fmac_f32_e32 v8, v6, v5
	v_fma_f32 v4, -v4, v8, v7
	v_div_fmas_f32 v4, v4, v5, v8
	v_div_fixup_f32 v16, v4, v3, v2
	v_and_b32_e32 v2, 0xffff0000, v199
	v_and_b32_e32 v3, 0xffff0000, v37
	v_div_scale_f32 v4, s[4:5], v3, v3, v2
	v_rcp_f32_e32 v5, v4
	s_nop 0
	v_fma_f32 v6, -v4, v5, 1.0
	v_fmac_f32_e32 v5, v6, v5
	v_div_scale_f32 v7, vcc, v2, v3, v2
	v_mul_f32_e32 v8, v7, v5
	v_fma_f32 v6, -v4, v8, v7
	v_fmac_f32_e32 v8, v6, v5
	v_fma_f32 v4, -v4, v8, v7
	v_div_fmas_f32 v4, v4, v5, v8
	v_div_fixup_f32 v17, v4, v3, v2
	s_waitcnt lgkmcnt(0)
	v_pk_mul_f32 v[42:43], v[42:43], v[10:11]
	v_pk_mul_f32 v[44:45], v[44:45], v[12:13]
	v_pk_mul_f32 v[46:47], v[46:47], v[14:15]
	v_pk_mul_f32 v[48:49], v[48:49], v[16:17]
	ds_write_b128 v50, v[42:45] offset:50720
	ds_write_b128 v50, v[46:49] offset:50736
	ds_read_b128 v[42:45], v50 offset:59168
	ds_read_b128 v[46:49], v50 offset:59184
	s_waitcnt vmcnt(0)
	v_lshlrev_b32_e32 v2, 16, v38
	v_lshlrev_b32_e32 v3, 16, v52
	v_div_scale_f32 v4, s[4:5], v3, v3, v2
	v_rcp_f32_e32 v5, v4
	s_nop 0
	v_fma_f32 v6, -v4, v5, 1.0
	v_fmac_f32_e32 v5, v6, v5
	v_div_scale_f32 v7, vcc, v2, v3, v2
	v_mul_f32_e32 v8, v7, v5
	v_fma_f32 v6, -v4, v8, v7
	v_fmac_f32_e32 v8, v6, v5
	v_fma_f32 v4, -v4, v8, v7
	v_div_fmas_f32 v4, v4, v5, v8
	v_div_fixup_f32 v10, v4, v3, v2
	v_and_b32_e32 v2, 0xffff0000, v38
	v_and_b32_e32 v3, 0xffff0000, v52
	v_div_scale_f32 v4, s[4:5], v3, v3, v2
	v_rcp_f32_e32 v5, v4
	s_nop 0
	v_fma_f32 v6, -v4, v5, 1.0
	v_fmac_f32_e32 v5, v6, v5
	v_div_scale_f32 v7, vcc, v2, v3, v2
	v_mul_f32_e32 v8, v7, v5
	v_fma_f32 v6, -v4, v8, v7
	v_fmac_f32_e32 v8, v6, v5
	v_fma_f32 v4, -v4, v8, v7
	v_div_fmas_f32 v4, v4, v5, v8
	v_div_fixup_f32 v11, v4, v3, v2
	v_lshlrev_b32_e32 v2, 16, v39
	v_lshlrev_b32_e32 v3, 16, v53
	v_div_scale_f32 v4, s[4:5], v3, v3, v2
	v_rcp_f32_e32 v5, v4
	s_nop 0
	v_fma_f32 v6, -v4, v5, 1.0
	v_fmac_f32_e32 v5, v6, v5
	v_div_scale_f32 v7, vcc, v2, v3, v2
	v_mul_f32_e32 v8, v7, v5
	v_fma_f32 v6, -v4, v8, v7
	v_fmac_f32_e32 v8, v6, v5
	v_fma_f32 v4, -v4, v8, v7
	v_div_fmas_f32 v4, v4, v5, v8
	v_div_fixup_f32 v12, v4, v3, v2
	v_and_b32_e32 v2, 0xffff0000, v39
	v_and_b32_e32 v3, 0xffff0000, v53
	v_div_scale_f32 v4, s[4:5], v3, v3, v2
	v_rcp_f32_e32 v5, v4
	s_nop 0
	v_fma_f32 v6, -v4, v5, 1.0
	v_fmac_f32_e32 v5, v6, v5
	v_div_scale_f32 v7, vcc, v2, v3, v2
	v_mul_f32_e32 v8, v7, v5
	v_fma_f32 v6, -v4, v8, v7
	v_fmac_f32_e32 v8, v6, v5
	v_fma_f32 v4, -v4, v8, v7
	v_div_fmas_f32 v4, v4, v5, v8
	v_div_fixup_f32 v13, v4, v3, v2
	v_lshlrev_b32_e32 v2, 16, v40
	v_lshlrev_b32_e32 v3, 16, v54
	v_div_scale_f32 v4, s[4:5], v3, v3, v2
	v_rcp_f32_e32 v5, v4
	s_nop 0
	v_fma_f32 v6, -v4, v5, 1.0
	v_fmac_f32_e32 v5, v6, v5
	v_div_scale_f32 v7, vcc, v2, v3, v2
	v_mul_f32_e32 v8, v7, v5
	v_fma_f32 v6, -v4, v8, v7
	v_fmac_f32_e32 v8, v6, v5
	v_fma_f32 v4, -v4, v8, v7
	v_div_fmas_f32 v4, v4, v5, v8
	v_div_fixup_f32 v14, v4, v3, v2
	v_and_b32_e32 v2, 0xffff0000, v40
	v_and_b32_e32 v3, 0xffff0000, v54
	v_div_scale_f32 v4, s[4:5], v3, v3, v2
	v_rcp_f32_e32 v5, v4
	s_nop 0
	v_fma_f32 v6, -v4, v5, 1.0
	v_fmac_f32_e32 v5, v6, v5
	v_div_scale_f32 v7, vcc, v2, v3, v2
	v_mul_f32_e32 v8, v7, v5
	v_fma_f32 v6, -v4, v8, v7
	v_fmac_f32_e32 v8, v6, v5
	v_fma_f32 v4, -v4, v8, v7
	v_div_fmas_f32 v4, v4, v5, v8
	v_div_fixup_f32 v15, v4, v3, v2
	v_lshlrev_b32_e32 v2, 16, v41
	v_lshlrev_b32_e32 v3, 16, v55
	v_div_scale_f32 v4, s[4:5], v3, v3, v2
	v_rcp_f32_e32 v5, v4
	s_nop 0
	v_fma_f32 v6, -v4, v5, 1.0
	v_fmac_f32_e32 v5, v6, v5
	v_div_scale_f32 v7, vcc, v2, v3, v2
	v_mul_f32_e32 v8, v7, v5
	v_fma_f32 v6, -v4, v8, v7
	v_fmac_f32_e32 v8, v6, v5
	v_fma_f32 v4, -v4, v8, v7
	v_div_fmas_f32 v4, v4, v5, v8
	v_div_fixup_f32 v16, v4, v3, v2
	v_and_b32_e32 v2, 0xffff0000, v41
	v_and_b32_e32 v3, 0xffff0000, v55
	v_div_scale_f32 v4, s[4:5], v3, v3, v2
	v_rcp_f32_e32 v5, v4
	s_nop 0
	v_fma_f32 v6, -v4, v5, 1.0
	v_fmac_f32_e32 v5, v6, v5
	v_div_scale_f32 v7, vcc, v2, v3, v2
	v_mul_f32_e32 v8, v7, v5
	v_fma_f32 v6, -v4, v8, v7
	v_fmac_f32_e32 v8, v6, v5
	v_fma_f32 v4, -v4, v8, v7
	v_div_fmas_f32 v4, v4, v5, v8
	v_div_fixup_f32 v17, v4, v3, v2
	s_waitcnt lgkmcnt(0)
	v_pk_mul_f32 v[42:43], v[42:43], v[10:11]
	v_pk_mul_f32 v[44:45], v[44:45], v[12:13]
	v_pk_mul_f32 v[46:47], v[46:47], v[14:15]
	v_pk_mul_f32 v[48:49], v[48:49], v[16:17]
	ds_write_b128 v50, v[42:45] offset:59168
	ds_write_b128 v50, v[46:49] offset:59184

.Lk_aol1b_loop:
	s_barrier
	s_add_u32 m0, s36, 32768
	v_mfma_f32_16x16x32_bf16 v[26:29], v[116:119], v[152:155], v[26:29]
	ds_read_b128 v[34:37], v100 offset:32
	global_load_lds_dwordx4 v170, s[6:7] offset:0
	v_mfma_f32_16x16x32_bf16 v[90:93], v[116:119], v[156:159], v[90:93]
	ds_read_b128 v[50:53], v168 offset:32
	global_load_lds_dwordx4 v171, s[6:7] offset:1024
	v_mfma_f32_16x16x32_bf16 v[22:25], v[116:119], v[160:163], v[22:25]
	ds_read_b128 v[54:57], v168 offset:2080
	global_load_lds_dwordx4 v172, s[6:7] offset:2048
	v_mfma_f32_16x16x32_bf16 v[86:89], v[116:119], v[164:167], v[86:89]
	ds_read_b128 v[38:41], v100 offset:2080
	global_load_lds_dwordx4 v173, s[6:7] offset:3072
	s_add_u32 m0, s36, 49152
	v_mfma_f32_16x16x32_bf16 v[18:21], v[120:123], v[152:155], v[18:21]
	ds_read_b128 v[58:61], v168 offset:4128
	global_load_lds_dwordx4 v170, s[8:9] offset:0
	v_mfma_f32_16x16x32_bf16 v[82:85], v[120:123], v[156:159], v[82:85]
	ds_read_b128 v[62:65], v168 offset:6176
	global_load_lds_dwordx4 v171, s[8:9] offset:1024
	v_mfma_f32_16x16x32_bf16 v[14:17], v[120:123], v[160:163], v[14:17]
	ds_read_b128 v[42:45], v100 offset:4128
	global_load_lds_dwordx4 v172, s[8:9] offset:2048
	v_mfma_f32_16x16x32_bf16 v[78:81], v[120:123], v[164:167], v[78:81]
	ds_read_b128 v[46:49], v100 offset:6176
	global_load_lds_dwordx4 v173, s[8:9] offset:3072
	v_mfma_f32_16x16x32_bf16 v[10:13], v[124:127], v[152:155], v[10:13]
	v_mfma_f32_16x16x32_bf16 v[74:77], v[124:127], v[156:159], v[74:77]
	v_mfma_f32_16x16x32_bf16 v[6:9], v[124:127], v[160:163], v[6:9]
	v_mfma_f32_16x16x32_bf16 v[70:73], v[124:127], v[164:167], v[70:73]
	v_mfma_f32_16x16x32_bf16 v[2:5], v[148:151], v[152:155], v[2:5]
	v_mfma_f32_16x16x32_bf16 v[66:69], v[148:151], v[156:159], v[66:69]
	v_mfma_f32_16x16x32_bf16 v[30:33], v[148:151], v[160:163], v[30:33]
	v_mfma_f32_16x16x32_bf16 v[94:97], v[148:151], v[164:167], v[94:97]
	s_add_u32 s98, s98, 1
	s_and_b32 s98, s98, 15
	s_cmp_eq_u32 s98, 0
	s_cselect_b32 s99, 0x800, 0
	s_add_u32 s6, s6, 0x80
	s_addc_u32 s7, s7, 0
	s_sub_u32 s6, s6, s99
	s_subb_u32 s7, s7, 0
	s_add_u32 s8, s8, 0x80
	s_addc_u32 s9, s9, 0
	s_sub_u32 s8, s8, s99
	s_subb_u32 s9, s9, 0
	s_waitcnt lgkmcnt(0)
	v_mfma_f32_16x16x32_bf16 v[26:29], v[34:37], v[50:53], v[26:29]
	ds_read_b128 v[116:119], v111 offset:32
	v_mfma_f32_16x16x32_bf16 v[90:93], v[34:37], v[54:57], v[90:93]
	ds_read_b128 v[152:155], v169 offset:32
	v_mfma_f32_16x16x32_bf16 v[22:25], v[34:37], v[58:61], v[22:25]
	ds_read_b128 v[156:159], v169 offset:2080
	v_mfma_f32_16x16x32_bf16 v[86:89], v[34:37], v[62:65], v[86:89]
	ds_read_b128 v[120:123], v111 offset:2080
	v_mfma_f32_16x16x32_bf16 v[18:21], v[38:41], v[50:53], v[18:21]
	ds_read_b128 v[160:163], v169 offset:4128
	v_mfma_f32_16x16x32_bf16 v[82:85], v[38:41], v[54:57], v[82:85]
	ds_read_b128 v[164:167], v169 offset:6176
	v_mfma_f32_16x16x32_bf16 v[14:17], v[38:41], v[58:61], v[14:17]
	ds_read_b128 v[124:127], v111 offset:4128
	v_mfma_f32_16x16x32_bf16 v[78:81], v[38:41], v[62:65], v[78:81]
	ds_read_b128 v[148:151], v111 offset:6176
	v_mfma_f32_16x16x32_bf16 v[10:13], v[42:45], v[50:53], v[10:13]
	v_mfma_f32_16x16x32_bf16 v[74:77], v[42:45], v[54:57], v[74:77]
	v_mfma_f32_16x16x32_bf16 v[6:9], v[42:45], v[58:61], v[6:9]
	v_mfma_f32_16x16x32_bf16 v[70:73], v[42:45], v[62:65], v[70:73]
	v_mfma_f32_16x16x32_bf16 v[2:5], v[46:49], v[50:53], v[2:5]
	v_mfma_f32_16x16x32_bf16 v[66:69], v[46:49], v[54:57], v[66:69]
	v_mfma_f32_16x16x32_bf16 v[30:33], v[46:49], v[58:61], v[30:33]
	v_mfma_f32_16x16x32_bf16 v[94:97], v[46:49], v[62:65], v[94:97]
	s_waitcnt lgkmcnt(0)
	s_waitcnt vmcnt(0)
	s_barrier
	s_add_u32 m0, s36, 0
	v_mfma_f32_16x16x32_bf16 v[26:29], v[116:119], v[152:155], v[26:29]
	ds_read_b128 v[34:37], v100 offset:32800
	global_load_lds_dwordx4 v170, s[6:7] offset:0
	v_mfma_f32_16x16x32_bf16 v[90:93], v[116:119], v[156:159], v[90:93]
	ds_read_b128 v[50:53], v168 offset:32800
	global_load_lds_dwordx4 v171, s[6:7] offset:1024
	v_mfma_f32_16x16x32_bf16 v[22:25], v[116:119], v[160:163], v[22:25]
	ds_read_b128 v[54:57], v168 offset:34848
	global_load_lds_dwordx4 v172, s[6:7] offset:2048
	v_mfma_f32_16x16x32_bf16 v[86:89], v[116:119], v[164:167], v[86:89]
	ds_read_b128 v[38:41], v100 offset:34848
	global_load_lds_dwordx4 v173, s[6:7] offset:3072
	s_add_u32 m0, s36, 16384
	v_mfma_f32_16x16x32_bf16 v[18:21], v[120:123], v[152:155], v[18:21]
	ds_read_b128 v[58:61], v168 offset:36896
	global_load_lds_dwordx4 v170, s[8:9] offset:0
	v_mfma_f32_16x16x32_bf16 v[82:85], v[120:123], v[156:159], v[82:85]
	ds_read_b128 v[62:65], v168 offset:38944
	global_load_lds_dwordx4 v171, s[8:9] offset:1024
	v_mfma_f32_16x16x32_bf16 v[14:17], v[120:123], v[160:163], v[14:17]
	ds_read_b128 v[42:45], v100 offset:36896
	global_load_lds_dwordx4 v172, s[8:9] offset:2048
	v_mfma_f32_16x16x32_bf16 v[78:81], v[120:123], v[164:167], v[78:81]
	ds_read_b128 v[46:49], v100 offset:38944
	global_load_lds_dwordx4 v173, s[8:9] offset:3072
	v_mfma_f32_16x16x32_bf16 v[10:13], v[124:127], v[152:155], v[10:13]
	v_mfma_f32_16x16x32_bf16 v[74:77], v[124:127], v[156:159], v[74:77]
	v_mfma_f32_16x16x32_bf16 v[6:9], v[124:127], v[160:163], v[6:9]
	v_mfma_f32_16x16x32_bf16 v[70:73], v[124:127], v[164:167], v[70:73]
	v_mfma_f32_16x16x32_bf16 v[2:5], v[148:151], v[152:155], v[2:5]
	v_mfma_f32_16x16x32_bf16 v[66:69], v[148:151], v[156:159], v[66:69]
	v_mfma_f32_16x16x32_bf16 v[30:33], v[148:151], v[160:163], v[30:33]
	v_mfma_f32_16x16x32_bf16 v[94:97], v[148:151], v[164:167], v[94:97]
	s_add_u32 s98, s98, 1
	s_and_b32 s98, s98, 15
	s_cmp_eq_u32 s98, 0
	s_cselect_b32 s99, 0x800, 0
	s_add_u32 s6, s6, 0x80
	s_addc_u32 s7, s7, 0
	s_sub_u32 s6, s6, s99
	s_subb_u32 s7, s7, 0
	s_add_u32 s8, s8, 0x80
	s_addc_u32 s9, s9, 0
	s_sub_u32 s8, s8, s99
	s_subb_u32 s9, s9, 0
	s_waitcnt lgkmcnt(0)
	v_mfma_f32_16x16x32_bf16 v[26:29], v[34:37], v[50:53], v[26:29]
	ds_read_b128 v[116:119], v111 offset:32800
	v_mfma_f32_16x16x32_bf16 v[90:93], v[34:37], v[54:57], v[90:93]
	ds_read_b128 v[152:155], v169 offset:32800
	v_mfma_f32_16x16x32_bf16 v[22:25], v[34:37], v[58:61], v[22:25]
	ds_read_b128 v[156:159], v169 offset:34848
	v_mfma_f32_16x16x32_bf16 v[86:89], v[34:37], v[62:65], v[86:89]
	ds_read_b128 v[120:123], v111 offset:34848
	v_mfma_f32_16x16x32_bf16 v[18:21], v[38:41], v[50:53], v[18:21]
	ds_read_b128 v[160:163], v169 offset:36896
	v_mfma_f32_16x16x32_bf16 v[82:85], v[38:41], v[54:57], v[82:85]
	ds_read_b128 v[164:167], v169 offset:38944
	v_mfma_f32_16x16x32_bf16 v[14:17], v[38:41], v[58:61], v[14:17]
	ds_read_b128 v[124:127], v111 offset:36896
	v_mfma_f32_16x16x32_bf16 v[78:81], v[38:41], v[62:65], v[78:81]
	ds_read_b128 v[148:151], v111 offset:38944
	v_mfma_f32_16x16x32_bf16 v[10:13], v[42:45], v[50:53], v[10:13]
	v_mfma_f32_16x16x32_bf16 v[74:77], v[42:45], v[54:57], v[74:77]
	v_mfma_f32_16x16x32_bf16 v[6:9], v[42:45], v[58:61], v[6:9]
	v_mfma_f32_16x16x32_bf16 v[70:73], v[42:45], v[62:65], v[70:73]
	v_mfma_f32_16x16x32_bf16 v[2:5], v[46:49], v[50:53], v[2:5]
	v_mfma_f32_16x16x32_bf16 v[66:69], v[46:49], v[54:57], v[66:69]
	v_mfma_f32_16x16x32_bf16 v[30:33], v[46:49], v[58:61], v[30:33]
	v_mfma_f32_16x16x32_bf16 v[94:97], v[46:49], v[62:65], v[94:97]
	s_waitcnt lgkmcnt(0)
	s_waitcnt vmcnt(0)
	s_add_u32 s5, s5, 1
	s_cmp_lt_u32 s5, 7
	s_cbranch_scc1 .Lk_aol1b_loop
	s_barrier
	s_add_u32 m0, s36, 32768
	v_mfma_f32_16x16x32_bf16 v[26:29], v[116:119], v[152:155], v[26:29]
	ds_read_b128 v[34:37], v100 offset:32
	global_load_lds_dwordx4 v170, s[6:7] offset:0
	v_mfma_f32_16x16x32_bf16 v[90:93], v[116:119], v[156:159], v[90:93]
	ds_read_b128 v[50:53], v168 offset:32
	global_load_lds_dwordx4 v171, s[6:7] offset:1024
	v_mfma_f32_16x16x32_bf16 v[22:25], v[116:119], v[160:163], v[22:25]
	ds_read_b128 v[54:57], v168 offset:2080
	global_load_lds_dwordx4 v172, s[6:7] offset:2048
	v_mfma_f32_16x16x32_bf16 v[86:89], v[116:119], v[164:167], v[86:89]
	ds_read_b128 v[38:41], v100 offset:2080
	global_load_lds_dwordx4 v173, s[6:7] offset:3072
	s_add_u32 m0, s36, 49152
	v_mfma_f32_16x16x32_bf16 v[18:21], v[120:123], v[152:155], v[18:21]
	ds_read_b128 v[58:61], v168 offset:4128
	global_load_lds_dwordx4 v170, s[8:9] offset:0
	v_mfma_f32_16x16x32_bf16 v[82:85], v[120:123], v[156:159], v[82:85]
	ds_read_b128 v[62:65], v168 offset:6176
	global_load_lds_dwordx4 v171, s[8:9] offset:1024
	v_mfma_f32_16x16x32_bf16 v[14:17], v[120:123], v[160:163], v[14:17]
	ds_read_b128 v[42:45], v100 offset:4128
	global_load_lds_dwordx4 v172, s[8:9] offset:2048
	v_mfma_f32_16x16x32_bf16 v[78:81], v[120:123], v[164:167], v[78:81]
	ds_read_b128 v[46:49], v100 offset:6176
	global_load_lds_dwordx4 v173, s[8:9] offset:3072
	v_mfma_f32_16x16x32_bf16 v[10:13], v[124:127], v[152:155], v[10:13]
	v_mfma_f32_16x16x32_bf16 v[74:77], v[124:127], v[156:159], v[74:77]
	v_mfma_f32_16x16x32_bf16 v[6:9], v[124:127], v[160:163], v[6:9]
	v_mfma_f32_16x16x32_bf16 v[70:73], v[124:127], v[164:167], v[70:73]
	v_mfma_f32_16x16x32_bf16 v[2:5], v[148:151], v[152:155], v[2:5]
	v_mfma_f32_16x16x32_bf16 v[66:69], v[148:151], v[156:159], v[66:69]
	v_mfma_f32_16x16x32_bf16 v[30:33], v[148:151], v[160:163], v[30:33]
	v_mfma_f32_16x16x32_bf16 v[94:97], v[148:151], v[164:167], v[94:97]
	s_add_u32 s98, s98, 1
	s_and_b32 s98, s98, 15
	s_cmp_eq_u32 s98, 0
	s_cselect_b32 s99, 0x800, 0
	s_add_u32 s6, s6, 0x80
	s_addc_u32 s7, s7, 0
	s_sub_u32 s6, s6, s99
	s_subb_u32 s7, s7, 0
	s_add_u32 s8, s8, 0x80
	s_addc_u32 s9, s9, 0
	s_sub_u32 s8, s8, s99
	s_subb_u32 s9, s9, 0
	s_waitcnt lgkmcnt(0)
	v_mfma_f32_16x16x32_bf16 v[26:29], v[34:37], v[50:53], v[26:29]
	ds_read_b128 v[116:119], v111 offset:32
	v_mfma_f32_16x16x32_bf16 v[90:93], v[34:37], v[54:57], v[90:93]
	ds_read_b128 v[152:155], v169 offset:32
	v_mfma_f32_16x16x32_bf16 v[22:25], v[34:37], v[58:61], v[22:25]
	ds_read_b128 v[156:159], v169 offset:2080
	v_mfma_f32_16x16x32_bf16 v[86:89], v[34:37], v[62:65], v[86:89]
	ds_read_b128 v[120:123], v111 offset:2080
	v_mfma_f32_16x16x32_bf16 v[18:21], v[38:41], v[50:53], v[18:21]
	ds_read_b128 v[160:163], v169 offset:4128
	v_mfma_f32_16x16x32_bf16 v[82:85], v[38:41], v[54:57], v[82:85]
	ds_read_b128 v[164:167], v169 offset:6176
	v_mfma_f32_16x16x32_bf16 v[14:17], v[38:41], v[58:61], v[14:17]
	ds_read_b128 v[124:127], v111 offset:4128
	v_mfma_f32_16x16x32_bf16 v[78:81], v[38:41], v[62:65], v[78:81]
	ds_read_b128 v[148:151], v111 offset:6176
	v_mfma_f32_16x16x32_bf16 v[10:13], v[42:45], v[50:53], v[10:13]
	v_mfma_f32_16x16x32_bf16 v[74:77], v[42:45], v[54:57], v[74:77]
	v_mfma_f32_16x16x32_bf16 v[6:9], v[42:45], v[58:61], v[6:9]
	v_mfma_f32_16x16x32_bf16 v[70:73], v[42:45], v[62:65], v[70:73]
	v_mfma_f32_16x16x32_bf16 v[2:5], v[46:49], v[50:53], v[2:5]
	v_mfma_f32_16x16x32_bf16 v[66:69], v[46:49], v[54:57], v[66:69]
	v_mfma_f32_16x16x32_bf16 v[30:33], v[46:49], v[58:61], v[30:33]
	v_mfma_f32_16x16x32_bf16 v[94:97], v[46:49], v[62:65], v[94:97]
	s_waitcnt lgkmcnt(0)
	s_waitcnt vmcnt(0)
	s_barrier
	v_mfma_f32_16x16x32_bf16 v[26:29], v[116:119], v[152:155], v[26:29]
	ds_read_b128 v[34:37], v100 offset:32800
	v_mfma_f32_16x16x32_bf16 v[90:93], v[116:119], v[156:159], v[90:93]
	ds_read_b128 v[50:53], v168 offset:32800
	v_mfma_f32_16x16x32_bf16 v[22:25], v[116:119], v[160:163], v[22:25]
	ds_read_b128 v[54:57], v168 offset:34848
	v_mfma_f32_16x16x32_bf16 v[86:89], v[116:119], v[164:167], v[86:89]
	ds_read_b128 v[38:41], v100 offset:34848
	v_mfma_f32_16x16x32_bf16 v[18:21], v[120:123], v[152:155], v[18:21]
	ds_read_b128 v[58:61], v168 offset:36896
	v_mfma_f32_16x16x32_bf16 v[82:85], v[120:123], v[156:159], v[82:85]
	ds_read_b128 v[62:65], v168 offset:38944
	v_mfma_f32_16x16x32_bf16 v[14:17], v[120:123], v[160:163], v[14:17]
	ds_read_b128 v[42:45], v100 offset:36896
	v_mfma_f32_16x16x32_bf16 v[78:81], v[120:123], v[164:167], v[78:81]
	ds_read_b128 v[46:49], v100 offset:38944
	v_mfma_f32_16x16x32_bf16 v[10:13], v[124:127], v[152:155], v[10:13]
	v_mfma_f32_16x16x32_bf16 v[74:77], v[124:127], v[156:159], v[74:77]
	v_mfma_f32_16x16x32_bf16 v[6:9], v[124:127], v[160:163], v[6:9]
	v_mfma_f32_16x16x32_bf16 v[70:73], v[124:127], v[164:167], v[70:73]
	v_mfma_f32_16x16x32_bf16 v[2:5], v[148:151], v[152:155], v[2:5]
	v_mfma_f32_16x16x32_bf16 v[66:69], v[148:151], v[156:159], v[66:69]
	v_mfma_f32_16x16x32_bf16 v[30:33], v[148:151], v[160:163], v[30:33]
	v_mfma_f32_16x16x32_bf16 v[94:97], v[148:151], v[164:167], v[94:97]
	s_waitcnt lgkmcnt(0)
	v_mfma_f32_16x16x32_bf16 v[26:29], v[34:37], v[50:53], v[26:29]
	ds_read_b128 v[116:119], v111 offset:32800
	v_mfma_f32_16x16x32_bf16 v[90:93], v[34:37], v[54:57], v[90:93]
	ds_read_b128 v[152:155], v169 offset:32800
	v_mfma_f32_16x16x32_bf16 v[22:25], v[34:37], v[58:61], v[22:25]
	ds_read_b128 v[156:159], v169 offset:34848
	v_mfma_f32_16x16x32_bf16 v[86:89], v[34:37], v[62:65], v[86:89]
	ds_read_b128 v[120:123], v111 offset:34848
	v_mfma_f32_16x16x32_bf16 v[18:21], v[38:41], v[50:53], v[18:21]
	ds_read_b128 v[160:163], v169 offset:36896
	v_mfma_f32_16x16x32_bf16 v[82:85], v[38:41], v[54:57], v[82:85]
	ds_read_b128 v[164:167], v169 offset:38944
	v_mfma_f32_16x16x32_bf16 v[14:17], v[38:41], v[58:61], v[14:17]
	ds_read_b128 v[124:127], v111 offset:36896
	v_mfma_f32_16x16x32_bf16 v[78:81], v[38:41], v[62:65], v[78:81]
	ds_read_b128 v[148:151], v111 offset:38944
	v_mfma_f32_16x16x32_bf16 v[10:13], v[42:45], v[50:53], v[10:13]
	v_mfma_f32_16x16x32_bf16 v[74:77], v[42:45], v[54:57], v[74:77]
	v_mfma_f32_16x16x32_bf16 v[6:9], v[42:45], v[58:61], v[6:9]
	v_mfma_f32_16x16x32_bf16 v[70:73], v[42:45], v[62:65], v[70:73]
	v_mfma_f32_16x16x32_bf16 v[2:5], v[46:49], v[50:53], v[2:5]
	v_mfma_f32_16x16x32_bf16 v[66:69], v[46:49], v[54:57], v[66:69]
	v_mfma_f32_16x16x32_bf16 v[30:33], v[46:49], v[58:61], v[30:33]
	v_mfma_f32_16x16x32_bf16 v[94:97], v[46:49], v[62:65], v[94:97]
	s_waitcnt lgkmcnt(0)
	v_mfma_f32_16x16x32_bf16 v[26:29], v[116:119], v[152:155], v[26:29]
	v_mfma_f32_16x16x32_bf16 v[90:93], v[116:119], v[156:159], v[90:93]
	v_mfma_f32_16x16x32_bf16 v[22:25], v[116:119], v[160:163], v[22:25]
	v_mfma_f32_16x16x32_bf16 v[86:89], v[116:119], v[164:167], v[86:89]
	v_mfma_f32_16x16x32_bf16 v[18:21], v[120:123], v[152:155], v[18:21]
	v_mfma_f32_16x16x32_bf16 v[82:85], v[120:123], v[156:159], v[82:85]
	v_mfma_f32_16x16x32_bf16 v[14:17], v[120:123], v[160:163], v[14:17]
	v_mfma_f32_16x16x32_bf16 v[78:81], v[120:123], v[164:167], v[78:81]
	v_mfma_f32_16x16x32_bf16 v[10:13], v[124:127], v[152:155], v[10:13]
	v_mfma_f32_16x16x32_bf16 v[74:77], v[124:127], v[156:159], v[74:77]
	v_mfma_f32_16x16x32_bf16 v[6:9], v[124:127], v[160:163], v[6:9]
	v_mfma_f32_16x16x32_bf16 v[70:73], v[124:127], v[164:167], v[70:73]
	v_mfma_f32_16x16x32_bf16 v[2:5], v[148:151], v[152:155], v[2:5]
	v_mfma_f32_16x16x32_bf16 v[66:69], v[148:151], v[156:159], v[66:69]
	v_mfma_f32_16x16x32_bf16 v[30:33], v[148:151], v[160:163], v[30:33]
	v_mfma_f32_16x16x32_bf16 v[94:97], v[148:151], v[164:167], v[94:97]
	s_lshr_b32 s101, s71, 10
	v_lshrrev_b32_e32 v117, 4, v0
	v_and_b32_e32 v117, 15, v117
	v_and_b32_e32 v118, 15, v0
	v_lshlrev_b32_e32 v118, 4, v118
	v_lshl_or_b32 v117, v117, 12, v118
	s_lshl_b32 s100, s101, 12
	s_lshl_b32 s98, s73, 8
	s_add_u32 s100, s100, s98
	s_add_u32 s98, s42, s100
	s_addc_u32 s99, s43, 0
	s_add_u32 s98, s98, 0x12d24800
	s_addc_u32 s99, s99, 0
	global_load_dwordx4 v[148:151], v117, s[98:99]
	s_add_u32 s98, s98, 0x10000
	s_addc_u32 s99, s99, 0
	global_load_dwordx4 v[152:155], v117, s[98:99]
	s_add_u32 s98, s98, 0x10000
	s_addc_u32 s99, s99, 0
	global_load_dwordx4 v[156:159], v117, s[98:99]
	s_add_u32 s98, s98, 0x10000
	s_addc_u32 s99, s99, 0
	global_load_dwordx4 v[160:163], v117, s[98:99]
	s_add_u32 s98, s98, 0x10000
	s_addc_u32 s99, s99, 0
	global_load_dwordx4 v[164:167], v117, s[98:99]
	s_add_u32 s98, s98, 0x10000
	s_addc_u32 s99, s99, 0
	global_load_dwordx4 v[168:171], v117, s[98:99]
	s_add_u32 s98, s98, 0x10000
	s_addc_u32 s99, s99, 0
	global_load_dwordx4 v[172:175], v117, s[98:99]
	s_add_u32 s98, s98, 0x10000
	s_addc_u32 s99, s99, 0
	global_load_dwordx4 v[176:179], v117, s[98:99]
	s_lshl_b32 s36, s4, 1
	s_lshl_b32 s4, s70, 10
	s_mul_hi_u32 s5, s70, 0x15555556
	s_barrier
	ds_write2_b32 v129, v26, v90 offset1:16
	ds_write2_b32 v129, v27, v91 offset0:132 offset1:148
	ds_write2_b32 v138, v28, v92 offset0:8 offset1:24
	ds_write2_b32 v138, v29, v93 offset0:140 offset1:156
	ds_write2_b32 v129, v22, v86 offset0:32 offset1:48
	ds_write2_b32 v129, v23, v87 offset0:164 offset1:180
	ds_write2_b32 v138, v24, v88 offset0:40 offset1:56
	ds_write2_b32 v138, v25, v89 offset0:172 offset1:188
	ds_write2_b32 v139, v18, v82 offset0:64 offset1:80
	ds_write2_b32 v139, v19, v83 offset0:196 offset1:212
	ds_write2_b32 v140, v20, v84 offset0:72 offset1:88
	ds_write2_b32 v140, v21, v85 offset0:204 offset1:220
	ds_write2_b32 v139, v14, v78 offset0:96 offset1:112
	ds_write2_b32 v139, v15, v79 offset0:228 offset1:244
	ds_write2_b32 v140, v16, v80 offset0:104 offset1:120
	ds_write2_b32 v140, v17, v81 offset0:236 offset1:252
	ds_write2_b32 v141, v10, v74 offset0:128 offset1:144
	ds_write2_b32 v142, v11, v75 offset0:4 offset1:20
	ds_write2_b32 v142, v12, v76 offset0:136 offset1:152
	ds_write2_b32 v143, v13, v77 offset0:12 offset1:28
	ds_write2_b32 v141, v6, v70 offset0:160 offset1:176
	ds_write2_b32 v142, v7, v71 offset0:36 offset1:52
	ds_write2_b32 v142, v8, v72 offset0:168 offset1:184
	ds_write2_b32 v143, v9, v73 offset0:44 offset1:60
	ds_write2_b32 v144, v2, v66 offset0:192 offset1:208
	ds_write2_b32 v145, v3, v67 offset0:68 offset1:84
	ds_write2_b32 v145, v4, v68 offset0:200 offset1:216
	ds_write2_b32 v146, v5, v69 offset0:76 offset1:92
	ds_write2_b32 v144, v30, v94 offset0:224 offset1:240
	ds_write2_b32 v145, v31, v95 offset0:100 offset1:116
	ds_write2_b32 v145, v32, v96 offset0:232 offset1:248
	ds_write2_b32 v146, v33, v97 offset0:108 offset1:124
	v_or_b32_e32 v4, s4, v134
	s_mulk_i32 s5, 0x3000
	v_or_b32_e32 v5, s4, v132
	v_lshl_add_u64 v[2:3], v[106:107], 0, s[36:37]
	v_subrev_u32_e32 v4, s5, v4
	v_subrev_u32_e32 v100, s5, v5
	s_mov_b32 s4, 0
	s_waitcnt lgkmcnt(0)
	s_barrier
	v_lshrrev_b32_e32 v52, 4, v0
	v_and_b32_e32 v52, 15, v52
	v_and_b32_e32 v50, 15, v0
	v_lshlrev_b32_e32 v53, 4, v50
	v_lshl_or_b32 v53, v52, 11, v53
	v_mul_u32_u24_e32 v52, 0x210, v52
	v_lshl_add_u32 v52, v50, 5, v52
	s_lshl_b32 s100, s101, 11
	s_lshl_b32 s98, s73, 8
	s_add_u32 s100, s100, s98
	s_add_u32 s98, s42, s100
	s_addc_u32 s99, s43, 0
	s_add_u32 s98, s98, 0xb724000
	s_addc_u32 s99, s99, 0
	ds_read_b128 v[34:37], v52 offset:32
	ds_read_b128 v[38:41], v52 offset:48
	ds_read_b128 v[42:45], v52 offset:8480
	ds_read_b128 v[46:49], v52 offset:8496
	s_waitcnt vmcnt(7) lgkmcnt(2)
	v_lshlrev_b32_e32 v51, 16, v148
	v_mul_f32_e32 v34, v34, v51
	v_and_b32_e32 v51, 0xffff0000, v148
	v_mul_f32_e32 v35, v35, v51
	v_lshlrev_b32_e32 v51, 16, v149
	v_mul_f32_e32 v36, v36, v51
	v_and_b32_e32 v51, 0xffff0000, v149
	v_mul_f32_e32 v37, v37, v51
	v_lshlrev_b32_e32 v51, 16, v150
	v_mul_f32_e32 v38, v38, v51
	v_and_b32_e32 v51, 0xffff0000, v150
	v_mul_f32_e32 v39, v39, v51
	v_lshlrev_b32_e32 v51, 16, v151
	v_mul_f32_e32 v40, v40, v51
	v_and_b32_e32 v51, 0xffff0000, v151
	v_mul_f32_e32 v41, v41, v51
	v_cvt_pk_bf16_f32 v34, v34, v35
	v_cvt_pk_bf16_f32 v35, v36, v37
	v_cvt_pk_bf16_f32 v36, v38, v39
	v_cvt_pk_bf16_f32 v37, v40, v41
	global_store_dwordx4 v53, v[34:37], s[98:99]
	s_add_u32 s98, s98, 0x8000
	s_addc_u32 s99, s99, 0
	s_nop 1
	ds_read_b128 v[34:37], v52 offset:16928
	ds_read_b128 v[38:41], v52 offset:16944
	s_waitcnt vmcnt(7) lgkmcnt(2)
	v_lshlrev_b32_e32 v51, 16, v152
	v_mul_f32_e32 v42, v42, v51
	v_and_b32_e32 v51, 0xffff0000, v152
	v_mul_f32_e32 v43, v43, v51
	v_lshlrev_b32_e32 v51, 16, v153
	v_mul_f32_e32 v44, v44, v51
	v_and_b32_e32 v51, 0xffff0000, v153
	v_mul_f32_e32 v45, v45, v51
	v_lshlrev_b32_e32 v51, 16, v154
	v_mul_f32_e32 v46, v46, v51
	v_and_b32_e32 v51, 0xffff0000, v154
	v_mul_f32_e32 v47, v47, v51
	v_lshlrev_b32_e32 v51, 16, v155
	v_mul_f32_e32 v48, v48, v51
	v_and_b32_e32 v51, 0xffff0000, v155
	v_mul_f32_e32 v49, v49, v51
	v_cvt_pk_bf16_f32 v42, v42, v43
	v_cvt_pk_bf16_f32 v43, v44, v45
	v_cvt_pk_bf16_f32 v44, v46, v47
	v_cvt_pk_bf16_f32 v45, v48, v49
	global_store_dwordx4 v53, v[42:45], s[98:99]
	s_add_u32 s98, s98, 0x8000
	s_addc_u32 s99, s99, 0
	s_nop 1
	ds_read_b128 v[42:45], v52 offset:25376
	ds_read_b128 v[46:49], v52 offset:25392
	s_waitcnt vmcnt(7) lgkmcnt(2)
	v_lshlrev_b32_e32 v51, 16, v156
	v_mul_f32_e32 v34, v34, v51
	v_and_b32_e32 v51, 0xffff0000, v156
	v_mul_f32_e32 v35, v35, v51
	v_lshlrev_b32_e32 v51, 16, v157
	v_mul_f32_e32 v36, v36, v51
	v_and_b32_e32 v51, 0xffff0000, v157
	v_mul_f32_e32 v37, v37, v51
	v_lshlrev_b32_e32 v51, 16, v158
	v_mul_f32_e32 v38, v38, v51
	v_and_b32_e32 v51, 0xffff0000, v158
	v_mul_f32_e32 v39, v39, v51
	v_lshlrev_b32_e32 v51, 16, v159
	v_mul_f32_e32 v40, v40, v51
	v_and_b32_e32 v51, 0xffff0000, v159
	v_mul_f32_e32 v41, v41, v51
	v_cvt_pk_bf16_f32 v34, v34, v35
	v_cvt_pk_bf16_f32 v35, v36, v37
	v_cvt_pk_bf16_f32 v36, v38, v39
	v_cvt_pk_bf16_f32 v37, v40, v41
	global_store_dwordx4 v53, v[34:37], s[98:99]
	s_add_u32 s98, s98, 0x8000
	s_addc_u32 s99, s99, 0
	s_nop 1
	ds_read_b128 v[34:37], v52 offset:33824
	ds_read_b128 v[38:41], v52 offset:33840
	s_waitcnt vmcnt(7) lgkmcnt(2)
	v_lshlrev_b32_e32 v51, 16, v160
	v_mul_f32_e32 v42, v42, v51
	v_and_b32_e32 v51, 0xffff0000, v160
	v_mul_f32_e32 v43, v43, v51
	v_lshlrev_b32_e32 v51, 16, v161
	v_mul_f32_e32 v44, v44, v51
	v_and_b32_e32 v51, 0xffff0000, v161
	v_mul_f32_e32 v45, v45, v51
	v_lshlrev_b32_e32 v51, 16, v162
	v_mul_f32_e32 v46, v46, v51
	v_and_b32_e32 v51, 0xffff0000, v162
	v_mul_f32_e32 v47, v47, v51
	v_lshlrev_b32_e32 v51, 16, v163
	v_mul_f32_e32 v48, v48, v51
	v_and_b32_e32 v51, 0xffff0000, v163
	v_mul_f32_e32 v49, v49, v51
	v_cvt_pk_bf16_f32 v42, v42, v43
	v_cvt_pk_bf16_f32 v43, v44, v45
	v_cvt_pk_bf16_f32 v44, v46, v47
	v_cvt_pk_bf16_f32 v45, v48, v49
	global_store_dwordx4 v53, v[42:45], s[98:99]
	s_add_u32 s98, s98, 0x8000
	s_addc_u32 s99, s99, 0
	s_nop 1
	ds_read_b128 v[42:45], v52 offset:42272
	ds_read_b128 v[46:49], v52 offset:42288
	s_waitcnt vmcnt(7) lgkmcnt(2)
	v_lshlrev_b32_e32 v51, 16, v164
	v_mul_f32_e32 v34, v34, v51
	v_and_b32_e32 v51, 0xffff0000, v164
	v_mul_f32_e32 v35, v35, v51
	v_lshlrev_b32_e32 v51, 16, v165
	v_mul_f32_e32 v36, v36, v51
	v_and_b32_e32 v51, 0xffff0000, v165
	v_mul_f32_e32 v37, v37, v51
	v_lshlrev_b32_e32 v51, 16, v166
	v_mul_f32_e32 v38, v38, v51
	v_and_b32_e32 v51, 0xffff0000, v166
	v_mul_f32_e32 v39, v39, v51
	v_lshlrev_b32_e32 v51, 16, v167
	v_mul_f32_e32 v40, v40, v51
	v_and_b32_e32 v51, 0xffff0000, v167
	v_mul_f32_e32 v41, v41, v51
	v_cvt_pk_bf16_f32 v34, v34, v35
	v_cvt_pk_bf16_f32 v35, v36, v37
	v_cvt_pk_bf16_f32 v36, v38, v39
	v_cvt_pk_bf16_f32 v37, v40, v41
	global_store_dwordx4 v53, v[34:37], s[98:99]
	s_add_u32 s98, s98, 0x8000
	s_addc_u32 s99, s99, 0
	s_nop 1
	ds_read_b128 v[34:37], v52 offset:50720
	ds_read_b128 v[38:41], v52 offset:50736
	s_waitcnt vmcnt(7) lgkmcnt(2)
	v_lshlrev_b32_e32 v51, 16, v168
	v_mul_f32_e32 v42, v42, v51
	v_and_b32_e32 v51, 0xffff0000, v168
	v_mul_f32_e32 v43, v43, v51
	v_lshlrev_b32_e32 v51, 16, v169
	v_mul_f32_e32 v44, v44, v51
	v_and_b32_e32 v51, 0xffff0000, v169
	v_mul_f32_e32 v45, v45, v51
	v_lshlrev_b32_e32 v51, 16, v170
	v_mul_f32_e32 v46, v46, v51
	v_and_b32_e32 v51, 0xffff0000, v170
	v_mul_f32_e32 v47, v47, v51
	v_lshlrev_b32_e32 v51, 16, v171
	v_mul_f32_e32 v48, v48, v51
	v_and_b32_e32 v51, 0xffff0000, v171
	v_mul_f32_e32 v49, v49, v51
	v_cvt_pk_bf16_f32 v42, v42, v43
	v_cvt_pk_bf16_f32 v43, v44, v45
	v_cvt_pk_bf16_f32 v44, v46, v47
	v_cvt_pk_bf16_f32 v45, v48, v49
	global_store_dwordx4 v53, v[42:45], s[98:99]
	s_add_u32 s98, s98, 0x8000
	s_addc_u32 s99, s99, 0
	s_nop 1
	ds_read_b128 v[42:45], v52 offset:59168
	ds_read_b128 v[46:49], v52 offset:59184
	s_waitcnt vmcnt(7) lgkmcnt(2)
	v_lshlrev_b32_e32 v51, 16, v172
	v_mul_f32_e32 v34, v34, v51
	v_and_b32_e32 v51, 0xffff0000, v172
	v_mul_f32_e32 v35, v35, v51
	v_lshlrev_b32_e32 v51, 16, v173
	v_mul_f32_e32 v36, v36, v51
	v_and_b32_e32 v51, 0xffff0000, v173
	v_mul_f32_e32 v37, v37, v51
	v_lshlrev_b32_e32 v51, 16, v174
	v_mul_f32_e32 v38, v38, v51
	v_and_b32_e32 v51, 0xffff0000, v174
	v_mul_f32_e32 v39, v39, v51
	v_lshlrev_b32_e32 v51, 16, v175
	v_mul_f32_e32 v40, v40, v51
	v_and_b32_e32 v51, 0xffff0000, v175
	v_mul_f32_e32 v41, v41, v51
	v_cvt_pk_bf16_f32 v34, v34, v35
	v_cvt_pk_bf16_f32 v35, v36, v37
	v_cvt_pk_bf16_f32 v36, v38, v39
	v_cvt_pk_bf16_f32 v37, v40, v41
	global_store_dwordx4 v53, v[34:37], s[98:99]
	s_add_u32 s98, s98, 0x8000
	s_addc_u32 s99, s99, 0
	s_waitcnt vmcnt(7) lgkmcnt(0)
	v_lshlrev_b32_e32 v51, 16, v176
	v_mul_f32_e32 v42, v42, v51
	v_and_b32_e32 v51, 0xffff0000, v176
	v_mul_f32_e32 v43, v43, v51
	v_lshlrev_b32_e32 v51, 16, v177
	v_mul_f32_e32 v44, v44, v51
	v_and_b32_e32 v51, 0xffff0000, v177
	v_mul_f32_e32 v45, v45, v51
	v_lshlrev_b32_e32 v51, 16, v178
	v_mul_f32_e32 v46, v46, v51
	v_and_b32_e32 v51, 0xffff0000, v178
	v_mul_f32_e32 v47, v47, v51
	v_lshlrev_b32_e32 v51, 16, v179
	v_mul_f32_e32 v48, v48, v51
	v_and_b32_e32 v51, 0xffff0000, v179
	v_mul_f32_e32 v49, v49, v51
	v_cvt_pk_bf16_f32 v42, v42, v43
	v_cvt_pk_bf16_f32 v43, v44, v45
	v_cvt_pk_bf16_f32 v44, v46, v47
	v_cvt_pk_bf16_f32 v45, v48, v49
	global_store_dwordx4 v53, v[42:45], s[98:99]
	s_add_i32 s69, s69, s62
	s_add_i32 s68, s68, 1
	s_cmpk_gt_u32 s69, 0x5f
	s_cbranch_scc0 .LBB0_1292
	v_readlane_b32 s70, v255, 18
	v_readlane_b32 s71, v255, 19
	v_readlane_b32 s66, v255, 16
	v_readlane_b32 s67, v255, 17

.Lcv_cv3_top:
	v_add_co_u32_e32 v96, vcc, 0x700, v2
	s_nop 1
	v_addc_co_u32_e32 v97, vcc, 0, v3, vcc
	v_cmp_gt_u64_e32 vcc, s[4:5], v[96:97]
	s_cmp_eq_u64 vcc, exec
	s_cbranch_scc0 .Lcv_cv3_exit
	v_lshlrev_b32_e32 v80, 5, v2
	v_lshlrev_b32_e32 v88, 3, v2
	v_add_u32_e32 v81, 0x2000, v80
	v_add_u32_e32 v89, 0x800, v88
	v_add_u32_e32 v82, 0x4000, v80
	v_add_u32_e32 v90, 0x1000, v88
	v_add_u32_e32 v83, 0x6000, v80
	v_add_u32_e32 v91, 0x1800, v88
	v_add_u32_e32 v84, 0x8000, v80
	v_add_u32_e32 v92, 0x2000, v88
	v_add_u32_e32 v85, 0xa000, v80
	v_add_u32_e32 v93, 0x2800, v88
	v_add_u32_e32 v86, 0xc000, v80
	v_add_u32_e32 v94, 0x3000, v88
	v_add_u32_e32 v87, 0xe000, v80
	v_add_u32_e32 v95, 0x3800, v88
	global_load_dwordx4 v[16:19], v80, s[8:9] nt
	global_load_dwordx4 v[20:23], v80, s[8:9] offset:16 nt
	global_load_dwordx4 v[24:27], v81, s[8:9] nt
	global_load_dwordx4 v[28:31], v81, s[8:9] offset:16 nt
	global_load_dwordx4 v[32:35], v82, s[8:9] nt
	global_load_dwordx4 v[36:39], v82, s[8:9] offset:16 nt
	global_load_dwordx4 v[40:43], v83, s[8:9] nt
	global_load_dwordx4 v[44:47], v83, s[8:9] offset:16 nt
	global_load_dwordx4 v[48:51], v84, s[8:9] nt
	global_load_dwordx4 v[52:55], v84, s[8:9] offset:16 nt
	global_load_dwordx4 v[56:59], v85, s[8:9] nt
	global_load_dwordx4 v[60:63], v85, s[8:9] offset:16 nt
	global_load_dwordx4 v[64:67], v86, s[8:9] nt
	global_load_dwordx4 v[68:71], v86, s[8:9] offset:16 nt
	global_load_dwordx4 v[72:75], v87, s[8:9] nt
	global_load_dwordx4 v[76:79], v87, s[8:9] offset:16 nt
	v_add_co_u32_e32 v2, vcc, 0x800, v2
	s_nop 1
	v_addc_co_u32_e32 v3, vcc, 0, v3, vcc
	s_waitcnt vmcnt(14)
	v_mul_f32_e32 v116, 0x41800000, v16
	v_mul_f32_e32 v117, 0x41800000, v17
	v_mul_f32_e32 v118, 0x41800000, v18
	v_mul_f32_e32 v119, 0x41800000, v19
	v_mul_f32_e32 v120, 0x41800000, v20
	v_mul_f32_e32 v121, 0x41800000, v21
	v_mul_f32_e32 v122, 0x41800000, v22
	v_mul_f32_e32 v123, 0x41800000, v23
	v_cvt_pk_fp8_f32 v100, v116, v117
	v_cvt_pk_fp8_f32 v101, v120, v121
	v_cvt_pk_fp8_f32 v100, v118, v119 op_sel:[0,0,1]
	v_cvt_pk_fp8_f32 v101, v122, v123 op_sel:[0,0,1]
	global_store_dwordx2 v88, v[100:101], s[10:11]
	s_waitcnt vmcnt(13)
	v_mul_f32_e32 v116, 0x41800000, v24
	v_mul_f32_e32 v117, 0x41800000, v25
	v_mul_f32_e32 v118, 0x41800000, v26
	v_mul_f32_e32 v119, 0x41800000, v27
	v_mul_f32_e32 v120, 0x41800000, v28
	v_mul_f32_e32 v121, 0x41800000, v29
	v_mul_f32_e32 v122, 0x41800000, v30
	v_mul_f32_e32 v123, 0x41800000, v31
	v_cvt_pk_fp8_f32 v102, v116, v117
	v_cvt_pk_fp8_f32 v103, v120, v121
	v_cvt_pk_fp8_f32 v102, v118, v119 op_sel:[0,0,1]
	v_cvt_pk_fp8_f32 v103, v122, v123 op_sel:[0,0,1]
	global_store_dwordx2 v89, v[102:103], s[10:11]
	s_waitcnt vmcnt(12)
	v_mul_f32_e32 v116, 0x41800000, v32
	v_mul_f32_e32 v117, 0x41800000, v33
	v_mul_f32_e32 v118, 0x41800000, v34
	v_mul_f32_e32 v119, 0x41800000, v35
	v_mul_f32_e32 v120, 0x41800000, v36
	v_mul_f32_e32 v121, 0x41800000, v37
	v_mul_f32_e32 v122, 0x41800000, v38
	v_mul_f32_e32 v123, 0x41800000, v39
	v_cvt_pk_fp8_f32 v104, v116, v117
	v_cvt_pk_fp8_f32 v105, v120, v121
	v_cvt_pk_fp8_f32 v104, v118, v119 op_sel:[0,0,1]
	v_cvt_pk_fp8_f32 v105, v122, v123 op_sel:[0,0,1]
	global_store_dwordx2 v90, v[104:105], s[10:11]
	s_waitcnt vmcnt(11)
	v_mul_f32_e32 v116, 0x41800000, v40
	v_mul_f32_e32 v117, 0x41800000, v41
	v_mul_f32_e32 v118, 0x41800000, v42
	v_mul_f32_e32 v119, 0x41800000, v43
	v_mul_f32_e32 v120, 0x41800000, v44
	v_mul_f32_e32 v121, 0x41800000, v45
	v_mul_f32_e32 v122, 0x41800000, v46
	v_mul_f32_e32 v123, 0x41800000, v47
	v_cvt_pk_fp8_f32 v106, v116, v117
	v_cvt_pk_fp8_f32 v107, v120, v121
	v_cvt_pk_fp8_f32 v106, v118, v119 op_sel:[0,0,1]
	v_cvt_pk_fp8_f32 v107, v122, v123 op_sel:[0,0,1]
	global_store_dwordx2 v91, v[106:107], s[10:11]
	s_waitcnt vmcnt(10)
	v_mul_f32_e32 v116, 0x41800000, v48
	v_mul_f32_e32 v117, 0x41800000, v49
	v_mul_f32_e32 v118, 0x41800000, v50
	v_mul_f32_e32 v119, 0x41800000, v51
	v_mul_f32_e32 v120, 0x41800000, v52
	v_mul_f32_e32 v121, 0x41800000, v53
	v_mul_f32_e32 v122, 0x41800000, v54
	v_mul_f32_e32 v123, 0x41800000, v55
	v_cvt_pk_fp8_f32 v108, v116, v117
	v_cvt_pk_fp8_f32 v109, v120, v121
	v_cvt_pk_fp8_f32 v108, v118, v119 op_sel:[0,0,1]
	v_cvt_pk_fp8_f32 v109, v122, v123 op_sel:[0,0,1]
	global_store_dwordx2 v92, v[108:109], s[10:11]
	s_waitcnt vmcnt(9)
	v_mul_f32_e32 v116, 0x41800000, v56
	v_mul_f32_e32 v117, 0x41800000, v57
	v_mul_f32_e32 v118, 0x41800000, v58
	v_mul_f32_e32 v119, 0x41800000, v59
	v_mul_f32_e32 v120, 0x41800000, v60
	v_mul_f32_e32 v121, 0x41800000, v61
	v_mul_f32_e32 v122, 0x41800000, v62
	v_mul_f32_e32 v123, 0x41800000, v63
	v_cvt_pk_fp8_f32 v110, v116, v117
	v_cvt_pk_fp8_f32 v111, v120, v121
	v_cvt_pk_fp8_f32 v110, v118, v119 op_sel:[0,0,1]
	v_cvt_pk_fp8_f32 v111, v122, v123 op_sel:[0,0,1]
	global_store_dwordx2 v93, v[110:111], s[10:11]
	s_waitcnt vmcnt(8)
	v_mul_f32_e32 v116, 0x41800000, v64
	v_mul_f32_e32 v117, 0x41800000, v65
	v_mul_f32_e32 v118, 0x41800000, v66
	v_mul_f32_e32 v119, 0x41800000, v67
	v_mul_f32_e32 v120, 0x41800000, v68
	v_mul_f32_e32 v121, 0x41800000, v69
	v_mul_f32_e32 v122, 0x41800000, v70
	v_mul_f32_e32 v123, 0x41800000, v71
	v_cvt_pk_fp8_f32 v112, v116, v117
	v_cvt_pk_fp8_f32 v113, v120, v121
	v_cvt_pk_fp8_f32 v112, v118, v119 op_sel:[0,0,1]
	v_cvt_pk_fp8_f32 v113, v122, v123 op_sel:[0,0,1]
	global_store_dwordx2 v94, v[112:113], s[10:11]
	s_waitcnt vmcnt(7)
	v_mul_f32_e32 v116, 0x41800000, v72
	v_mul_f32_e32 v117, 0x41800000, v73
	v_mul_f32_e32 v118, 0x41800000, v74
	v_mul_f32_e32 v119, 0x41800000, v75
	v_mul_f32_e32 v120, 0x41800000, v76
	v_mul_f32_e32 v121, 0x41800000, v77
	v_mul_f32_e32 v122, 0x41800000, v78
	v_mul_f32_e32 v123, 0x41800000, v79
	v_cvt_pk_fp8_f32 v114, v116, v117
	v_cvt_pk_fp8_f32 v115, v120, v121
	v_cvt_pk_fp8_f32 v114, v118, v119 op_sel:[0,0,1]
	v_cvt_pk_fp8_f32 v115, v122, v123 op_sel:[0,0,1]
	global_store_dwordx2 v95, v[114:115], s[10:11]
	s_branch .Lcv_cv3_top
